# lever 4: all per-segment s_setprio toggles removed from the GEMM mainloops (192 instructions); attention phase keeps its single static raise
# baseline (speedup 1.0000x reference)
; #define PG8_STAGE(bufoff, gbase, voff) do { _Pragma("unroll") for (int _i = 0; _i < 2; ++_i) \
;         __builtin_amdgcn_global_load_lds((const GAS unsigned*)((const char*)(gbase) + (voff)[_i]), (LAS unsigned*)(lds + (bufoff) + ldsw + _i * 8192), 16, 0, 0); } while (0)
; #define PG8_LDA(dst, b, h) do { _Pragma("unroll") for (int m = 0; m < 4; ++m) _Pragma("unroll") for (int k = 0; k < 2; ++k) dst[m][k] = *(const LAS bf16x8*)(lds + PG8_SA(b, h) + aoff + m * 2048 + k * 1024); } while (0)
; #define PG8_LDB(dst, b, h) do { _Pragma("unroll") for (int n = 0; n < 2; ++n) _Pragma("unroll") for (int k = 0; k < 2; ++k) dst[n][k] = *(const LAS bf16x8*)(lds + PG8_SB(b, h) + boff + n * 2048 + k * 1024); } while (0)
; #define PG8_MMA(ai, bj, At, Bt) do { __builtin_amdgcn_s_setprio(1); _Pragma("unroll") for (int m = 0; m < 4; ++m) _Pragma("unroll") for (int n = 0; n < 2; ++n) _Pragma("unroll") for (int k = 0; k < 2; ++k) \
;         acc[ai][bj][m][n] = __builtin_amdgcn_mfma_f32_16x16x32_bf16(Bt[n][k], At[m][k], acc[ai][bj][m][n], 0, 0, 0); __builtin_amdgcn_s_setprio(0); } while (0)
; #define PG8_WAIT_V(n) asm volatile("s_waitcnt vmcnt(" #n ")" ::: "memory")
; #define PG8_WAIT_L(n) asm volatile("s_waitcnt lgkmcnt(" #n ")" ::: "memory")
; #define PG8_BAR __builtin_amdgcn_s_barrier()
; #define PG8_SCHED __builtin_amdgcn_sched_barrier(0)
; template <class Epi, class Sched>
; __device__ __forceinline__ void gemm_phase(LAS unsigned char* lds, const Gemm g, const Sched& S, const Epi& E, const int wave_) {
;     ...
;             const bool last = (t == nt - 2);
;             const char* a1 = cA + (size_t)(t + 1) * kstep;
;             const char* a2 = last ? nA : cA + (size_t)(t + 2) * kstep; const char* b2 = last ? nB : cB + (size_t)(t + 2) * kstep;
;             const char* a3 = a2 + kstep; const char* b3 = b2 + kstep;
;             PG8_LDB(B0, 0, 0); PG8_LDB(B1, 0, 1); PG8_SCHED; PG8_LDA(At, 0, 0); PG8_STAGE(PG8_SA(1, 1), a1 + hstepA, voffA);
;             PG8_WAIT_V(8); PG8_WAIT_L(0); PG8_BAR; PG8_MMA(0, 0, At, B0); PG8_MMA(0, 1, At, B1); PG8_BAR; PG8_SCHED;
;             PG8_LDA(At, 0, 1); PG8_STAGE(PG8_SB(0, 0), b2, voffB); PG8_STAGE(PG8_SB(0, 1), b2 + hstepB, voffB); PG8_STAGE(PG8_SA(0, 0), a2, voffA);
;             PG8_WAIT_V(8); PG8_WAIT_L(0); PG8_BAR; PG8_MMA(1, 0, At, B0); PG8_MMA(1, 1, At, B1); PG8_BAR; PG8_SCHED;
.LBB0_183:
	ds_read_b128 v[150:153], v166
	ds_read_b128 v[154:157], v166 offset:1024
	ds_read_b128 v[158:161], v166 offset:2048
	ds_read_b128 v[170:173], v166 offset:3072
	ds_read_b128 v[174:177], v167
	ds_read_b128 v[178:181], v167 offset:1024
	ds_read_b128 v[188:191], v167 offset:2048
	ds_read_b128 v[192:195], v167 offset:3072
	s_add_i32 s74, s68, 2
	s_add_u32 s21, s8, 0xfffc0080
	s_addc_u32 s69, s9, -1
	s_cmp_eq_u32 s95, s68
	s_cselect_b32 s68, s59, s72
	s_cselect_b32 s71, s7, s69
	s_cselect_b32 s70, s38, s21
	s_cselect_b32 s69, s57, s73
	v_lshl_add_u64 v[182:183], s[8:9], 0, v[144:145]
	s_add_i32 m0, s29, 0xc000
	ds_read_b128 v[196:199], v168
	ds_read_b128 v[200:203], v168 offset:1024
	ds_read_b128 v[204:207], v168 offset:2048
	ds_read_b128 v[208:211], v168 offset:3072
	ds_read_b128 v[212:215], v168 offset:4096
	ds_read_b128 v[216:219], v168 offset:5120
	ds_read_b128 v[220:223], v168 offset:6144
	ds_read_b128 v[224:227], v168 offset:7168
	global_load_lds_dwordx4 v[182:183], off
	v_lshl_add_u64 v[182:183], s[8:9], 0, v[142:143]
	s_add_i32 m0, s29, 0xe000
	s_nop 0
	global_load_lds_dwordx4 v[182:183], off
	s_waitcnt vmcnt(8)
	s_waitcnt lgkmcnt(0)
	s_barrier
	s_waitcnt lgkmcnt(0)
	v_mfma_f32_16x16x32_bf16 v[120:123], v[150:153], v[196:199], v[120:123]
	v_mfma_f32_16x16x32_bf16 v[124:127], v[158:161], v[196:199], v[124:127]
	v_mfma_f32_16x16x32_bf16 v[108:111], v[150:153], v[204:207], v[108:111]
	v_mfma_f32_16x16x32_bf16 v[104:107], v[158:161], v[204:207], v[104:107]
	v_mfma_f32_16x16x32_bf16 v[92:95], v[150:153], v[212:215], v[92:95]
	v_mfma_f32_16x16x32_bf16 v[88:91], v[158:161], v[212:215], v[88:91]
	v_mfma_f32_16x16x32_bf16 v[76:79], v[150:153], v[220:223], v[76:79]
	v_mfma_f32_16x16x32_bf16 v[72:75], v[158:161], v[220:223], v[72:75]
	v_mfma_f32_16x16x32_bf16 v[120:123], v[154:157], v[200:203], v[120:123]
	v_mfma_f32_16x16x32_bf16 v[124:127], v[170:173], v[200:203], v[124:127]
	v_mfma_f32_16x16x32_bf16 v[108:111], v[154:157], v[208:211], v[108:111]
	v_mfma_f32_16x16x32_bf16 v[104:107], v[170:173], v[208:211], v[104:107]
	v_mfma_f32_16x16x32_bf16 v[92:95], v[154:157], v[216:219], v[92:95]
	v_mfma_f32_16x16x32_bf16 v[88:91], v[170:173], v[216:219], v[88:91]
	v_mfma_f32_16x16x32_bf16 v[76:79], v[154:157], v[224:227], v[76:79]
	v_mfma_f32_16x16x32_bf16 v[72:75], v[170:173], v[224:227], v[72:75]
	v_mfma_f32_16x16x32_bf16 v[116:119], v[174:177], v[196:199], v[116:119]
	v_mfma_f32_16x16x32_bf16 v[112:115], v[188:191], v[196:199], v[112:115]
	v_mfma_f32_16x16x32_bf16 v[100:103], v[174:177], v[204:207], v[100:103]
	v_mfma_f32_16x16x32_bf16 v[96:99], v[188:191], v[204:207], v[96:99]
	v_mfma_f32_16x16x32_bf16 v[84:87], v[174:177], v[212:215], v[84:87]
	v_mfma_f32_16x16x32_bf16 v[80:83], v[188:191], v[212:215], v[80:83]
	v_mfma_f32_16x16x32_bf16 v[68:71], v[174:177], v[220:223], v[68:71]
	v_mfma_f32_16x16x32_bf16 v[64:67], v[188:191], v[220:223], v[64:67]
	v_mfma_f32_16x16x32_bf16 v[116:119], v[178:181], v[200:203], v[116:119]
	v_mfma_f32_16x16x32_bf16 v[112:115], v[192:195], v[200:203], v[112:115]
	v_mfma_f32_16x16x32_bf16 v[100:103], v[178:181], v[208:211], v[100:103]
	v_mfma_f32_16x16x32_bf16 v[96:99], v[192:195], v[208:211], v[96:99]
	v_mfma_f32_16x16x32_bf16 v[84:87], v[178:181], v[216:219], v[84:87]
	v_mfma_f32_16x16x32_bf16 v[80:83], v[192:195], v[216:219], v[80:83]
	v_mfma_f32_16x16x32_bf16 v[68:71], v[178:181], v[224:227], v[68:71]
	v_mfma_f32_16x16x32_bf16 v[64:67], v[192:195], v[224:227], v[64:67]
	s_barrier
	s_add_i32 s21, s25, s83
	v_lshl_add_u64 v[182:183], s[68:69], 0, v[130:131]
	s_mov_b32 m0, s21
	ds_read_b128 v[196:199], v168 offset:16384
	ds_read_b128 v[200:203], v168 offset:17408
	ds_read_b128 v[204:207], v168 offset:18432
	ds_read_b128 v[208:211], v168 offset:19456
	ds_read_b128 v[212:215], v168 offset:20480
	ds_read_b128 v[216:219], v168 offset:21504
	ds_read_b128 v[220:223], v168 offset:22528
	ds_read_b128 v[224:227], v168 offset:23552
	global_load_lds_dwordx4 v[182:183], off
	s_add_i32 m0, s21, 0x2000
	s_add_u32 vcc_lo, s68, 0x40000
	v_lshl_add_u64 v[228:229], s[68:69], 0, v[134:135]
	s_addc_u32 vcc_hi, s69, 0
	s_add_i32 s21, s78, s83
	global_load_lds_dwordx4 v[228:229], off
	v_lshl_add_u64 v[230:231], vcc, 0, v[130:131]
	s_mov_b32 m0, s21
	v_lshl_add_u64 v[232:233], s[70:71], 0, v[132:133]
	global_load_lds_dwordx4 v[230:231], off
	v_lshl_add_u64 v[230:231], vcc, 0, v[134:135]
	s_add_i32 m0, s21, 0x2000
	s_nop 0
	global_load_lds_dwordx4 v[230:231], off
	v_lshl_add_u64 v[230:231], s[70:71], 0, v[128:129]
	s_mov_b32 m0, s29
	s_nop 0
	global_load_lds_dwordx4 v[230:231], off
	s_mov_b32 m0, s53
	s_nop 0
	global_load_lds_dwordx4 v[232:233], off
	s_waitcnt vmcnt(8)
	s_waitcnt lgkmcnt(0)
	s_barrier
; #define PG8_STAGE(bufoff, gbase, voff) do { _Pragma("unroll") for (int _i = 0; _i < 2; ++_i) \
;         __builtin_amdgcn_global_load_lds((const GAS unsigned*)((const char*)(gbase) + (voff)[_i]), (LAS unsigned*)(lds + (bufoff) + ldsw + _i * 8192), 16, 0, 0); } while (0)
; #define PG8_LDA(dst, b, h) do { _Pragma("unroll") for (int m = 0; m < 4; ++m) _Pragma("unroll") for (int k = 0; k < 2; ++k) dst[m][k] = *(const LAS bf16x8*)(lds + PG8_SA(b, h) + aoff + m * 2048 + k * 1024); } while (0)
; #define PG8_LDB(dst, b, h) do { _Pragma("unroll") for (int n = 0; n < 2; ++n) _Pragma("unroll") for (int k = 0; k < 2; ++k) dst[n][k] = *(const LAS bf16x8*)(lds + PG8_SB(b, h) + boff + n * 2048 + k * 1024); } while (0)
; #define PG8_MMA(ai, bj, At, Bt) do { __builtin_amdgcn_s_setprio(1); _Pragma("unroll") for (int m = 0; m < 4; ++m) _Pragma("unroll") for (int n = 0; n < 2; ++n) _Pragma("unroll") for (int k = 0; k < 2; ++k) \
;         acc[ai][bj][m][n] = __builtin_amdgcn_mfma_f32_16x16x32_bf16(Bt[n][k], At[m][k], acc[ai][bj][m][n], 0, 0, 0); __builtin_amdgcn_s_setprio(0); } while (0)
; #define PG8_WAIT_V(n) asm volatile("s_waitcnt vmcnt(" #n ")" ::: "memory")
; #define PG8_WAIT_L(n) asm volatile("s_waitcnt lgkmcnt(" #n ")" ::: "memory")
; #define PG8_BAR __builtin_amdgcn_s_barrier()
; #define PG8_SCHED __builtin_amdgcn_sched_barrier(0)
; template <class Epi, class Sched>
; __device__ __forceinline__ void gemm_phase(LAS unsigned char* lds, const Gemm g, const Sched& S, const Epi& E, const int wave_) {
;     ...
;             PG8_WAIT_V(8); PG8_WAIT_L(0); PG8_BAR; PG8_MMA(1, 0, At, B0); PG8_MMA(1, 1, At, B1); PG8_BAR; PG8_SCHED;
;             PG8_LDB(B0, 1, 0); PG8_LDB(B1, 1, 1); PG8_SCHED; PG8_LDA(At, 1, 0); PG8_STAGE(PG8_SA(0, 1), a2 + hstepA, voffA);
;             PG8_WAIT_V(8); PG8_WAIT_L(0); PG8_BAR; PG8_MMA(0, 0, At, B0); PG8_MMA(0, 1, At, B1); PG8_BAR; PG8_SCHED;
	s_waitcnt lgkmcnt(0)
	v_mfma_f32_16x16x32_bf16 v[60:63], v[150:153], v[196:199], v[60:63]
	v_mfma_f32_16x16x32_bf16 v[56:59], v[158:161], v[196:199], v[56:59]
	v_mfma_f32_16x16x32_bf16 v[44:47], v[150:153], v[204:207], v[44:47]
	v_mfma_f32_16x16x32_bf16 v[40:43], v[158:161], v[204:207], v[40:43]
	v_mfma_f32_16x16x32_bf16 v[28:31], v[150:153], v[212:215], v[28:31]
	v_mfma_f32_16x16x32_bf16 v[24:27], v[158:161], v[212:215], v[24:27]
	v_mfma_f32_16x16x32_bf16 v[12:15], v[150:153], v[220:223], v[12:15]
	v_mfma_f32_16x16x32_bf16 v[8:11], v[158:161], v[220:223], v[8:11]
	v_mfma_f32_16x16x32_bf16 v[60:63], v[154:157], v[200:203], v[60:63]
	v_mfma_f32_16x16x32_bf16 v[56:59], v[170:173], v[200:203], v[56:59]
	v_mfma_f32_16x16x32_bf16 v[44:47], v[154:157], v[208:211], v[44:47]
	v_mfma_f32_16x16x32_bf16 v[40:43], v[170:173], v[208:211], v[40:43]
	v_mfma_f32_16x16x32_bf16 v[28:31], v[154:157], v[216:219], v[28:31]
	v_mfma_f32_16x16x32_bf16 v[24:27], v[170:173], v[216:219], v[24:27]
	v_mfma_f32_16x16x32_bf16 v[12:15], v[154:157], v[224:227], v[12:15]
	v_mfma_f32_16x16x32_bf16 v[8:11], v[170:173], v[224:227], v[8:11]
	v_mfma_f32_16x16x32_bf16 v[52:55], v[174:177], v[196:199], v[52:55]
	v_mfma_f32_16x16x32_bf16 v[48:51], v[188:191], v[196:199], v[48:51]
	v_mfma_f32_16x16x32_bf16 v[36:39], v[174:177], v[204:207], v[36:39]
	v_mfma_f32_16x16x32_bf16 v[32:35], v[188:191], v[204:207], v[32:35]
	v_mfma_f32_16x16x32_bf16 v[20:23], v[174:177], v[212:215], v[20:23]
	v_mfma_f32_16x16x32_bf16 v[16:19], v[188:191], v[212:215], v[16:19]
	v_mfma_f32_16x16x32_bf16 v[4:7], v[174:177], v[220:223], v[4:7]
	v_mfma_f32_16x16x32_bf16 v[0:3], v[188:191], v[220:223], v[0:3]
	v_mfma_f32_16x16x32_bf16 v[52:55], v[178:181], v[200:203], v[52:55]
	v_mfma_f32_16x16x32_bf16 v[48:51], v[192:195], v[200:203], v[48:51]
	v_mfma_f32_16x16x32_bf16 v[36:39], v[178:181], v[208:211], v[36:39]
	v_mfma_f32_16x16x32_bf16 v[32:35], v[192:195], v[208:211], v[32:35]
	v_mfma_f32_16x16x32_bf16 v[20:23], v[178:181], v[216:219], v[20:23]
	v_mfma_f32_16x16x32_bf16 v[16:19], v[192:195], v[216:219], v[16:19]
	v_mfma_f32_16x16x32_bf16 v[4:7], v[178:181], v[224:227], v[4:7]
	v_mfma_f32_16x16x32_bf16 v[0:3], v[192:195], v[224:227], v[0:3]
	s_barrier
	s_add_i32 s21, 0, 0x18000
	v_add_u32_e32 v169, s21, v163
	s_add_i32 s75, 0, 0x1c000
	ds_read_b128 v[150:153], v169
	ds_read_b128 v[154:157], v169 offset:1024
	ds_read_b128 v[158:161], v169 offset:2048
	ds_read_b128 v[170:173], v169 offset:3072
	v_add_u32_e32 v169, s75, v163
	ds_read_b128 v[174:177], v169
	ds_read_b128 v[178:181], v169 offset:1024
	ds_read_b128 v[188:191], v169 offset:2048
	ds_read_b128 v[192:195], v169 offset:3072
	s_add_u32 s70, s70, 0x40000
	s_addc_u32 s71, s71, 0
	s_mov_b32 m0, s90
	v_lshl_add_u64 v[234:235], s[70:71], 0, v[128:129]
	ds_read_b128 v[196:199], v168 offset:32768
	ds_read_b128 v[200:203], v168 offset:33792
	ds_read_b128 v[204:207], v168 offset:34816
	ds_read_b128 v[208:211], v168 offset:35840
	ds_read_b128 v[212:215], v168 offset:36864
	ds_read_b128 v[216:219], v168 offset:37888
	ds_read_b128 v[220:223], v168 offset:38912
	ds_read_b128 v[224:227], v168 offset:39936
	global_load_lds_dwordx4 v[234:235], off
	v_lshl_add_u64 v[234:235], s[70:71], 0, v[132:133]
	s_mov_b32 m0, s91
	s_nop 0
	global_load_lds_dwordx4 v[234:235], off
	s_waitcnt vmcnt(8)
	s_waitcnt lgkmcnt(0)
	s_barrier
	s_waitcnt lgkmcnt(0)
	v_mfma_f32_16x16x32_bf16 v[120:123], v[150:153], v[196:199], v[120:123]
	v_mfma_f32_16x16x32_bf16 v[124:127], v[158:161], v[196:199], v[124:127]
	v_mfma_f32_16x16x32_bf16 v[108:111], v[150:153], v[204:207], v[108:111]
	v_mfma_f32_16x16x32_bf16 v[104:107], v[158:161], v[204:207], v[104:107]
	v_mfma_f32_16x16x32_bf16 v[92:95], v[150:153], v[212:215], v[92:95]
	v_mfma_f32_16x16x32_bf16 v[88:91], v[158:161], v[212:215], v[88:91]
	v_mfma_f32_16x16x32_bf16 v[76:79], v[150:153], v[220:223], v[76:79]
	v_mfma_f32_16x16x32_bf16 v[72:75], v[158:161], v[220:223], v[72:75]
	v_mfma_f32_16x16x32_bf16 v[120:123], v[154:157], v[200:203], v[120:123]
	v_mfma_f32_16x16x32_bf16 v[124:127], v[170:173], v[200:203], v[124:127]
	v_mfma_f32_16x16x32_bf16 v[108:111], v[154:157], v[208:211], v[108:111]
	v_mfma_f32_16x16x32_bf16 v[104:107], v[170:173], v[208:211], v[104:107]
	v_mfma_f32_16x16x32_bf16 v[92:95], v[154:157], v[216:219], v[92:95]
	v_mfma_f32_16x16x32_bf16 v[88:91], v[170:173], v[216:219], v[88:91]
	v_mfma_f32_16x16x32_bf16 v[76:79], v[154:157], v[224:227], v[76:79]
	v_mfma_f32_16x16x32_bf16 v[72:75], v[170:173], v[224:227], v[72:75]
	v_mfma_f32_16x16x32_bf16 v[116:119], v[174:177], v[196:199], v[116:119]
	v_mfma_f32_16x16x32_bf16 v[112:115], v[188:191], v[196:199], v[112:115]
	v_mfma_f32_16x16x32_bf16 v[100:103], v[174:177], v[204:207], v[100:103]
	v_mfma_f32_16x16x32_bf16 v[96:99], v[188:191], v[204:207], v[96:99]
	v_mfma_f32_16x16x32_bf16 v[84:87], v[174:177], v[212:215], v[84:87]
	v_mfma_f32_16x16x32_bf16 v[80:83], v[188:191], v[212:215], v[80:83]
	v_mfma_f32_16x16x32_bf16 v[68:71], v[174:177], v[220:223], v[68:71]
	v_mfma_f32_16x16x32_bf16 v[64:67], v[188:191], v[220:223], v[64:67]
	v_mfma_f32_16x16x32_bf16 v[116:119], v[178:181], v[200:203], v[116:119]
	v_mfma_f32_16x16x32_bf16 v[112:115], v[192:195], v[200:203], v[112:115]
	v_mfma_f32_16x16x32_bf16 v[100:103], v[178:181], v[208:211], v[100:103]
	v_mfma_f32_16x16x32_bf16 v[96:99], v[192:195], v[208:211], v[96:99]
	v_mfma_f32_16x16x32_bf16 v[84:87], v[178:181], v[216:219], v[84:87]
	v_mfma_f32_16x16x32_bf16 v[80:83], v[192:195], v[216:219], v[80:83]
	v_mfma_f32_16x16x32_bf16 v[68:71], v[178:181], v[224:227], v[68:71]
	v_mfma_f32_16x16x32_bf16 v[64:67], v[192:195], v[224:227], v[64:67]
	s_barrier
; #define PG8_STAGE(bufoff, gbase, voff) do { _Pragma("unroll") for (int _i = 0; _i < 2; ++_i) \
;         __builtin_amdgcn_global_load_lds((const GAS unsigned*)((const char*)(gbase) + (voff)[_i]), (LAS unsigned*)(lds + (bufoff) + ldsw + _i * 8192), 16, 0, 0); } while (0)
; #define PG8_LDA(dst, b, h) do { _Pragma("unroll") for (int m = 0; m < 4; ++m) _Pragma("unroll") for (int k = 0; k < 2; ++k) dst[m][k] = *(const LAS bf16x8*)(lds + PG8_SA(b, h) + aoff + m * 2048 + k * 1024); } while (0)
; #define PG8_MMA(ai, bj, At, Bt) do { __builtin_amdgcn_s_setprio(1); _Pragma("unroll") for (int m = 0; m < 4; ++m) _Pragma("unroll") for (int n = 0; n < 2; ++n) _Pragma("unroll") for (int k = 0; k < 2; ++k) \
;         acc[ai][bj][m][n] = __builtin_amdgcn_mfma_f32_16x16x32_bf16(Bt[n][k], At[m][k], acc[ai][bj][m][n], 0, 0, 0); __builtin_amdgcn_s_setprio(0); } while (0)
; #define PG8_WAIT_V(n) asm volatile("s_waitcnt vmcnt(" #n ")" ::: "memory")
; #define PG8_WAIT_L(n) asm volatile("s_waitcnt lgkmcnt(" #n ")" ::: "memory")
; #define PG8_BAR __builtin_amdgcn_s_barrier()
; #define PG8_SCHED __builtin_amdgcn_sched_barrier(0)
; template <class Epi, class Sched>
; __device__ __forceinline__ void gemm_phase(LAS unsigned char* lds, const Gemm g, const Sched& S, const Epi& E, const int wave_) {
;     ...
;         for (int t = 0; t < nt; t += 2) {
;     ...
;             PG8_LDA(At, 1, 1); PG8_STAGE(PG8_SB(1, 0), b3, voffB); PG8_STAGE(PG8_SB(1, 1), b3 + hstepB, voffB); PG8_STAGE(PG8_SA(1, 0), a3, voffA);
;             PG8_WAIT_V(8); PG8_WAIT_L(0); PG8_BAR; PG8_MMA(1, 0, At, B0); PG8_MMA(1, 1, At, B1); PG8_BAR; PG8_SCHED;
	s_add_i32 s21, s21, s83
	v_lshl_add_u64 v[182:183], v[182:183], 0, s[46:47]
	s_mov_b32 m0, s21
	ds_read_b128 v[196:199], v168 offset:49152
	ds_read_b128 v[200:203], v168 offset:50176
	ds_read_b128 v[204:207], v168 offset:51200
	ds_read_b128 v[208:211], v168 offset:52224
	ds_read_b128 v[212:215], v168 offset:53248
	ds_read_b128 v[216:219], v168 offset:54272
	ds_read_b128 v[220:223], v168 offset:55296
	ds_read_b128 v[224:227], v168 offset:56320
	global_load_lds_dwordx4 v[182:183], off
	s_add_i32 m0, s21, 0x2000
	s_add_u32 s68, s68, 0x40080
	v_lshl_add_u64 v[182:183], v[228:229], 0, s[46:47]
	s_addc_u32 s69, s69, 0
	s_add_i32 s21, s75, s83
	global_load_lds_dwordx4 v[182:183], off
	v_lshl_add_u64 v[182:183], s[68:69], 0, v[130:131]
	s_mov_b32 m0, s21
	s_nop 0
	global_load_lds_dwordx4 v[182:183], off
	v_lshl_add_u64 v[182:183], s[68:69], 0, v[134:135]
	s_add_i32 m0, s21, 0x2000
	s_nop 0
	global_load_lds_dwordx4 v[182:183], off
	v_lshl_add_u64 v[182:183], v[230:231], 0, s[46:47]
	s_mov_b32 m0, s93
	s_nop 0
	global_load_lds_dwordx4 v[182:183], off
	v_lshl_add_u64 v[182:183], v[232:233], 0, s[46:47]
	s_mov_b32 m0, s94
	s_nop 0
	global_load_lds_dwordx4 v[182:183], off
	s_waitcnt vmcnt(8)
	s_waitcnt lgkmcnt(0)
	s_barrier
	s_waitcnt lgkmcnt(0)
	v_mfma_f32_16x16x32_bf16 v[60:63], v[150:153], v[196:199], v[60:63]
	v_mfma_f32_16x16x32_bf16 v[56:59], v[158:161], v[196:199], v[56:59]
	v_mfma_f32_16x16x32_bf16 v[44:47], v[150:153], v[204:207], v[44:47]
	v_mfma_f32_16x16x32_bf16 v[40:43], v[158:161], v[204:207], v[40:43]
	v_mfma_f32_16x16x32_bf16 v[28:31], v[150:153], v[212:215], v[28:31]
	v_mfma_f32_16x16x32_bf16 v[24:27], v[158:161], v[212:215], v[24:27]
	v_mfma_f32_16x16x32_bf16 v[12:15], v[150:153], v[220:223], v[12:15]
	v_mfma_f32_16x16x32_bf16 v[8:11], v[158:161], v[220:223], v[8:11]
	v_mfma_f32_16x16x32_bf16 v[60:63], v[154:157], v[200:203], v[60:63]
	v_mfma_f32_16x16x32_bf16 v[56:59], v[170:173], v[200:203], v[56:59]
	v_mfma_f32_16x16x32_bf16 v[44:47], v[154:157], v[208:211], v[44:47]
	v_mfma_f32_16x16x32_bf16 v[40:43], v[170:173], v[208:211], v[40:43]
	v_mfma_f32_16x16x32_bf16 v[28:31], v[154:157], v[216:219], v[28:31]
	v_mfma_f32_16x16x32_bf16 v[24:27], v[170:173], v[216:219], v[24:27]
	v_mfma_f32_16x16x32_bf16 v[12:15], v[154:157], v[224:227], v[12:15]
	v_mfma_f32_16x16x32_bf16 v[8:11], v[170:173], v[224:227], v[8:11]
	v_mfma_f32_16x16x32_bf16 v[52:55], v[174:177], v[196:199], v[52:55]
	v_mfma_f32_16x16x32_bf16 v[48:51], v[188:191], v[196:199], v[48:51]
	v_mfma_f32_16x16x32_bf16 v[36:39], v[174:177], v[204:207], v[36:39]
	v_mfma_f32_16x16x32_bf16 v[32:35], v[188:191], v[204:207], v[32:35]
	v_mfma_f32_16x16x32_bf16 v[20:23], v[174:177], v[212:215], v[20:23]
	v_mfma_f32_16x16x32_bf16 v[16:19], v[188:191], v[212:215], v[16:19]
	v_mfma_f32_16x16x32_bf16 v[4:7], v[174:177], v[220:223], v[4:7]
	v_mfma_f32_16x16x32_bf16 v[0:3], v[188:191], v[220:223], v[0:3]
	v_mfma_f32_16x16x32_bf16 v[52:55], v[178:181], v[200:203], v[52:55]
	v_mfma_f32_16x16x32_bf16 v[48:51], v[192:195], v[200:203], v[48:51]
	v_mfma_f32_16x16x32_bf16 v[36:39], v[178:181], v[208:211], v[36:39]
	v_mfma_f32_16x16x32_bf16 v[32:35], v[192:195], v[208:211], v[32:35]
	v_mfma_f32_16x16x32_bf16 v[20:23], v[178:181], v[216:219], v[20:23]
	v_mfma_f32_16x16x32_bf16 v[16:19], v[192:195], v[216:219], v[16:19]
	v_mfma_f32_16x16x32_bf16 v[4:7], v[178:181], v[224:227], v[4:7]
	v_mfma_f32_16x16x32_bf16 v[0:3], v[192:195], v[224:227], v[0:3]
	s_barrier
	s_add_u32 s72, s72, 0x100
	s_addc_u32 s73, s73, 0
	s_add_u32 s8, s8, 0x100
	s_addc_u32 s9, s9, 0
	s_cmp_ge_i32 s74, s92
	s_mov_b32 s68, s74
	s_cbranch_scc0 .LBB0_183

; #define PG8_STAGE(bufoff, gbase, voff) do { _Pragma("unroll") for (int _i = 0; _i < 2; ++_i) \
;         __builtin_amdgcn_global_load_lds((const GAS unsigned*)((const char*)(gbase) + (voff)[_i]), (LAS unsigned*)(lds + (bufoff) + ldsw + _i * 8192), 16, 0, 0); } while (0)
; #define PG8_LDA(dst, b, h) do { _Pragma("unroll") for (int m = 0; m < 4; ++m) _Pragma("unroll") for (int k = 0; k < 2; ++k) dst[m][k] = *(const LAS bf16x8*)(lds + PG8_SA(b, h) + aoff + m * 2048 + k * 1024); } while (0)
; #define PG8_LDB(dst, b, h) do { _Pragma("unroll") for (int n = 0; n < 2; ++n) _Pragma("unroll") for (int k = 0; k < 2; ++k) dst[n][k] = *(const LAS bf16x8*)(lds + PG8_SB(b, h) + boff + n * 2048 + k * 1024); } while (0)
; #define PG8_MMA(ai, bj, At, Bt) do { __builtin_amdgcn_s_setprio(1); _Pragma("unroll") for (int m = 0; m < 4; ++m) _Pragma("unroll") for (int n = 0; n < 2; ++n) _Pragma("unroll") for (int k = 0; k < 2; ++k) \
;         acc[ai][bj][m][n] = __builtin_amdgcn_mfma_f32_16x16x32_bf16(Bt[n][k], At[m][k], acc[ai][bj][m][n], 0, 0, 0); __builtin_amdgcn_s_setprio(0); } while (0)
; #define PG8_WAIT_V(n) asm volatile("s_waitcnt vmcnt(" #n ")" ::: "memory")
; #define PG8_WAIT_L(n) asm volatile("s_waitcnt lgkmcnt(" #n ")" ::: "memory")
; #define PG8_BAR __builtin_amdgcn_s_barrier()
; #define PG8_SCHED __builtin_amdgcn_sched_barrier(0)
; template <class Epi, class Sched>
; __device__ __forceinline__ void gemm_phase(LAS unsigned char* lds, const Gemm g, const Sched& S, const Epi& E, const int wave_) {
;     ...
;             const bool last = (t == nt - 2);
;             const char* a1 = cA + (size_t)(t + 1) * kstep;
;             const char* a2 = last ? nA : cA + (size_t)(t + 2) * kstep; const char* b2 = last ? nB : cB + (size_t)(t + 2) * kstep;
;             const char* a3 = a2 + kstep; const char* b3 = b2 + kstep;
;             PG8_LDB(B0, 0, 0); PG8_LDB(B1, 0, 1); PG8_SCHED; PG8_LDA(At, 0, 0); PG8_STAGE(PG8_SA(1, 1), a1 + hstepA, voffA);
;             PG8_WAIT_V(8); PG8_WAIT_L(0); PG8_BAR; PG8_MMA(0, 0, At, B0); PG8_MMA(0, 1, At, B1); PG8_BAR; PG8_SCHED;
;             PG8_LDA(At, 0, 1); PG8_STAGE(PG8_SB(0, 0), b2, voffB); PG8_STAGE(PG8_SB(0, 1), b2 + hstepB, voffB); PG8_STAGE(PG8_SA(0, 0), a2, voffA);
;             PG8_WAIT_V(8); PG8_WAIT_L(0); PG8_BAR; PG8_MMA(1, 0, At, B0); PG8_MMA(1, 1, At, B1); PG8_BAR; PG8_SCHED;
.LBB0_524:
	ds_read_b128 v[152:155], v148
	ds_read_b128 v[156:159], v148 offset:1024
	ds_read_b128 v[160:163], v148 offset:2048
	ds_read_b128 v[164:167], v148 offset:3072
	ds_read_b128 v[168:171], v149
	ds_read_b128 v[172:175], v149 offset:1024
	ds_read_b128 v[176:179], v149 offset:2048
	ds_read_b128 v[180:183], v149 offset:3072
	s_add_i32 s78, s56, 2
	s_add_u32 s21, s54, 0xfffc0080
	s_addc_u32 s57, s55, -1
	s_cmp_eq_u32 s69, s56
	s_cselect_b32 s56, s75, s76
	s_cselect_b32 s59, s43, s57
	s_cselect_b32 s58, s73, s21
	s_cselect_b32 s57, s74, s77
	v_lshl_add_u64 v[220:221], s[54:55], 0, v[138:139]
	s_add_i32 m0, s61, 0xc000
	ds_read_b128 v[188:191], v150
	ds_read_b128 v[192:195], v150 offset:1024
	ds_read_b128 v[196:199], v150 offset:2048
	ds_read_b128 v[200:203], v150 offset:3072
	ds_read_b128 v[204:207], v150 offset:4096
	ds_read_b128 v[208:211], v150 offset:5120
	ds_read_b128 v[212:215], v150 offset:6144
	ds_read_b128 v[216:219], v150 offset:7168
	global_load_lds_dwordx4 v[220:221], off
	v_lshl_add_u64 v[220:221], s[54:55], 0, v[136:137]
	s_add_i32 m0, s61, 0xe000
	s_nop 0
	global_load_lds_dwordx4 v[220:221], off
	s_waitcnt vmcnt(8)
	s_waitcnt lgkmcnt(0)
	s_barrier
	s_waitcnt lgkmcnt(0)
	v_mfma_f32_16x16x32_bf16 v[120:123], v[152:155], v[188:191], v[120:123]
	v_mfma_f32_16x16x32_bf16 v[124:127], v[160:163], v[188:191], v[124:127]
	v_mfma_f32_16x16x32_bf16 v[108:111], v[152:155], v[196:199], v[108:111]
	v_mfma_f32_16x16x32_bf16 v[104:107], v[160:163], v[196:199], v[104:107]
	v_mfma_f32_16x16x32_bf16 v[92:95], v[152:155], v[204:207], v[92:95]
	v_mfma_f32_16x16x32_bf16 v[88:91], v[160:163], v[204:207], v[88:91]
	v_mfma_f32_16x16x32_bf16 v[76:79], v[152:155], v[212:215], v[76:79]
	v_mfma_f32_16x16x32_bf16 v[72:75], v[160:163], v[212:215], v[72:75]
	v_mfma_f32_16x16x32_bf16 v[120:123], v[156:159], v[192:195], v[120:123]
	v_mfma_f32_16x16x32_bf16 v[124:127], v[164:167], v[192:195], v[124:127]
	v_mfma_f32_16x16x32_bf16 v[108:111], v[156:159], v[200:203], v[108:111]
	v_mfma_f32_16x16x32_bf16 v[104:107], v[164:167], v[200:203], v[104:107]
	v_mfma_f32_16x16x32_bf16 v[92:95], v[156:159], v[208:211], v[92:95]
	v_mfma_f32_16x16x32_bf16 v[88:91], v[164:167], v[208:211], v[88:91]
	v_mfma_f32_16x16x32_bf16 v[76:79], v[156:159], v[216:219], v[76:79]
	v_mfma_f32_16x16x32_bf16 v[72:75], v[164:167], v[216:219], v[72:75]
	v_mfma_f32_16x16x32_bf16 v[116:119], v[168:171], v[188:191], v[116:119]
	v_mfma_f32_16x16x32_bf16 v[112:115], v[176:179], v[188:191], v[112:115]
	v_mfma_f32_16x16x32_bf16 v[100:103], v[168:171], v[196:199], v[100:103]
	v_mfma_f32_16x16x32_bf16 v[96:99], v[176:179], v[196:199], v[96:99]
	v_mfma_f32_16x16x32_bf16 v[84:87], v[168:171], v[204:207], v[84:87]
	v_mfma_f32_16x16x32_bf16 v[80:83], v[176:179], v[204:207], v[80:83]
	v_mfma_f32_16x16x32_bf16 v[68:71], v[168:171], v[212:215], v[68:71]
	v_mfma_f32_16x16x32_bf16 v[64:67], v[176:179], v[212:215], v[64:67]
	v_mfma_f32_16x16x32_bf16 v[116:119], v[172:175], v[192:195], v[116:119]
	v_mfma_f32_16x16x32_bf16 v[112:115], v[180:183], v[192:195], v[112:115]
	v_mfma_f32_16x16x32_bf16 v[100:103], v[172:175], v[200:203], v[100:103]
	v_mfma_f32_16x16x32_bf16 v[96:99], v[180:183], v[200:203], v[96:99]
	v_mfma_f32_16x16x32_bf16 v[84:87], v[172:175], v[208:211], v[84:87]
	v_mfma_f32_16x16x32_bf16 v[80:83], v[180:183], v[208:211], v[80:83]
	v_mfma_f32_16x16x32_bf16 v[68:71], v[172:175], v[216:219], v[68:71]
	v_mfma_f32_16x16x32_bf16 v[64:67], v[180:183], v[216:219], v[64:67]
	s_barrier
	s_add_i32 s21, s70, s83
	v_lshl_add_u64 v[220:221], s[56:57], 0, v[130:131]
	s_mov_b32 m0, s21
	ds_read_b128 v[188:191], v150 offset:16384
	ds_read_b128 v[192:195], v150 offset:17408
	ds_read_b128 v[196:199], v150 offset:18432
	ds_read_b128 v[200:203], v150 offset:19456
	ds_read_b128 v[204:207], v150 offset:20480
	ds_read_b128 v[208:211], v150 offset:21504
	ds_read_b128 v[212:215], v150 offset:22528
	ds_read_b128 v[216:219], v150 offset:23552
	global_load_lds_dwordx4 v[220:221], off
	s_add_i32 m0, s21, 0x2000
	s_add_u32 s90, s56, 0x40000
	v_lshl_add_u64 v[222:223], s[56:57], 0, v[134:135]
	s_addc_u32 s91, s57, 0
	s_add_i32 s21, s71, s83
	global_load_lds_dwordx4 v[222:223], off
	v_lshl_add_u64 v[224:225], s[90:91], 0, v[130:131]
	s_mov_b32 m0, s21
	v_lshl_add_u64 v[226:227], s[58:59], 0, v[132:133]
	global_load_lds_dwordx4 v[224:225], off
	v_lshl_add_u64 v[224:225], s[90:91], 0, v[134:135]
	s_add_i32 m0, s21, 0x2000
	s_nop 0
	global_load_lds_dwordx4 v[224:225], off
	v_lshl_add_u64 v[224:225], s[58:59], 0, v[128:129]
	s_mov_b32 m0, s61
	s_nop 0
	global_load_lds_dwordx4 v[224:225], off
	s_mov_b32 m0, s62
	s_nop 0
	global_load_lds_dwordx4 v[226:227], off
	s_waitcnt vmcnt(8)
	s_waitcnt lgkmcnt(0)
	s_barrier
; #define PG8_STAGE(bufoff, gbase, voff) do { _Pragma("unroll") for (int _i = 0; _i < 2; ++_i) \
;         __builtin_amdgcn_global_load_lds((const GAS unsigned*)((const char*)(gbase) + (voff)[_i]), (LAS unsigned*)(lds + (bufoff) + ldsw + _i * 8192), 16, 0, 0); } while (0)
; #define PG8_LDA(dst, b, h) do { _Pragma("unroll") for (int m = 0; m < 4; ++m) _Pragma("unroll") for (int k = 0; k < 2; ++k) dst[m][k] = *(const LAS bf16x8*)(lds + PG8_SA(b, h) + aoff + m * 2048 + k * 1024); } while (0)
; #define PG8_LDB(dst, b, h) do { _Pragma("unroll") for (int n = 0; n < 2; ++n) _Pragma("unroll") for (int k = 0; k < 2; ++k) dst[n][k] = *(const LAS bf16x8*)(lds + PG8_SB(b, h) + boff + n * 2048 + k * 1024); } while (0)
; #define PG8_MMA(ai, bj, At, Bt) do { __builtin_amdgcn_s_setprio(1); _Pragma("unroll") for (int m = 0; m < 4; ++m) _Pragma("unroll") for (int n = 0; n < 2; ++n) _Pragma("unroll") for (int k = 0; k < 2; ++k) \
;         acc[ai][bj][m][n] = __builtin_amdgcn_mfma_f32_16x16x32_bf16(Bt[n][k], At[m][k], acc[ai][bj][m][n], 0, 0, 0); __builtin_amdgcn_s_setprio(0); } while (0)
; #define PG8_WAIT_V(n) asm volatile("s_waitcnt vmcnt(" #n ")" ::: "memory")
; #define PG8_WAIT_L(n) asm volatile("s_waitcnt lgkmcnt(" #n ")" ::: "memory")
; #define PG8_BAR __builtin_amdgcn_s_barrier()
; #define PG8_SCHED __builtin_amdgcn_sched_barrier(0)
; template <class Epi, class Sched>
; __device__ __forceinline__ void gemm_phase(LAS unsigned char* lds, const Gemm g, const Sched& S, const Epi& E, const int wave_) {
;     ...
;             PG8_WAIT_V(8); PG8_WAIT_L(0); PG8_BAR; PG8_MMA(1, 0, At, B0); PG8_MMA(1, 1, At, B1); PG8_BAR; PG8_SCHED;
;             PG8_LDB(B0, 1, 0); PG8_LDB(B1, 1, 1); PG8_SCHED; PG8_LDA(At, 1, 0); PG8_STAGE(PG8_SA(0, 1), a2 + hstepA, voffA);
;             PG8_WAIT_V(8); PG8_WAIT_L(0); PG8_BAR; PG8_MMA(0, 0, At, B0); PG8_MMA(0, 1, At, B1); PG8_BAR; PG8_SCHED;
	s_waitcnt lgkmcnt(0)
	v_mfma_f32_16x16x32_bf16 v[60:63], v[152:155], v[188:191], v[60:63]
	v_mfma_f32_16x16x32_bf16 v[56:59], v[160:163], v[188:191], v[56:59]
	v_mfma_f32_16x16x32_bf16 v[44:47], v[152:155], v[196:199], v[44:47]
	v_mfma_f32_16x16x32_bf16 v[40:43], v[160:163], v[196:199], v[40:43]
	v_mfma_f32_16x16x32_bf16 v[28:31], v[152:155], v[204:207], v[28:31]
	v_mfma_f32_16x16x32_bf16 v[24:27], v[160:163], v[204:207], v[24:27]
	v_mfma_f32_16x16x32_bf16 v[12:15], v[152:155], v[212:215], v[12:15]
	v_mfma_f32_16x16x32_bf16 v[8:11], v[160:163], v[212:215], v[8:11]
	v_mfma_f32_16x16x32_bf16 v[60:63], v[156:159], v[192:195], v[60:63]
	v_mfma_f32_16x16x32_bf16 v[56:59], v[164:167], v[192:195], v[56:59]
	v_mfma_f32_16x16x32_bf16 v[44:47], v[156:159], v[200:203], v[44:47]
	v_mfma_f32_16x16x32_bf16 v[40:43], v[164:167], v[200:203], v[40:43]
	v_mfma_f32_16x16x32_bf16 v[28:31], v[156:159], v[208:211], v[28:31]
	v_mfma_f32_16x16x32_bf16 v[24:27], v[164:167], v[208:211], v[24:27]
	v_mfma_f32_16x16x32_bf16 v[12:15], v[156:159], v[216:219], v[12:15]
	v_mfma_f32_16x16x32_bf16 v[8:11], v[164:167], v[216:219], v[8:11]
	v_mfma_f32_16x16x32_bf16 v[52:55], v[168:171], v[188:191], v[52:55]
	v_mfma_f32_16x16x32_bf16 v[48:51], v[176:179], v[188:191], v[48:51]
	v_mfma_f32_16x16x32_bf16 v[36:39], v[168:171], v[196:199], v[36:39]
	v_mfma_f32_16x16x32_bf16 v[32:35], v[176:179], v[196:199], v[32:35]
	v_mfma_f32_16x16x32_bf16 v[20:23], v[168:171], v[204:207], v[20:23]
	v_mfma_f32_16x16x32_bf16 v[16:19], v[176:179], v[204:207], v[16:19]
	v_mfma_f32_16x16x32_bf16 v[4:7], v[168:171], v[212:215], v[4:7]
	v_mfma_f32_16x16x32_bf16 v[0:3], v[176:179], v[212:215], v[0:3]
	v_mfma_f32_16x16x32_bf16 v[52:55], v[172:175], v[192:195], v[52:55]
	v_mfma_f32_16x16x32_bf16 v[48:51], v[180:183], v[192:195], v[48:51]
	v_mfma_f32_16x16x32_bf16 v[36:39], v[172:175], v[200:203], v[36:39]
	v_mfma_f32_16x16x32_bf16 v[32:35], v[180:183], v[200:203], v[32:35]
	v_mfma_f32_16x16x32_bf16 v[20:23], v[172:175], v[208:211], v[20:23]
	v_mfma_f32_16x16x32_bf16 v[16:19], v[180:183], v[208:211], v[16:19]
	v_mfma_f32_16x16x32_bf16 v[4:7], v[172:175], v[216:219], v[4:7]
	v_mfma_f32_16x16x32_bf16 v[0:3], v[180:183], v[216:219], v[0:3]
	s_barrier
	s_add_i32 s21, 0, 0x18000
	v_add_u32_e32 v151, s21, v144
	s_add_i32 s81, 0, 0x1c000
	ds_read_b128 v[152:155], v151
	ds_read_b128 v[156:159], v151 offset:1024
	ds_read_b128 v[160:163], v151 offset:2048
	ds_read_b128 v[164:167], v151 offset:3072
	v_add_u32_e32 v151, s81, v144
	ds_read_b128 v[168:171], v151
	ds_read_b128 v[172:175], v151 offset:1024
	ds_read_b128 v[176:179], v151 offset:2048
	ds_read_b128 v[180:183], v151 offset:3072
	s_add_u32 s58, s58, 0x40000
	s_addc_u32 s59, s59, 0
	s_mov_b32 m0, s63
	v_lshl_add_u64 v[228:229], s[58:59], 0, v[128:129]
	ds_read_b128 v[188:191], v150 offset:32768
	ds_read_b128 v[192:195], v150 offset:33792
	ds_read_b128 v[196:199], v150 offset:34816
	ds_read_b128 v[200:203], v150 offset:35840
	ds_read_b128 v[204:207], v150 offset:36864
	ds_read_b128 v[208:211], v150 offset:37888
	ds_read_b128 v[212:215], v150 offset:38912
	ds_read_b128 v[216:219], v150 offset:39936
	global_load_lds_dwordx4 v[228:229], off
	v_lshl_add_u64 v[228:229], s[58:59], 0, v[132:133]
	s_mov_b32 m0, s64
	s_nop 0
	global_load_lds_dwordx4 v[228:229], off
	s_waitcnt vmcnt(8)
	s_waitcnt lgkmcnt(0)
	s_barrier
	s_waitcnt lgkmcnt(0)
	v_mfma_f32_16x16x32_bf16 v[120:123], v[152:155], v[188:191], v[120:123]
	v_mfma_f32_16x16x32_bf16 v[124:127], v[160:163], v[188:191], v[124:127]
	v_mfma_f32_16x16x32_bf16 v[108:111], v[152:155], v[196:199], v[108:111]
	v_mfma_f32_16x16x32_bf16 v[104:107], v[160:163], v[196:199], v[104:107]
	v_mfma_f32_16x16x32_bf16 v[92:95], v[152:155], v[204:207], v[92:95]
	v_mfma_f32_16x16x32_bf16 v[88:91], v[160:163], v[204:207], v[88:91]
	v_mfma_f32_16x16x32_bf16 v[76:79], v[152:155], v[212:215], v[76:79]
	v_mfma_f32_16x16x32_bf16 v[72:75], v[160:163], v[212:215], v[72:75]
	v_mfma_f32_16x16x32_bf16 v[120:123], v[156:159], v[192:195], v[120:123]
	v_mfma_f32_16x16x32_bf16 v[124:127], v[164:167], v[192:195], v[124:127]
	v_mfma_f32_16x16x32_bf16 v[108:111], v[156:159], v[200:203], v[108:111]
	v_mfma_f32_16x16x32_bf16 v[104:107], v[164:167], v[200:203], v[104:107]
	v_mfma_f32_16x16x32_bf16 v[92:95], v[156:159], v[208:211], v[92:95]
	v_mfma_f32_16x16x32_bf16 v[88:91], v[164:167], v[208:211], v[88:91]
	v_mfma_f32_16x16x32_bf16 v[76:79], v[156:159], v[216:219], v[76:79]
	v_mfma_f32_16x16x32_bf16 v[72:75], v[164:167], v[216:219], v[72:75]
	v_mfma_f32_16x16x32_bf16 v[116:119], v[168:171], v[188:191], v[116:119]
	v_mfma_f32_16x16x32_bf16 v[112:115], v[176:179], v[188:191], v[112:115]
	v_mfma_f32_16x16x32_bf16 v[100:103], v[168:171], v[196:199], v[100:103]
	v_mfma_f32_16x16x32_bf16 v[96:99], v[176:179], v[196:199], v[96:99]
	v_mfma_f32_16x16x32_bf16 v[84:87], v[168:171], v[204:207], v[84:87]
	v_mfma_f32_16x16x32_bf16 v[80:83], v[176:179], v[204:207], v[80:83]
	v_mfma_f32_16x16x32_bf16 v[68:71], v[168:171], v[212:215], v[68:71]
	v_mfma_f32_16x16x32_bf16 v[64:67], v[176:179], v[212:215], v[64:67]
	v_mfma_f32_16x16x32_bf16 v[116:119], v[172:175], v[192:195], v[116:119]
	v_mfma_f32_16x16x32_bf16 v[112:115], v[180:183], v[192:195], v[112:115]
	v_mfma_f32_16x16x32_bf16 v[100:103], v[172:175], v[200:203], v[100:103]
	v_mfma_f32_16x16x32_bf16 v[96:99], v[180:183], v[200:203], v[96:99]
	v_mfma_f32_16x16x32_bf16 v[84:87], v[172:175], v[208:211], v[84:87]
	v_mfma_f32_16x16x32_bf16 v[80:83], v[180:183], v[208:211], v[80:83]
	v_mfma_f32_16x16x32_bf16 v[68:71], v[172:175], v[216:219], v[68:71]
	v_mfma_f32_16x16x32_bf16 v[64:67], v[180:183], v[216:219], v[64:67]
	s_barrier
; #define PG8_STAGE(bufoff, gbase, voff) do { _Pragma("unroll") for (int _i = 0; _i < 2; ++_i) \
;         __builtin_amdgcn_global_load_lds((const GAS unsigned*)((const char*)(gbase) + (voff)[_i]), (LAS unsigned*)(lds + (bufoff) + ldsw + _i * 8192), 16, 0, 0); } while (0)
; #define PG8_LDA(dst, b, h) do { _Pragma("unroll") for (int m = 0; m < 4; ++m) _Pragma("unroll") for (int k = 0; k < 2; ++k) dst[m][k] = *(const LAS bf16x8*)(lds + PG8_SA(b, h) + aoff + m * 2048 + k * 1024); } while (0)
; #define PG8_MMA(ai, bj, At, Bt) do { __builtin_amdgcn_s_setprio(1); _Pragma("unroll") for (int m = 0; m < 4; ++m) _Pragma("unroll") for (int n = 0; n < 2; ++n) _Pragma("unroll") for (int k = 0; k < 2; ++k) \
;         acc[ai][bj][m][n] = __builtin_amdgcn_mfma_f32_16x16x32_bf16(Bt[n][k], At[m][k], acc[ai][bj][m][n], 0, 0, 0); __builtin_amdgcn_s_setprio(0); } while (0)
; #define PG8_WAIT_V(n) asm volatile("s_waitcnt vmcnt(" #n ")" ::: "memory")
; #define PG8_WAIT_L(n) asm volatile("s_waitcnt lgkmcnt(" #n ")" ::: "memory")
; #define PG8_BAR __builtin_amdgcn_s_barrier()
; #define PG8_SCHED __builtin_amdgcn_sched_barrier(0)
; template <class Epi, class Sched>
; __device__ __forceinline__ void gemm_phase(LAS unsigned char* lds, const Gemm g, const Sched& S, const Epi& E, const int wave_) {
;     ...
;         for (int t = 0; t < nt; t += 2) {
;     ...
;             PG8_LDA(At, 1, 1); PG8_STAGE(PG8_SB(1, 0), b3, voffB); PG8_STAGE(PG8_SB(1, 1), b3 + hstepB, voffB); PG8_STAGE(PG8_SA(1, 0), a3, voffA);
;             PG8_WAIT_V(8); PG8_WAIT_L(0); PG8_BAR; PG8_MMA(1, 0, At, B0); PG8_MMA(1, 1, At, B1); PG8_BAR; PG8_SCHED;
	s_add_i32 s21, s21, s83
	v_lshl_add_u64 v[220:221], v[220:221], 0, s[8:9]
	s_mov_b32 m0, s21
	ds_read_b128 v[188:191], v150 offset:49152
	ds_read_b128 v[192:195], v150 offset:50176
	ds_read_b128 v[196:199], v150 offset:51200
	ds_read_b128 v[200:203], v150 offset:52224
	ds_read_b128 v[204:207], v150 offset:53248
	ds_read_b128 v[208:211], v150 offset:54272
	ds_read_b128 v[212:215], v150 offset:55296
	ds_read_b128 v[216:219], v150 offset:56320
	global_load_lds_dwordx4 v[220:221], off
	s_add_i32 m0, s21, 0x2000
	s_add_u32 s56, s56, 0x40080
	v_lshl_add_u64 v[220:221], v[222:223], 0, s[8:9]
	s_addc_u32 s57, s57, 0
	s_add_i32 s21, s81, s83
	global_load_lds_dwordx4 v[220:221], off
	v_lshl_add_u64 v[220:221], s[56:57], 0, v[130:131]
	s_mov_b32 m0, s21
	s_nop 0
	global_load_lds_dwordx4 v[220:221], off
	v_lshl_add_u64 v[220:221], s[56:57], 0, v[134:135]
	s_add_i32 m0, s21, 0x2000
	s_nop 0
	global_load_lds_dwordx4 v[220:221], off
	v_lshl_add_u64 v[220:221], v[224:225], 0, s[8:9]
	s_mov_b32 m0, s67
	s_nop 0
	global_load_lds_dwordx4 v[220:221], off
	v_lshl_add_u64 v[220:221], v[226:227], 0, s[8:9]
	s_mov_b32 m0, s68
	s_nop 0
	global_load_lds_dwordx4 v[220:221], off
	s_waitcnt vmcnt(8)
	s_waitcnt lgkmcnt(0)
	s_barrier
	s_waitcnt lgkmcnt(0)
	v_mfma_f32_16x16x32_bf16 v[60:63], v[152:155], v[188:191], v[60:63]
	v_mfma_f32_16x16x32_bf16 v[56:59], v[160:163], v[188:191], v[56:59]
	v_mfma_f32_16x16x32_bf16 v[44:47], v[152:155], v[196:199], v[44:47]
	v_mfma_f32_16x16x32_bf16 v[40:43], v[160:163], v[196:199], v[40:43]
	v_mfma_f32_16x16x32_bf16 v[28:31], v[152:155], v[204:207], v[28:31]
	v_mfma_f32_16x16x32_bf16 v[24:27], v[160:163], v[204:207], v[24:27]
	v_mfma_f32_16x16x32_bf16 v[12:15], v[152:155], v[212:215], v[12:15]
	v_mfma_f32_16x16x32_bf16 v[8:11], v[160:163], v[212:215], v[8:11]
	v_mfma_f32_16x16x32_bf16 v[60:63], v[156:159], v[192:195], v[60:63]
	v_mfma_f32_16x16x32_bf16 v[56:59], v[164:167], v[192:195], v[56:59]
	v_mfma_f32_16x16x32_bf16 v[44:47], v[156:159], v[200:203], v[44:47]
	v_mfma_f32_16x16x32_bf16 v[40:43], v[164:167], v[200:203], v[40:43]
	v_mfma_f32_16x16x32_bf16 v[28:31], v[156:159], v[208:211], v[28:31]
	v_mfma_f32_16x16x32_bf16 v[24:27], v[164:167], v[208:211], v[24:27]
	v_mfma_f32_16x16x32_bf16 v[12:15], v[156:159], v[216:219], v[12:15]
	v_mfma_f32_16x16x32_bf16 v[8:11], v[164:167], v[216:219], v[8:11]
	v_mfma_f32_16x16x32_bf16 v[52:55], v[168:171], v[188:191], v[52:55]
	v_mfma_f32_16x16x32_bf16 v[48:51], v[176:179], v[188:191], v[48:51]
	v_mfma_f32_16x16x32_bf16 v[36:39], v[168:171], v[196:199], v[36:39]
	v_mfma_f32_16x16x32_bf16 v[32:35], v[176:179], v[196:199], v[32:35]
	v_mfma_f32_16x16x32_bf16 v[20:23], v[168:171], v[204:207], v[20:23]
	v_mfma_f32_16x16x32_bf16 v[16:19], v[176:179], v[204:207], v[16:19]
	v_mfma_f32_16x16x32_bf16 v[4:7], v[168:171], v[212:215], v[4:7]
	v_mfma_f32_16x16x32_bf16 v[0:3], v[176:179], v[212:215], v[0:3]
	v_mfma_f32_16x16x32_bf16 v[52:55], v[172:175], v[192:195], v[52:55]
	v_mfma_f32_16x16x32_bf16 v[48:51], v[180:183], v[192:195], v[48:51]
	v_mfma_f32_16x16x32_bf16 v[36:39], v[172:175], v[200:203], v[36:39]
	v_mfma_f32_16x16x32_bf16 v[32:35], v[180:183], v[200:203], v[32:35]
	v_mfma_f32_16x16x32_bf16 v[20:23], v[172:175], v[208:211], v[20:23]
	v_mfma_f32_16x16x32_bf16 v[16:19], v[180:183], v[208:211], v[16:19]
	v_mfma_f32_16x16x32_bf16 v[4:7], v[172:175], v[216:219], v[4:7]
	v_mfma_f32_16x16x32_bf16 v[0:3], v[180:183], v[216:219], v[0:3]
	s_barrier
	s_add_u32 s76, s76, 0x100
	s_addc_u32 s77, s77, 0
	s_add_u32 s54, s54, 0x100
	s_addc_u32 s55, s55, 0
	s_cmp_ge_i32 s78, s66
	s_mov_b32 s56, s78
	s_cbranch_scc0 .LBB0_524

; #define PG8_STAGE(bufoff, gbase, voff) do { _Pragma("unroll") for (int _i = 0; _i < 2; ++_i) \
;         __builtin_amdgcn_global_load_lds((const GAS unsigned*)((const char*)(gbase) + (voff)[_i]), (LAS unsigned*)(lds + (bufoff) + ldsw + _i * 8192), 16, 0, 0); } while (0)
; #define PG8_LDA(dst, b, h) do { _Pragma("unroll") for (int m = 0; m < 4; ++m) _Pragma("unroll") for (int k = 0; k < 2; ++k) dst[m][k] = *(const LAS bf16x8*)(lds + PG8_SA(b, h) + aoff + m * 2048 + k * 1024); } while (0)
; #define PG8_LDB(dst, b, h) do { _Pragma("unroll") for (int n = 0; n < 2; ++n) _Pragma("unroll") for (int k = 0; k < 2; ++k) dst[n][k] = *(const LAS bf16x8*)(lds + PG8_SB(b, h) + boff + n * 2048 + k * 1024); } while (0)
; #define PG8_MMA(ai, bj, At, Bt) do { __builtin_amdgcn_s_setprio(1); _Pragma("unroll") for (int m = 0; m < 4; ++m) _Pragma("unroll") for (int n = 0; n < 2; ++n) _Pragma("unroll") for (int k = 0; k < 2; ++k) \
;         acc[ai][bj][m][n] = __builtin_amdgcn_mfma_f32_16x16x32_bf16(Bt[n][k], At[m][k], acc[ai][bj][m][n], 0, 0, 0); __builtin_amdgcn_s_setprio(0); } while (0)
; #define PG8_WAIT_V(n) asm volatile("s_waitcnt vmcnt(" #n ")" ::: "memory")
; #define PG8_WAIT_L(n) asm volatile("s_waitcnt lgkmcnt(" #n ")" ::: "memory")
; #define PG8_BAR __builtin_amdgcn_s_barrier()
; #define PG8_SCHED __builtin_amdgcn_sched_barrier(0)
; template <class Epi, class Sched>
; __device__ __forceinline__ void gemm_phase(LAS unsigned char* lds, const Gemm g, const Sched& S, const Epi& E, const int wave_) {
;     ...
;             const bool last = (t == nt - 2);
;             const char* a1 = cA + (size_t)(t + 1) * kstep;
;             const char* a2 = last ? nA : cA + (size_t)(t + 2) * kstep; const char* b2 = last ? nB : cB + (size_t)(t + 2) * kstep;
;             const char* a3 = a2 + kstep; const char* b3 = b2 + kstep;
;             PG8_LDB(B0, 0, 0); PG8_LDB(B1, 0, 1); PG8_SCHED; PG8_LDA(At, 0, 0); PG8_STAGE(PG8_SA(1, 1), a1 + hstepA, voffA);
;             PG8_WAIT_V(8); PG8_WAIT_L(0); PG8_BAR; PG8_MMA(0, 0, At, B0); PG8_MMA(0, 1, At, B1); PG8_BAR; PG8_SCHED;
;             PG8_LDA(At, 0, 1); PG8_STAGE(PG8_SB(0, 0), b2, voffB); PG8_STAGE(PG8_SB(0, 1), b2 + hstepB, voffB); PG8_STAGE(PG8_SA(0, 0), a2, voffA);
;             PG8_WAIT_V(8); PG8_WAIT_L(0); PG8_BAR; PG8_MMA(1, 0, At, B0); PG8_MMA(1, 1, At, B1); PG8_BAR; PG8_SCHED;
.LBB0_549:
	ds_read_b128 v[148:151], v145
	ds_read_b128 v[152:155], v145 offset:1024
	ds_read_b128 v[156:159], v145 offset:2048
	ds_read_b128 v[160:163], v145 offset:3072
	ds_read_b128 v[164:167], v146
	ds_read_b128 v[168:171], v146 offset:1024
	ds_read_b128 v[172:175], v146 offset:2048
	ds_read_b128 v[176:179], v146 offset:3072
	s_add_i32 s76, s56, 2
	s_add_u32 s21, s54, 0xfffc0080
	s_addc_u32 s57, s55, -1
	s_cmp_eq_u32 s24, s56
	s_cselect_b32 s56, s73, s74
	s_cselect_b32 s59, s43, s57
	s_cselect_b32 s58, s45, s21
	s_cselect_b32 s57, s72, s75
	v_lshl_add_u64 v[216:217], s[54:55], 0, v[140:141]
	s_add_i32 m0, s62, 0xc000
	ds_read_b128 v[180:183], v147
	ds_read_b128 v[188:191], v147 offset:1024
	ds_read_b128 v[192:195], v147 offset:2048
	ds_read_b128 v[196:199], v147 offset:3072
	ds_read_b128 v[200:203], v147 offset:4096
	ds_read_b128 v[204:207], v147 offset:5120
	ds_read_b128 v[208:211], v147 offset:6144
	ds_read_b128 v[212:215], v147 offset:7168
	global_load_lds_dwordx4 v[216:217], off
	v_lshl_add_u64 v[216:217], s[54:55], 0, v[138:139]
	s_add_i32 m0, s62, 0xe000
	s_nop 0
	global_load_lds_dwordx4 v[216:217], off
	s_waitcnt vmcnt(8)
	s_waitcnt lgkmcnt(0)
	s_barrier
	s_waitcnt lgkmcnt(0)
	v_mfma_f32_16x16x32_bf16 v[120:123], v[148:151], v[180:183], v[120:123]
	v_mfma_f32_16x16x32_bf16 v[124:127], v[156:159], v[180:183], v[124:127]
	v_mfma_f32_16x16x32_bf16 v[108:111], v[148:151], v[192:195], v[108:111]
	v_mfma_f32_16x16x32_bf16 v[104:107], v[156:159], v[192:195], v[104:107]
	v_mfma_f32_16x16x32_bf16 v[92:95], v[148:151], v[200:203], v[92:95]
	v_mfma_f32_16x16x32_bf16 v[88:91], v[156:159], v[200:203], v[88:91]
	v_mfma_f32_16x16x32_bf16 v[76:79], v[148:151], v[208:211], v[76:79]
	v_mfma_f32_16x16x32_bf16 v[72:75], v[156:159], v[208:211], v[72:75]
	v_mfma_f32_16x16x32_bf16 v[120:123], v[152:155], v[188:191], v[120:123]
	v_mfma_f32_16x16x32_bf16 v[124:127], v[160:163], v[188:191], v[124:127]
	v_mfma_f32_16x16x32_bf16 v[108:111], v[152:155], v[196:199], v[108:111]
	v_mfma_f32_16x16x32_bf16 v[104:107], v[160:163], v[196:199], v[104:107]
	v_mfma_f32_16x16x32_bf16 v[92:95], v[152:155], v[204:207], v[92:95]
	v_mfma_f32_16x16x32_bf16 v[88:91], v[160:163], v[204:207], v[88:91]
	v_mfma_f32_16x16x32_bf16 v[76:79], v[152:155], v[212:215], v[76:79]
	v_mfma_f32_16x16x32_bf16 v[72:75], v[160:163], v[212:215], v[72:75]
	v_mfma_f32_16x16x32_bf16 v[116:119], v[164:167], v[180:183], v[116:119]
	v_mfma_f32_16x16x32_bf16 v[112:115], v[172:175], v[180:183], v[112:115]
	v_mfma_f32_16x16x32_bf16 v[100:103], v[164:167], v[192:195], v[100:103]
	v_mfma_f32_16x16x32_bf16 v[96:99], v[172:175], v[192:195], v[96:99]
	v_mfma_f32_16x16x32_bf16 v[84:87], v[164:167], v[200:203], v[84:87]
	v_mfma_f32_16x16x32_bf16 v[80:83], v[172:175], v[200:203], v[80:83]
	v_mfma_f32_16x16x32_bf16 v[68:71], v[164:167], v[208:211], v[68:71]
	v_mfma_f32_16x16x32_bf16 v[64:67], v[172:175], v[208:211], v[64:67]
	v_mfma_f32_16x16x32_bf16 v[116:119], v[168:171], v[188:191], v[116:119]
	v_mfma_f32_16x16x32_bf16 v[112:115], v[176:179], v[188:191], v[112:115]
	v_mfma_f32_16x16x32_bf16 v[100:103], v[168:171], v[196:199], v[100:103]
	v_mfma_f32_16x16x32_bf16 v[96:99], v[176:179], v[196:199], v[96:99]
	v_mfma_f32_16x16x32_bf16 v[84:87], v[168:171], v[204:207], v[84:87]
	v_mfma_f32_16x16x32_bf16 v[80:83], v[176:179], v[204:207], v[80:83]
	v_mfma_f32_16x16x32_bf16 v[68:71], v[168:171], v[212:215], v[68:71]
	v_mfma_f32_16x16x32_bf16 v[64:67], v[176:179], v[212:215], v[64:67]
	s_barrier
	s_add_i32 s21, s70, s83
	v_lshl_add_u64 v[216:217], s[56:57], 0, v[130:131]
	s_mov_b32 m0, s21
	ds_read_b128 v[180:183], v147 offset:16384
	ds_read_b128 v[188:191], v147 offset:17408
	ds_read_b128 v[192:195], v147 offset:18432
	ds_read_b128 v[196:199], v147 offset:19456
	ds_read_b128 v[200:203], v147 offset:20480
	ds_read_b128 v[204:207], v147 offset:21504
	ds_read_b128 v[208:211], v147 offset:22528
	ds_read_b128 v[212:215], v147 offset:23552
	global_load_lds_dwordx4 v[216:217], off
	s_add_i32 m0, s21, 0x2000
	s_add_u32 s90, s56, 0x40000
	v_lshl_add_u64 v[218:219], s[56:57], 0, v[134:135]
	s_addc_u32 s91, s57, 0
	s_add_i32 s21, s71, s83
	global_load_lds_dwordx4 v[218:219], off
	v_lshl_add_u64 v[220:221], s[90:91], 0, v[130:131]
	s_mov_b32 m0, s21
	v_lshl_add_u64 v[222:223], s[58:59], 0, v[132:133]
	global_load_lds_dwordx4 v[220:221], off
	v_lshl_add_u64 v[220:221], s[90:91], 0, v[134:135]
	s_add_i32 m0, s21, 0x2000
	s_nop 0
	global_load_lds_dwordx4 v[220:221], off
	v_lshl_add_u64 v[220:221], s[58:59], 0, v[128:129]
	s_mov_b32 m0, s62
	s_nop 0
	global_load_lds_dwordx4 v[220:221], off
	s_mov_b32 m0, s63
	s_nop 0
	global_load_lds_dwordx4 v[222:223], off
	s_waitcnt vmcnt(8)
	s_waitcnt lgkmcnt(0)
	s_barrier
; #define PG8_STAGE(bufoff, gbase, voff) do { _Pragma("unroll") for (int _i = 0; _i < 2; ++_i) \
;         __builtin_amdgcn_global_load_lds((const GAS unsigned*)((const char*)(gbase) + (voff)[_i]), (LAS unsigned*)(lds + (bufoff) + ldsw + _i * 8192), 16, 0, 0); } while (0)
; #define PG8_LDA(dst, b, h) do { _Pragma("unroll") for (int m = 0; m < 4; ++m) _Pragma("unroll") for (int k = 0; k < 2; ++k) dst[m][k] = *(const LAS bf16x8*)(lds + PG8_SA(b, h) + aoff + m * 2048 + k * 1024); } while (0)
; #define PG8_LDB(dst, b, h) do { _Pragma("unroll") for (int n = 0; n < 2; ++n) _Pragma("unroll") for (int k = 0; k < 2; ++k) dst[n][k] = *(const LAS bf16x8*)(lds + PG8_SB(b, h) + boff + n * 2048 + k * 1024); } while (0)
; #define PG8_MMA(ai, bj, At, Bt) do { __builtin_amdgcn_s_setprio(1); _Pragma("unroll") for (int m = 0; m < 4; ++m) _Pragma("unroll") for (int n = 0; n < 2; ++n) _Pragma("unroll") for (int k = 0; k < 2; ++k) \
;         acc[ai][bj][m][n] = __builtin_amdgcn_mfma_f32_16x16x32_bf16(Bt[n][k], At[m][k], acc[ai][bj][m][n], 0, 0, 0); __builtin_amdgcn_s_setprio(0); } while (0)
; #define PG8_WAIT_V(n) asm volatile("s_waitcnt vmcnt(" #n ")" ::: "memory")
; #define PG8_WAIT_L(n) asm volatile("s_waitcnt lgkmcnt(" #n ")" ::: "memory")
; #define PG8_BAR __builtin_amdgcn_s_barrier()
; #define PG8_SCHED __builtin_amdgcn_sched_barrier(0)
; template <class Epi, class Sched>
; __device__ __forceinline__ void gemm_phase(LAS unsigned char* lds, const Gemm g, const Sched& S, const Epi& E, const int wave_) {
;     ...
;             PG8_WAIT_V(8); PG8_WAIT_L(0); PG8_BAR; PG8_MMA(1, 0, At, B0); PG8_MMA(1, 1, At, B1); PG8_BAR; PG8_SCHED;
;             PG8_LDB(B0, 1, 0); PG8_LDB(B1, 1, 1); PG8_SCHED; PG8_LDA(At, 1, 0); PG8_STAGE(PG8_SA(0, 1), a2 + hstepA, voffA);
;             PG8_WAIT_V(8); PG8_WAIT_L(0); PG8_BAR; PG8_MMA(0, 0, At, B0); PG8_MMA(0, 1, At, B1); PG8_BAR; PG8_SCHED;
	s_waitcnt lgkmcnt(0)
	v_mfma_f32_16x16x32_bf16 v[60:63], v[148:151], v[180:183], v[60:63]
	v_mfma_f32_16x16x32_bf16 v[56:59], v[156:159], v[180:183], v[56:59]
	v_mfma_f32_16x16x32_bf16 v[44:47], v[148:151], v[192:195], v[44:47]
	v_mfma_f32_16x16x32_bf16 v[40:43], v[156:159], v[192:195], v[40:43]
	v_mfma_f32_16x16x32_bf16 v[28:31], v[148:151], v[200:203], v[28:31]
	v_mfma_f32_16x16x32_bf16 v[24:27], v[156:159], v[200:203], v[24:27]
	v_mfma_f32_16x16x32_bf16 v[12:15], v[148:151], v[208:211], v[12:15]
	v_mfma_f32_16x16x32_bf16 v[8:11], v[156:159], v[208:211], v[8:11]
	v_mfma_f32_16x16x32_bf16 v[60:63], v[152:155], v[188:191], v[60:63]
	v_mfma_f32_16x16x32_bf16 v[56:59], v[160:163], v[188:191], v[56:59]
	v_mfma_f32_16x16x32_bf16 v[44:47], v[152:155], v[196:199], v[44:47]
	v_mfma_f32_16x16x32_bf16 v[40:43], v[160:163], v[196:199], v[40:43]
	v_mfma_f32_16x16x32_bf16 v[28:31], v[152:155], v[204:207], v[28:31]
	v_mfma_f32_16x16x32_bf16 v[24:27], v[160:163], v[204:207], v[24:27]
	v_mfma_f32_16x16x32_bf16 v[12:15], v[152:155], v[212:215], v[12:15]
	v_mfma_f32_16x16x32_bf16 v[8:11], v[160:163], v[212:215], v[8:11]
	v_mfma_f32_16x16x32_bf16 v[52:55], v[164:167], v[180:183], v[52:55]
	v_mfma_f32_16x16x32_bf16 v[48:51], v[172:175], v[180:183], v[48:51]
	v_mfma_f32_16x16x32_bf16 v[36:39], v[164:167], v[192:195], v[36:39]
	v_mfma_f32_16x16x32_bf16 v[32:35], v[172:175], v[192:195], v[32:35]
	v_mfma_f32_16x16x32_bf16 v[20:23], v[164:167], v[200:203], v[20:23]
	v_mfma_f32_16x16x32_bf16 v[16:19], v[172:175], v[200:203], v[16:19]
	v_mfma_f32_16x16x32_bf16 v[4:7], v[164:167], v[208:211], v[4:7]
	v_mfma_f32_16x16x32_bf16 v[0:3], v[172:175], v[208:211], v[0:3]
	v_mfma_f32_16x16x32_bf16 v[52:55], v[168:171], v[188:191], v[52:55]
	v_mfma_f32_16x16x32_bf16 v[48:51], v[176:179], v[188:191], v[48:51]
	v_mfma_f32_16x16x32_bf16 v[36:39], v[168:171], v[196:199], v[36:39]
	v_mfma_f32_16x16x32_bf16 v[32:35], v[176:179], v[196:199], v[32:35]
	v_mfma_f32_16x16x32_bf16 v[20:23], v[168:171], v[204:207], v[20:23]
	v_mfma_f32_16x16x32_bf16 v[16:19], v[176:179], v[204:207], v[16:19]
	v_mfma_f32_16x16x32_bf16 v[4:7], v[168:171], v[212:215], v[4:7]
	v_mfma_f32_16x16x32_bf16 v[0:3], v[176:179], v[212:215], v[0:3]
	s_barrier
	s_add_i32 s21, 0, 0x18000
	s_add_i32 s77, 0, 0x1c000
	v_add_u32_e32 v160, s21, v144
	v_add_u32_e32 v176, s77, v144
	ds_read_b128 v[148:151], v160
	ds_read_b128 v[152:155], v160 offset:1024
	ds_read_b128 v[156:159], v160 offset:2048
	ds_read_b128 v[160:163], v160 offset:3072
	ds_read_b128 v[164:167], v176
	ds_read_b128 v[168:171], v176 offset:1024
	ds_read_b128 v[172:175], v176 offset:2048
	ds_read_b128 v[176:179], v176 offset:3072
	s_add_u32 s58, s58, 0x40000
	s_addc_u32 s59, s59, 0
	s_mov_b32 m0, s64
	v_lshl_add_u64 v[224:225], s[58:59], 0, v[128:129]
	ds_read_b128 v[180:183], v147 offset:32768
	ds_read_b128 v[188:191], v147 offset:33792
	ds_read_b128 v[192:195], v147 offset:34816
	ds_read_b128 v[196:199], v147 offset:35840
	ds_read_b128 v[200:203], v147 offset:36864
	ds_read_b128 v[204:207], v147 offset:37888
	ds_read_b128 v[208:211], v147 offset:38912
	ds_read_b128 v[212:215], v147 offset:39936
	global_load_lds_dwordx4 v[224:225], off
	v_lshl_add_u64 v[224:225], s[58:59], 0, v[132:133]
	s_mov_b32 m0, s65
	s_nop 0
	global_load_lds_dwordx4 v[224:225], off
	s_waitcnt vmcnt(8)
	s_waitcnt lgkmcnt(0)
	s_barrier
	s_waitcnt lgkmcnt(0)
	v_mfma_f32_16x16x32_bf16 v[120:123], v[148:151], v[180:183], v[120:123]
	v_mfma_f32_16x16x32_bf16 v[124:127], v[156:159], v[180:183], v[124:127]
	v_mfma_f32_16x16x32_bf16 v[108:111], v[148:151], v[192:195], v[108:111]
	v_mfma_f32_16x16x32_bf16 v[104:107], v[156:159], v[192:195], v[104:107]
	v_mfma_f32_16x16x32_bf16 v[92:95], v[148:151], v[200:203], v[92:95]
	v_mfma_f32_16x16x32_bf16 v[88:91], v[156:159], v[200:203], v[88:91]
	v_mfma_f32_16x16x32_bf16 v[76:79], v[148:151], v[208:211], v[76:79]
	v_mfma_f32_16x16x32_bf16 v[72:75], v[156:159], v[208:211], v[72:75]
	v_mfma_f32_16x16x32_bf16 v[120:123], v[152:155], v[188:191], v[120:123]
	v_mfma_f32_16x16x32_bf16 v[124:127], v[160:163], v[188:191], v[124:127]
	v_mfma_f32_16x16x32_bf16 v[108:111], v[152:155], v[196:199], v[108:111]
	v_mfma_f32_16x16x32_bf16 v[104:107], v[160:163], v[196:199], v[104:107]
	v_mfma_f32_16x16x32_bf16 v[92:95], v[152:155], v[204:207], v[92:95]
	v_mfma_f32_16x16x32_bf16 v[88:91], v[160:163], v[204:207], v[88:91]
	v_mfma_f32_16x16x32_bf16 v[76:79], v[152:155], v[212:215], v[76:79]
	v_mfma_f32_16x16x32_bf16 v[72:75], v[160:163], v[212:215], v[72:75]
	v_mfma_f32_16x16x32_bf16 v[116:119], v[164:167], v[180:183], v[116:119]
	v_mfma_f32_16x16x32_bf16 v[112:115], v[172:175], v[180:183], v[112:115]
	v_mfma_f32_16x16x32_bf16 v[100:103], v[164:167], v[192:195], v[100:103]
	v_mfma_f32_16x16x32_bf16 v[96:99], v[172:175], v[192:195], v[96:99]
	v_mfma_f32_16x16x32_bf16 v[84:87], v[164:167], v[200:203], v[84:87]
	v_mfma_f32_16x16x32_bf16 v[80:83], v[172:175], v[200:203], v[80:83]
	v_mfma_f32_16x16x32_bf16 v[68:71], v[164:167], v[208:211], v[68:71]
	v_mfma_f32_16x16x32_bf16 v[64:67], v[172:175], v[208:211], v[64:67]
	v_mfma_f32_16x16x32_bf16 v[116:119], v[168:171], v[188:191], v[116:119]
	v_mfma_f32_16x16x32_bf16 v[112:115], v[176:179], v[188:191], v[112:115]
	v_mfma_f32_16x16x32_bf16 v[100:103], v[168:171], v[196:199], v[100:103]
	v_mfma_f32_16x16x32_bf16 v[96:99], v[176:179], v[196:199], v[96:99]
	v_mfma_f32_16x16x32_bf16 v[84:87], v[168:171], v[204:207], v[84:87]
	v_mfma_f32_16x16x32_bf16 v[80:83], v[176:179], v[204:207], v[80:83]
	v_mfma_f32_16x16x32_bf16 v[68:71], v[168:171], v[212:215], v[68:71]
	v_mfma_f32_16x16x32_bf16 v[64:67], v[176:179], v[212:215], v[64:67]
	s_barrier
; #define PG8_STAGE(bufoff, gbase, voff) do { _Pragma("unroll") for (int _i = 0; _i < 2; ++_i) \
;         __builtin_amdgcn_global_load_lds((const GAS unsigned*)((const char*)(gbase) + (voff)[_i]), (LAS unsigned*)(lds + (bufoff) + ldsw + _i * 8192), 16, 0, 0); } while (0)
; #define PG8_LDA(dst, b, h) do { _Pragma("unroll") for (int m = 0; m < 4; ++m) _Pragma("unroll") for (int k = 0; k < 2; ++k) dst[m][k] = *(const LAS bf16x8*)(lds + PG8_SA(b, h) + aoff + m * 2048 + k * 1024); } while (0)
; #define PG8_MMA(ai, bj, At, Bt) do { __builtin_amdgcn_s_setprio(1); _Pragma("unroll") for (int m = 0; m < 4; ++m) _Pragma("unroll") for (int n = 0; n < 2; ++n) _Pragma("unroll") for (int k = 0; k < 2; ++k) \
;         acc[ai][bj][m][n] = __builtin_amdgcn_mfma_f32_16x16x32_bf16(Bt[n][k], At[m][k], acc[ai][bj][m][n], 0, 0, 0); __builtin_amdgcn_s_setprio(0); } while (0)
; #define PG8_WAIT_V(n) asm volatile("s_waitcnt vmcnt(" #n ")" ::: "memory")
; #define PG8_WAIT_L(n) asm volatile("s_waitcnt lgkmcnt(" #n ")" ::: "memory")
; #define PG8_BAR __builtin_amdgcn_s_barrier()
; #define PG8_SCHED __builtin_amdgcn_sched_barrier(0)
; template <class Epi, class Sched>
; __device__ __forceinline__ void gemm_phase(LAS unsigned char* lds, const Gemm g, const Sched& S, const Epi& E, const int wave_) {
;     ...
;         for (int t = 0; t < nt; t += 2) {
;     ...
;             PG8_LDA(At, 1, 1); PG8_STAGE(PG8_SB(1, 0), b3, voffB); PG8_STAGE(PG8_SB(1, 1), b3 + hstepB, voffB); PG8_STAGE(PG8_SA(1, 0), a3, voffA);
;             PG8_WAIT_V(8); PG8_WAIT_L(0); PG8_BAR; PG8_MMA(1, 0, At, B0); PG8_MMA(1, 1, At, B1); PG8_BAR; PG8_SCHED;
	s_add_i32 s21, s21, s83
	v_lshl_add_u64 v[216:217], v[216:217], 0, s[6:7]
	s_mov_b32 m0, s21
	ds_read_b128 v[180:183], v147 offset:49152
	ds_read_b128 v[188:191], v147 offset:50176
	ds_read_b128 v[192:195], v147 offset:51200
	ds_read_b128 v[196:199], v147 offset:52224
	ds_read_b128 v[200:203], v147 offset:53248
	ds_read_b128 v[204:207], v147 offset:54272
	ds_read_b128 v[208:211], v147 offset:55296
	ds_read_b128 v[212:215], v147 offset:56320
	global_load_lds_dwordx4 v[216:217], off
	s_add_i32 m0, s21, 0x2000
	s_add_u32 s56, s56, 0x40080
	v_lshl_add_u64 v[216:217], v[218:219], 0, s[6:7]
	s_addc_u32 s57, s57, 0
	s_add_i32 s21, s77, s83
	global_load_lds_dwordx4 v[216:217], off
	v_lshl_add_u64 v[216:217], s[56:57], 0, v[130:131]
	s_mov_b32 m0, s21
	s_nop 0
	global_load_lds_dwordx4 v[216:217], off
	v_lshl_add_u64 v[216:217], s[56:57], 0, v[134:135]
	s_add_i32 m0, s21, 0x2000
	s_nop 0
	global_load_lds_dwordx4 v[216:217], off
	v_lshl_add_u64 v[216:217], v[220:221], 0, s[6:7]
	s_mov_b32 m0, s68
	s_nop 0
	global_load_lds_dwordx4 v[216:217], off
	v_lshl_add_u64 v[216:217], v[222:223], 0, s[6:7]
	s_mov_b32 m0, s69
	s_nop 0
	global_load_lds_dwordx4 v[216:217], off
	s_waitcnt vmcnt(8)
	s_waitcnt lgkmcnt(0)
	s_barrier
	s_waitcnt lgkmcnt(0)
	v_mfma_f32_16x16x32_bf16 v[60:63], v[148:151], v[180:183], v[60:63]
	v_mfma_f32_16x16x32_bf16 v[56:59], v[156:159], v[180:183], v[56:59]
	v_mfma_f32_16x16x32_bf16 v[44:47], v[148:151], v[192:195], v[44:47]
	v_mfma_f32_16x16x32_bf16 v[40:43], v[156:159], v[192:195], v[40:43]
	v_mfma_f32_16x16x32_bf16 v[28:31], v[148:151], v[200:203], v[28:31]
	v_mfma_f32_16x16x32_bf16 v[24:27], v[156:159], v[200:203], v[24:27]
	v_mfma_f32_16x16x32_bf16 v[12:15], v[148:151], v[208:211], v[12:15]
	v_mfma_f32_16x16x32_bf16 v[8:11], v[156:159], v[208:211], v[8:11]
	v_mfma_f32_16x16x32_bf16 v[60:63], v[152:155], v[188:191], v[60:63]
	v_mfma_f32_16x16x32_bf16 v[56:59], v[160:163], v[188:191], v[56:59]
	v_mfma_f32_16x16x32_bf16 v[44:47], v[152:155], v[196:199], v[44:47]
	v_mfma_f32_16x16x32_bf16 v[40:43], v[160:163], v[196:199], v[40:43]
	v_mfma_f32_16x16x32_bf16 v[28:31], v[152:155], v[204:207], v[28:31]
	v_mfma_f32_16x16x32_bf16 v[24:27], v[160:163], v[204:207], v[24:27]
	v_mfma_f32_16x16x32_bf16 v[12:15], v[152:155], v[212:215], v[12:15]
	v_mfma_f32_16x16x32_bf16 v[8:11], v[160:163], v[212:215], v[8:11]
	v_mfma_f32_16x16x32_bf16 v[52:55], v[164:167], v[180:183], v[52:55]
	v_mfma_f32_16x16x32_bf16 v[48:51], v[172:175], v[180:183], v[48:51]
	v_mfma_f32_16x16x32_bf16 v[36:39], v[164:167], v[192:195], v[36:39]
	v_mfma_f32_16x16x32_bf16 v[32:35], v[172:175], v[192:195], v[32:35]
	v_mfma_f32_16x16x32_bf16 v[20:23], v[164:167], v[200:203], v[20:23]
	v_mfma_f32_16x16x32_bf16 v[16:19], v[172:175], v[200:203], v[16:19]
	v_mfma_f32_16x16x32_bf16 v[4:7], v[164:167], v[208:211], v[4:7]
	v_mfma_f32_16x16x32_bf16 v[0:3], v[172:175], v[208:211], v[0:3]
	v_mfma_f32_16x16x32_bf16 v[52:55], v[168:171], v[188:191], v[52:55]
	v_mfma_f32_16x16x32_bf16 v[48:51], v[176:179], v[188:191], v[48:51]
	v_mfma_f32_16x16x32_bf16 v[36:39], v[168:171], v[196:199], v[36:39]
	v_mfma_f32_16x16x32_bf16 v[32:35], v[176:179], v[196:199], v[32:35]
	v_mfma_f32_16x16x32_bf16 v[20:23], v[168:171], v[204:207], v[20:23]
	v_mfma_f32_16x16x32_bf16 v[16:19], v[176:179], v[204:207], v[16:19]
	v_mfma_f32_16x16x32_bf16 v[4:7], v[168:171], v[212:215], v[4:7]
	v_mfma_f32_16x16x32_bf16 v[0:3], v[176:179], v[212:215], v[0:3]
	s_barrier
	s_add_u32 s74, s74, 0x100
	s_addc_u32 s75, s75, 0
	s_add_u32 s54, s54, 0x100
	s_addc_u32 s55, s55, 0
	s_cmp_ge_i32 s76, s67
	s_mov_b32 s56, s76
	s_cbranch_scc0 .LBB0_549

; #define PG8_STAGE(bufoff, gbase, voff) do { _Pragma("unroll") for (int _i = 0; _i < 2; ++_i) \
;         __builtin_amdgcn_global_load_lds((const GAS unsigned*)((const char*)(gbase) + (voff)[_i]), (LAS unsigned*)(lds + (bufoff) + ldsw + _i * 8192), 16, 0, 0); } while (0)
; #define PG8_LDA(dst, b, h) do { _Pragma("unroll") for (int m = 0; m < 4; ++m) _Pragma("unroll") for (int k = 0; k < 2; ++k) dst[m][k] = *(const LAS bf16x8*)(lds + PG8_SA(b, h) + aoff + m * 2048 + k * 1024); } while (0)
; #define PG8_LDB(dst, b, h) do { _Pragma("unroll") for (int n = 0; n < 2; ++n) _Pragma("unroll") for (int k = 0; k < 2; ++k) dst[n][k] = *(const LAS bf16x8*)(lds + PG8_SB(b, h) + boff + n * 2048 + k * 1024); } while (0)
; #define PG8_MMA(ai, bj, At, Bt) do { __builtin_amdgcn_s_setprio(1); _Pragma("unroll") for (int m = 0; m < 4; ++m) _Pragma("unroll") for (int n = 0; n < 2; ++n) _Pragma("unroll") for (int k = 0; k < 2; ++k) \
;         acc[ai][bj][m][n] = __builtin_amdgcn_mfma_f32_16x16x32_bf16(Bt[n][k], At[m][k], acc[ai][bj][m][n], 0, 0, 0); __builtin_amdgcn_s_setprio(0); } while (0)
; #define PG8_WAIT_V(n) asm volatile("s_waitcnt vmcnt(" #n ")" ::: "memory")
; #define PG8_WAIT_L(n) asm volatile("s_waitcnt lgkmcnt(" #n ")" ::: "memory")
; #define PG8_BAR __builtin_amdgcn_s_barrier()
; #define PG8_SCHED __builtin_amdgcn_sched_barrier(0)
; template <class Epi, class Sched>
; __device__ __forceinline__ void gemm_phase(LAS unsigned char* lds, const Gemm g, const Sched& S, const Epi& E, const int wave_) {
;     ...
;             const bool last = (t == nt - 2);
;             const char* a1 = cA + (size_t)(t + 1) * kstep;
;             const char* a2 = last ? nA : cA + (size_t)(t + 2) * kstep; const char* b2 = last ? nB : cB + (size_t)(t + 2) * kstep;
;             const char* a3 = a2 + kstep; const char* b3 = b2 + kstep;
;             PG8_LDB(B0, 0, 0); PG8_LDB(B1, 0, 1); PG8_SCHED; PG8_LDA(At, 0, 0); PG8_STAGE(PG8_SA(1, 1), a1 + hstepA, voffA);
;             PG8_WAIT_V(8); PG8_WAIT_L(0); PG8_BAR; PG8_MMA(0, 0, At, B0); PG8_MMA(0, 1, At, B1); PG8_BAR; PG8_SCHED;
;             PG8_LDA(At, 0, 1); PG8_STAGE(PG8_SB(0, 0), b2, voffB); PG8_STAGE(PG8_SB(0, 1), b2 + hstepB, voffB); PG8_STAGE(PG8_SA(0, 0), a2, voffA);
;             PG8_WAIT_V(8); PG8_WAIT_L(0); PG8_BAR; PG8_MMA(1, 0, At, B0); PG8_MMA(1, 1, At, B1); PG8_BAR; PG8_SCHED;
.LBB0_617:
	ds_read_b128 v[154:157], v151
	ds_read_b128 v[158:161], v151 offset:1024
	ds_read_b128 v[162:165], v151 offset:2048
	ds_read_b128 v[166:169], v151 offset:3072
	ds_read_b128 v[170:173], v152
	ds_read_b128 v[174:177], v152 offset:1024
	ds_read_b128 v[178:181], v152 offset:2048
	ds_read_b128 v[188:191], v152 offset:3072
	s_add_i32 s72, s48, 2
	s_add_u32 s21, s46, 0xfffe0080
	s_addc_u32 s49, s47, -1
	s_cmp_eq_u32 s59, s48
	s_cselect_b32 s48, s69, s70
	s_cselect_b32 s51, s66, s49
	s_cselect_b32 s50, s67, s21
	s_cselect_b32 s49, s68, s71
	v_lshl_add_u64 v[182:183], s[46:47], 0, v[140:141]
	s_add_i32 m0, s52, 0xc000
	ds_read_b128 v[192:195], v153
	ds_read_b128 v[196:199], v153 offset:1024
	ds_read_b128 v[200:203], v153 offset:2048
	ds_read_b128 v[204:207], v153 offset:3072
	ds_read_b128 v[208:211], v153 offset:4096
	ds_read_b128 v[212:215], v153 offset:5120
	ds_read_b128 v[216:219], v153 offset:6144
	ds_read_b128 v[220:223], v153 offset:7168
	global_load_lds_dwordx4 v[182:183], off
	v_lshl_add_u64 v[182:183], s[46:47], 0, v[138:139]
	s_add_i32 m0, s52, 0xe000
	s_nop 0
	global_load_lds_dwordx4 v[182:183], off
	s_waitcnt vmcnt(8)
	s_waitcnt lgkmcnt(0)
	s_barrier
	s_waitcnt lgkmcnt(0)
	v_mfma_f32_16x16x32_bf16 v[124:127], v[154:157], v[192:195], v[124:127]
	v_mfma_f32_16x16x32_bf16 v[120:123], v[162:165], v[192:195], v[120:123]
	v_mfma_f32_16x16x32_bf16 v[108:111], v[154:157], v[200:203], v[108:111]
	v_mfma_f32_16x16x32_bf16 v[104:107], v[162:165], v[200:203], v[104:107]
	v_mfma_f32_16x16x32_bf16 v[92:95], v[154:157], v[208:211], v[92:95]
	v_mfma_f32_16x16x32_bf16 v[88:91], v[162:165], v[208:211], v[88:91]
	v_mfma_f32_16x16x32_bf16 v[76:79], v[154:157], v[216:219], v[76:79]
	v_mfma_f32_16x16x32_bf16 v[72:75], v[162:165], v[216:219], v[72:75]
	v_mfma_f32_16x16x32_bf16 v[124:127], v[158:161], v[196:199], v[124:127]
	v_mfma_f32_16x16x32_bf16 v[120:123], v[166:169], v[196:199], v[120:123]
	v_mfma_f32_16x16x32_bf16 v[108:111], v[158:161], v[204:207], v[108:111]
	v_mfma_f32_16x16x32_bf16 v[104:107], v[166:169], v[204:207], v[104:107]
	v_mfma_f32_16x16x32_bf16 v[92:95], v[158:161], v[212:215], v[92:95]
	v_mfma_f32_16x16x32_bf16 v[88:91], v[166:169], v[212:215], v[88:91]
	v_mfma_f32_16x16x32_bf16 v[76:79], v[158:161], v[220:223], v[76:79]
	v_mfma_f32_16x16x32_bf16 v[72:75], v[166:169], v[220:223], v[72:75]
	v_mfma_f32_16x16x32_bf16 v[116:119], v[170:173], v[192:195], v[116:119]
	v_mfma_f32_16x16x32_bf16 v[112:115], v[178:181], v[192:195], v[112:115]
	v_mfma_f32_16x16x32_bf16 v[100:103], v[170:173], v[200:203], v[100:103]
	v_mfma_f32_16x16x32_bf16 v[96:99], v[178:181], v[200:203], v[96:99]
	v_mfma_f32_16x16x32_bf16 v[84:87], v[170:173], v[208:211], v[84:87]
	v_mfma_f32_16x16x32_bf16 v[80:83], v[178:181], v[208:211], v[80:83]
	v_mfma_f32_16x16x32_bf16 v[68:71], v[170:173], v[216:219], v[68:71]
	v_mfma_f32_16x16x32_bf16 v[64:67], v[178:181], v[216:219], v[64:67]
	v_mfma_f32_16x16x32_bf16 v[116:119], v[174:177], v[196:199], v[116:119]
	v_mfma_f32_16x16x32_bf16 v[112:115], v[188:191], v[196:199], v[112:115]
	v_mfma_f32_16x16x32_bf16 v[100:103], v[174:177], v[204:207], v[100:103]
	v_mfma_f32_16x16x32_bf16 v[96:99], v[188:191], v[204:207], v[96:99]
	v_mfma_f32_16x16x32_bf16 v[84:87], v[174:177], v[212:215], v[84:87]
	v_mfma_f32_16x16x32_bf16 v[80:83], v[188:191], v[212:215], v[80:83]
	v_mfma_f32_16x16x32_bf16 v[68:71], v[174:177], v[220:223], v[68:71]
	v_mfma_f32_16x16x32_bf16 v[64:67], v[188:191], v[220:223], v[64:67]
	s_barrier
	s_add_i32 s21, s62, s83
	v_lshl_add_u64 v[182:183], s[48:49], 0, v[132:133]
	s_mov_b32 m0, s21
	ds_read_b128 v[192:195], v153 offset:16384
	ds_read_b128 v[196:199], v153 offset:17408
	ds_read_b128 v[200:203], v153 offset:18432
	ds_read_b128 v[204:207], v153 offset:19456
	ds_read_b128 v[208:211], v153 offset:20480
	ds_read_b128 v[212:215], v153 offset:21504
	ds_read_b128 v[216:219], v153 offset:22528
	ds_read_b128 v[220:223], v153 offset:23552
	global_load_lds_dwordx4 v[182:183], off
	s_add_i32 m0, s21, 0x2000
	s_add_u32 s74, s48, 0x10000
	v_lshl_add_u64 v[224:225], s[48:49], 0, v[128:129]
	s_addc_u32 s75, s49, 0
	s_add_i32 s21, s63, s83
	global_load_lds_dwordx4 v[224:225], off
	v_lshl_add_u64 v[226:227], s[74:75], 0, v[132:133]
	s_mov_b32 m0, s21
	v_lshl_add_u64 v[228:229], s[50:51], 0, v[130:131]
	global_load_lds_dwordx4 v[226:227], off
	v_lshl_add_u64 v[226:227], s[74:75], 0, v[128:129]
	s_add_i32 m0, s21, 0x2000
	s_nop 0
	global_load_lds_dwordx4 v[226:227], off
	v_lshl_add_u64 v[226:227], s[50:51], 0, v[134:135]
	s_mov_b32 m0, s52
	s_nop 0
	global_load_lds_dwordx4 v[226:227], off
	s_mov_b32 m0, s53
	s_nop 0
	global_load_lds_dwordx4 v[228:229], off
	s_waitcnt vmcnt(8)
	s_waitcnt lgkmcnt(0)
	s_barrier
; #define PG8_STAGE(bufoff, gbase, voff) do { _Pragma("unroll") for (int _i = 0; _i < 2; ++_i) \
;         __builtin_amdgcn_global_load_lds((const GAS unsigned*)((const char*)(gbase) + (voff)[_i]), (LAS unsigned*)(lds + (bufoff) + ldsw + _i * 8192), 16, 0, 0); } while (0)
; #define PG8_LDA(dst, b, h) do { _Pragma("unroll") for (int m = 0; m < 4; ++m) _Pragma("unroll") for (int k = 0; k < 2; ++k) dst[m][k] = *(const LAS bf16x8*)(lds + PG8_SA(b, h) + aoff + m * 2048 + k * 1024); } while (0)
; #define PG8_LDB(dst, b, h) do { _Pragma("unroll") for (int n = 0; n < 2; ++n) _Pragma("unroll") for (int k = 0; k < 2; ++k) dst[n][k] = *(const LAS bf16x8*)(lds + PG8_SB(b, h) + boff + n * 2048 + k * 1024); } while (0)
; #define PG8_MMA(ai, bj, At, Bt) do { __builtin_amdgcn_s_setprio(1); _Pragma("unroll") for (int m = 0; m < 4; ++m) _Pragma("unroll") for (int n = 0; n < 2; ++n) _Pragma("unroll") for (int k = 0; k < 2; ++k) \
;         acc[ai][bj][m][n] = __builtin_amdgcn_mfma_f32_16x16x32_bf16(Bt[n][k], At[m][k], acc[ai][bj][m][n], 0, 0, 0); __builtin_amdgcn_s_setprio(0); } while (0)
; #define PG8_WAIT_V(n) asm volatile("s_waitcnt vmcnt(" #n ")" ::: "memory")
; #define PG8_WAIT_L(n) asm volatile("s_waitcnt lgkmcnt(" #n ")" ::: "memory")
; #define PG8_BAR __builtin_amdgcn_s_barrier()
; #define PG8_SCHED __builtin_amdgcn_sched_barrier(0)
; template <class Epi, class Sched>
; __device__ __forceinline__ void gemm_phase(LAS unsigned char* lds, const Gemm g, const Sched& S, const Epi& E, const int wave_) {
;     ...
;             PG8_WAIT_V(8); PG8_WAIT_L(0); PG8_BAR; PG8_MMA(1, 0, At, B0); PG8_MMA(1, 1, At, B1); PG8_BAR; PG8_SCHED;
;             PG8_LDB(B0, 1, 0); PG8_LDB(B1, 1, 1); PG8_SCHED; PG8_LDA(At, 1, 0); PG8_STAGE(PG8_SA(0, 1), a2 + hstepA, voffA);
;             PG8_WAIT_V(8); PG8_WAIT_L(0); PG8_BAR; PG8_MMA(0, 0, At, B0); PG8_MMA(0, 1, At, B1); PG8_BAR; PG8_SCHED;
	s_waitcnt lgkmcnt(0)
	v_mfma_f32_16x16x32_bf16 v[60:63], v[154:157], v[192:195], v[60:63]
	v_mfma_f32_16x16x32_bf16 v[56:59], v[162:165], v[192:195], v[56:59]
	v_mfma_f32_16x16x32_bf16 v[44:47], v[154:157], v[200:203], v[44:47]
	v_mfma_f32_16x16x32_bf16 v[40:43], v[162:165], v[200:203], v[40:43]
	v_mfma_f32_16x16x32_bf16 v[28:31], v[154:157], v[208:211], v[28:31]
	v_mfma_f32_16x16x32_bf16 v[24:27], v[162:165], v[208:211], v[24:27]
	v_mfma_f32_16x16x32_bf16 v[12:15], v[154:157], v[216:219], v[12:15]
	v_mfma_f32_16x16x32_bf16 v[8:11], v[162:165], v[216:219], v[8:11]
	v_mfma_f32_16x16x32_bf16 v[60:63], v[158:161], v[196:199], v[60:63]
	v_mfma_f32_16x16x32_bf16 v[56:59], v[166:169], v[196:199], v[56:59]
	v_mfma_f32_16x16x32_bf16 v[44:47], v[158:161], v[204:207], v[44:47]
	v_mfma_f32_16x16x32_bf16 v[40:43], v[166:169], v[204:207], v[40:43]
	v_mfma_f32_16x16x32_bf16 v[28:31], v[158:161], v[212:215], v[28:31]
	v_mfma_f32_16x16x32_bf16 v[24:27], v[166:169], v[212:215], v[24:27]
	v_mfma_f32_16x16x32_bf16 v[12:15], v[158:161], v[220:223], v[12:15]
	v_mfma_f32_16x16x32_bf16 v[8:11], v[166:169], v[220:223], v[8:11]
	v_mfma_f32_16x16x32_bf16 v[52:55], v[170:173], v[192:195], v[52:55]
	v_mfma_f32_16x16x32_bf16 v[48:51], v[178:181], v[192:195], v[48:51]
	v_mfma_f32_16x16x32_bf16 v[36:39], v[170:173], v[200:203], v[36:39]
	v_mfma_f32_16x16x32_bf16 v[32:35], v[178:181], v[200:203], v[32:35]
	v_mfma_f32_16x16x32_bf16 v[20:23], v[170:173], v[208:211], v[20:23]
	v_mfma_f32_16x16x32_bf16 v[16:19], v[178:181], v[208:211], v[16:19]
	v_mfma_f32_16x16x32_bf16 v[4:7], v[170:173], v[216:219], v[4:7]
	v_mfma_f32_16x16x32_bf16 v[0:3], v[178:181], v[216:219], v[0:3]
	v_mfma_f32_16x16x32_bf16 v[52:55], v[174:177], v[196:199], v[52:55]
	v_mfma_f32_16x16x32_bf16 v[48:51], v[188:191], v[196:199], v[48:51]
	v_mfma_f32_16x16x32_bf16 v[36:39], v[174:177], v[204:207], v[36:39]
	v_mfma_f32_16x16x32_bf16 v[32:35], v[188:191], v[204:207], v[32:35]
	v_mfma_f32_16x16x32_bf16 v[20:23], v[174:177], v[212:215], v[20:23]
	v_mfma_f32_16x16x32_bf16 v[16:19], v[188:191], v[212:215], v[16:19]
	v_mfma_f32_16x16x32_bf16 v[4:7], v[174:177], v[220:223], v[4:7]
	v_mfma_f32_16x16x32_bf16 v[0:3], v[188:191], v[220:223], v[0:3]
	s_barrier
	s_add_i32 s21, 0, 0x18000
	s_add_i32 s73, 0, 0x1c000
	v_add_u32_e32 v166, s21, v147
	v_add_u32_e32 v188, s73, v147
	ds_read_b128 v[154:157], v166
	ds_read_b128 v[158:161], v166 offset:1024
	ds_read_b128 v[162:165], v166 offset:2048
	ds_read_b128 v[166:169], v166 offset:3072
	ds_read_b128 v[170:173], v188
	ds_read_b128 v[174:177], v188 offset:1024
	ds_read_b128 v[178:181], v188 offset:2048
	ds_read_b128 v[188:191], v188 offset:3072
	s_add_u32 s50, s50, 0x20000
	s_addc_u32 s51, s51, 0
	s_mov_b32 m0, s54
	v_lshl_add_u64 v[230:231], s[50:51], 0, v[134:135]
	ds_read_b128 v[192:195], v153 offset:32768
	ds_read_b128 v[196:199], v153 offset:33792
	ds_read_b128 v[200:203], v153 offset:34816
	ds_read_b128 v[204:207], v153 offset:35840
	ds_read_b128 v[208:211], v153 offset:36864
	ds_read_b128 v[212:215], v153 offset:37888
	ds_read_b128 v[216:219], v153 offset:38912
	ds_read_b128 v[220:223], v153 offset:39936
	global_load_lds_dwordx4 v[230:231], off
	v_lshl_add_u64 v[230:231], s[50:51], 0, v[130:131]
	s_mov_b32 m0, s55
	s_nop 0
	global_load_lds_dwordx4 v[230:231], off
	s_waitcnt vmcnt(8)
	s_waitcnt lgkmcnt(0)
	s_barrier
	s_waitcnt lgkmcnt(0)
	v_mfma_f32_16x16x32_bf16 v[124:127], v[154:157], v[192:195], v[124:127]
	v_mfma_f32_16x16x32_bf16 v[120:123], v[162:165], v[192:195], v[120:123]
	v_mfma_f32_16x16x32_bf16 v[108:111], v[154:157], v[200:203], v[108:111]
	v_mfma_f32_16x16x32_bf16 v[104:107], v[162:165], v[200:203], v[104:107]
	v_mfma_f32_16x16x32_bf16 v[92:95], v[154:157], v[208:211], v[92:95]
	v_mfma_f32_16x16x32_bf16 v[88:91], v[162:165], v[208:211], v[88:91]
	v_mfma_f32_16x16x32_bf16 v[76:79], v[154:157], v[216:219], v[76:79]
	v_mfma_f32_16x16x32_bf16 v[72:75], v[162:165], v[216:219], v[72:75]
	v_mfma_f32_16x16x32_bf16 v[124:127], v[158:161], v[196:199], v[124:127]
	v_mfma_f32_16x16x32_bf16 v[120:123], v[166:169], v[196:199], v[120:123]
	v_mfma_f32_16x16x32_bf16 v[108:111], v[158:161], v[204:207], v[108:111]
	v_mfma_f32_16x16x32_bf16 v[104:107], v[166:169], v[204:207], v[104:107]
	v_mfma_f32_16x16x32_bf16 v[92:95], v[158:161], v[212:215], v[92:95]
	v_mfma_f32_16x16x32_bf16 v[88:91], v[166:169], v[212:215], v[88:91]
	v_mfma_f32_16x16x32_bf16 v[76:79], v[158:161], v[220:223], v[76:79]
	v_mfma_f32_16x16x32_bf16 v[72:75], v[166:169], v[220:223], v[72:75]
	v_mfma_f32_16x16x32_bf16 v[116:119], v[170:173], v[192:195], v[116:119]
	v_mfma_f32_16x16x32_bf16 v[112:115], v[178:181], v[192:195], v[112:115]
	v_mfma_f32_16x16x32_bf16 v[100:103], v[170:173], v[200:203], v[100:103]
	v_mfma_f32_16x16x32_bf16 v[96:99], v[178:181], v[200:203], v[96:99]
	v_mfma_f32_16x16x32_bf16 v[84:87], v[170:173], v[208:211], v[84:87]
	v_mfma_f32_16x16x32_bf16 v[80:83], v[178:181], v[208:211], v[80:83]
	v_mfma_f32_16x16x32_bf16 v[68:71], v[170:173], v[216:219], v[68:71]
	v_mfma_f32_16x16x32_bf16 v[64:67], v[178:181], v[216:219], v[64:67]
	v_mfma_f32_16x16x32_bf16 v[116:119], v[174:177], v[196:199], v[116:119]
	v_mfma_f32_16x16x32_bf16 v[112:115], v[188:191], v[196:199], v[112:115]
	v_mfma_f32_16x16x32_bf16 v[100:103], v[174:177], v[204:207], v[100:103]
	v_mfma_f32_16x16x32_bf16 v[96:99], v[188:191], v[204:207], v[96:99]
	v_mfma_f32_16x16x32_bf16 v[84:87], v[174:177], v[212:215], v[84:87]
	v_mfma_f32_16x16x32_bf16 v[80:83], v[188:191], v[212:215], v[80:83]
	v_mfma_f32_16x16x32_bf16 v[68:71], v[174:177], v[220:223], v[68:71]
	v_mfma_f32_16x16x32_bf16 v[64:67], v[188:191], v[220:223], v[64:67]
	s_barrier
; #define PG8_STAGE(bufoff, gbase, voff) do { _Pragma("unroll") for (int _i = 0; _i < 2; ++_i) \
;         __builtin_amdgcn_global_load_lds((const GAS unsigned*)((const char*)(gbase) + (voff)[_i]), (LAS unsigned*)(lds + (bufoff) + ldsw + _i * 8192), 16, 0, 0); } while (0)
; #define PG8_LDA(dst, b, h) do { _Pragma("unroll") for (int m = 0; m < 4; ++m) _Pragma("unroll") for (int k = 0; k < 2; ++k) dst[m][k] = *(const LAS bf16x8*)(lds + PG8_SA(b, h) + aoff + m * 2048 + k * 1024); } while (0)
; #define PG8_MMA(ai, bj, At, Bt) do { __builtin_amdgcn_s_setprio(1); _Pragma("unroll") for (int m = 0; m < 4; ++m) _Pragma("unroll") for (int n = 0; n < 2; ++n) _Pragma("unroll") for (int k = 0; k < 2; ++k) \
;         acc[ai][bj][m][n] = __builtin_amdgcn_mfma_f32_16x16x32_bf16(Bt[n][k], At[m][k], acc[ai][bj][m][n], 0, 0, 0); __builtin_amdgcn_s_setprio(0); } while (0)
; #define PG8_WAIT_V(n) asm volatile("s_waitcnt vmcnt(" #n ")" ::: "memory")
; #define PG8_WAIT_L(n) asm volatile("s_waitcnt lgkmcnt(" #n ")" ::: "memory")
; #define PG8_BAR __builtin_amdgcn_s_barrier()
; #define PG8_SCHED __builtin_amdgcn_sched_barrier(0)
; template <class Epi, class Sched>
; __device__ __forceinline__ void gemm_phase(LAS unsigned char* lds, const Gemm g, const Sched& S, const Epi& E, const int wave_) {
;     ...
;         for (int t = 0; t < nt; t += 2) {
;     ...
;             PG8_LDA(At, 1, 1); PG8_STAGE(PG8_SB(1, 0), b3, voffB); PG8_STAGE(PG8_SB(1, 1), b3 + hstepB, voffB); PG8_STAGE(PG8_SA(1, 0), a3, voffA);
;             PG8_WAIT_V(8); PG8_WAIT_L(0); PG8_BAR; PG8_MMA(1, 0, At, B0); PG8_MMA(1, 1, At, B1); PG8_BAR; PG8_SCHED;
	s_add_i32 s21, s21, s83
	v_lshl_add_u64 v[182:183], v[182:183], 0, s[36:37]
	s_mov_b32 m0, s21
	ds_read_b128 v[192:195], v153 offset:49152
	ds_read_b128 v[196:199], v153 offset:50176
	ds_read_b128 v[200:203], v153 offset:51200
	ds_read_b128 v[204:207], v153 offset:52224
	ds_read_b128 v[208:211], v153 offset:53248
	ds_read_b128 v[212:215], v153 offset:54272
	ds_read_b128 v[216:219], v153 offset:55296
	ds_read_b128 v[220:223], v153 offset:56320
	global_load_lds_dwordx4 v[182:183], off
	s_add_i32 m0, s21, 0x2000
	s_add_u32 s48, s48, 0x10080
	v_lshl_add_u64 v[182:183], v[224:225], 0, s[36:37]
	s_addc_u32 s49, s49, 0
	s_add_i32 s21, s73, s83
	global_load_lds_dwordx4 v[182:183], off
	v_lshl_add_u64 v[182:183], s[48:49], 0, v[132:133]
	s_mov_b32 m0, s21
	s_nop 0
	global_load_lds_dwordx4 v[182:183], off
	v_lshl_add_u64 v[182:183], s[48:49], 0, v[128:129]
	s_add_i32 m0, s21, 0x2000
	s_nop 0
	global_load_lds_dwordx4 v[182:183], off
	v_lshl_add_u64 v[182:183], v[226:227], 0, s[36:37]
	s_mov_b32 m0, s57
	s_nop 0
	global_load_lds_dwordx4 v[182:183], off
	v_lshl_add_u64 v[182:183], v[228:229], 0, s[36:37]
	s_mov_b32 m0, s58
	s_nop 0
	global_load_lds_dwordx4 v[182:183], off
	s_waitcnt vmcnt(8)
	s_waitcnt lgkmcnt(0)
	s_barrier
	s_waitcnt lgkmcnt(0)
	v_mfma_f32_16x16x32_bf16 v[60:63], v[154:157], v[192:195], v[60:63]
	v_mfma_f32_16x16x32_bf16 v[56:59], v[162:165], v[192:195], v[56:59]
	v_mfma_f32_16x16x32_bf16 v[44:47], v[154:157], v[200:203], v[44:47]
	v_mfma_f32_16x16x32_bf16 v[40:43], v[162:165], v[200:203], v[40:43]
	v_mfma_f32_16x16x32_bf16 v[28:31], v[154:157], v[208:211], v[28:31]
	v_mfma_f32_16x16x32_bf16 v[24:27], v[162:165], v[208:211], v[24:27]
	v_mfma_f32_16x16x32_bf16 v[12:15], v[154:157], v[216:219], v[12:15]
	v_mfma_f32_16x16x32_bf16 v[8:11], v[162:165], v[216:219], v[8:11]
	v_mfma_f32_16x16x32_bf16 v[60:63], v[158:161], v[196:199], v[60:63]
	v_mfma_f32_16x16x32_bf16 v[56:59], v[166:169], v[196:199], v[56:59]
	v_mfma_f32_16x16x32_bf16 v[44:47], v[158:161], v[204:207], v[44:47]
	v_mfma_f32_16x16x32_bf16 v[40:43], v[166:169], v[204:207], v[40:43]
	v_mfma_f32_16x16x32_bf16 v[28:31], v[158:161], v[212:215], v[28:31]
	v_mfma_f32_16x16x32_bf16 v[24:27], v[166:169], v[212:215], v[24:27]
	v_mfma_f32_16x16x32_bf16 v[12:15], v[158:161], v[220:223], v[12:15]
	v_mfma_f32_16x16x32_bf16 v[8:11], v[166:169], v[220:223], v[8:11]
	v_mfma_f32_16x16x32_bf16 v[52:55], v[170:173], v[192:195], v[52:55]
	v_mfma_f32_16x16x32_bf16 v[48:51], v[178:181], v[192:195], v[48:51]
	v_mfma_f32_16x16x32_bf16 v[36:39], v[170:173], v[200:203], v[36:39]
	v_mfma_f32_16x16x32_bf16 v[32:35], v[178:181], v[200:203], v[32:35]
	v_mfma_f32_16x16x32_bf16 v[20:23], v[170:173], v[208:211], v[20:23]
	v_mfma_f32_16x16x32_bf16 v[16:19], v[178:181], v[208:211], v[16:19]
	v_mfma_f32_16x16x32_bf16 v[4:7], v[170:173], v[216:219], v[4:7]
	v_mfma_f32_16x16x32_bf16 v[0:3], v[178:181], v[216:219], v[0:3]
	v_mfma_f32_16x16x32_bf16 v[52:55], v[174:177], v[196:199], v[52:55]
	v_mfma_f32_16x16x32_bf16 v[48:51], v[188:191], v[196:199], v[48:51]
	v_mfma_f32_16x16x32_bf16 v[36:39], v[174:177], v[204:207], v[36:39]
	v_mfma_f32_16x16x32_bf16 v[32:35], v[188:191], v[204:207], v[32:35]
	v_mfma_f32_16x16x32_bf16 v[20:23], v[174:177], v[212:215], v[20:23]
	v_mfma_f32_16x16x32_bf16 v[16:19], v[188:191], v[212:215], v[16:19]
	v_mfma_f32_16x16x32_bf16 v[4:7], v[174:177], v[220:223], v[4:7]
	v_mfma_f32_16x16x32_bf16 v[0:3], v[188:191], v[220:223], v[0:3]
	s_barrier
	s_add_u32 s70, s70, 0x100
	s_addc_u32 s71, s71, 0
	s_add_u32 s46, s46, 0x100
	s_addc_u32 s47, s47, 0
	s_cmp_ge_i32 s72, s56
	s_mov_b32 s48, s72
	s_cbranch_scc0 .LBB0_617

; #define PG8_STAGE(bufoff, gbase, voff) do { _Pragma("unroll") for (int _i = 0; _i < 2; ++_i) \
;         __builtin_amdgcn_global_load_lds((const GAS unsigned*)((const char*)(gbase) + (voff)[_i]), (LAS unsigned*)(lds + (bufoff) + ldsw + _i * 8192), 16, 0, 0); } while (0)
; #define PG8_LDA(dst, b, h) do { _Pragma("unroll") for (int m = 0; m < 4; ++m) _Pragma("unroll") for (int k = 0; k < 2; ++k) dst[m][k] = *(const LAS bf16x8*)(lds + PG8_SA(b, h) + aoff + m * 2048 + k * 1024); } while (0)
; #define PG8_LDB(dst, b, h) do { _Pragma("unroll") for (int n = 0; n < 2; ++n) _Pragma("unroll") for (int k = 0; k < 2; ++k) dst[n][k] = *(const LAS bf16x8*)(lds + PG8_SB(b, h) + boff + n * 2048 + k * 1024); } while (0)
; #define PG8_MMA(ai, bj, At, Bt) do { __builtin_amdgcn_s_setprio(1); _Pragma("unroll") for (int m = 0; m < 4; ++m) _Pragma("unroll") for (int n = 0; n < 2; ++n) _Pragma("unroll") for (int k = 0; k < 2; ++k) \
;         acc[ai][bj][m][n] = __builtin_amdgcn_mfma_f32_16x16x32_bf16(Bt[n][k], At[m][k], acc[ai][bj][m][n], 0, 0, 0); __builtin_amdgcn_s_setprio(0); } while (0)
; #define PG8_WAIT_V(n) asm volatile("s_waitcnt vmcnt(" #n ")" ::: "memory")
; #define PG8_WAIT_L(n) asm volatile("s_waitcnt lgkmcnt(" #n ")" ::: "memory")
; #define PG8_BAR __builtin_amdgcn_s_barrier()
; #define PG8_SCHED __builtin_amdgcn_sched_barrier(0)
; template <class Epi, class Sched>
; __device__ __forceinline__ void gemm_phase(LAS unsigned char* lds, const Gemm g, const Sched& S, const Epi& E, const int wave_) {
;     ...
;             const bool last = (t == nt - 2);
;             const char* a1 = cA + (size_t)(t + 1) * kstep;
;             const char* a2 = last ? nA : cA + (size_t)(t + 2) * kstep; const char* b2 = last ? nB : cB + (size_t)(t + 2) * kstep;
;             const char* a3 = a2 + kstep; const char* b3 = b2 + kstep;
;             PG8_LDB(B0, 0, 0); PG8_LDB(B1, 0, 1); PG8_SCHED; PG8_LDA(At, 0, 0); PG8_STAGE(PG8_SA(1, 1), a1 + hstepA, voffA);
;             PG8_WAIT_V(8); PG8_WAIT_L(0); PG8_BAR; PG8_MMA(0, 0, At, B0); PG8_MMA(0, 1, At, B1); PG8_BAR; PG8_SCHED;
;             PG8_LDA(At, 0, 1); PG8_STAGE(PG8_SB(0, 0), b2, voffB); PG8_STAGE(PG8_SB(0, 1), b2 + hstepB, voffB); PG8_STAGE(PG8_SA(0, 0), a2, voffA);
;             PG8_WAIT_V(8); PG8_WAIT_L(0); PG8_BAR; PG8_MMA(1, 0, At, B0); PG8_MMA(1, 1, At, B1); PG8_BAR; PG8_SCHED;
.LBB0_696:
	ds_read_b128 v[154:157], v150
	ds_read_b128 v[158:161], v150 offset:1024
	ds_read_b128 v[162:165], v150 offset:2048
	ds_read_b128 v[166:169], v150 offset:3072
	ds_read_b128 v[170:173], v151
	ds_read_b128 v[174:177], v151 offset:1024
	ds_read_b128 v[178:181], v151 offset:2048
	ds_read_b128 v[188:191], v151 offset:3072
	s_add_i32 s81, s52, 2
	s_add_u32 s21, s50, 0xfffe0080
	s_addc_u32 s53, s51, -1
	s_cmp_eq_u32 s65, s52
	s_cselect_b32 s52, s76, s77
	s_cselect_b32 s55, s73, s53
	s_cselect_b32 s54, s74, s21
	s_cselect_b32 s53, s75, s78
	v_lshl_add_u64 v[182:183], s[50:51], 0, v[140:141]
	s_add_i32 m0, s58, 0xc000
	ds_read_b128 v[192:195], v152
	ds_read_b128 v[196:199], v152 offset:1024
	ds_read_b128 v[200:203], v152 offset:2048
	ds_read_b128 v[204:207], v152 offset:3072
	ds_read_b128 v[208:211], v152 offset:4096
	ds_read_b128 v[212:215], v152 offset:5120
	ds_read_b128 v[216:219], v152 offset:6144
	ds_read_b128 v[220:223], v152 offset:7168
	global_load_lds_dwordx4 v[182:183], off
	v_lshl_add_u64 v[182:183], s[50:51], 0, v[138:139]
	s_add_i32 m0, s58, 0xe000
	s_nop 0
	global_load_lds_dwordx4 v[182:183], off
	s_waitcnt vmcnt(8)
	s_waitcnt lgkmcnt(0)
	s_barrier
	s_waitcnt lgkmcnt(0)
	v_mfma_f32_16x16x32_bf16 v[124:127], v[154:157], v[192:195], v[124:127]
	v_mfma_f32_16x16x32_bf16 v[120:123], v[162:165], v[192:195], v[120:123]
	v_mfma_f32_16x16x32_bf16 v[108:111], v[154:157], v[200:203], v[108:111]
	v_mfma_f32_16x16x32_bf16 v[104:107], v[162:165], v[200:203], v[104:107]
	v_mfma_f32_16x16x32_bf16 v[92:95], v[154:157], v[208:211], v[92:95]
	v_mfma_f32_16x16x32_bf16 v[88:91], v[162:165], v[208:211], v[88:91]
	v_mfma_f32_16x16x32_bf16 v[76:79], v[154:157], v[216:219], v[76:79]
	v_mfma_f32_16x16x32_bf16 v[72:75], v[162:165], v[216:219], v[72:75]
	v_mfma_f32_16x16x32_bf16 v[124:127], v[158:161], v[196:199], v[124:127]
	v_mfma_f32_16x16x32_bf16 v[120:123], v[166:169], v[196:199], v[120:123]
	v_mfma_f32_16x16x32_bf16 v[108:111], v[158:161], v[204:207], v[108:111]
	v_mfma_f32_16x16x32_bf16 v[104:107], v[166:169], v[204:207], v[104:107]
	v_mfma_f32_16x16x32_bf16 v[92:95], v[158:161], v[212:215], v[92:95]
	v_mfma_f32_16x16x32_bf16 v[88:91], v[166:169], v[212:215], v[88:91]
	v_mfma_f32_16x16x32_bf16 v[76:79], v[158:161], v[220:223], v[76:79]
	v_mfma_f32_16x16x32_bf16 v[72:75], v[166:169], v[220:223], v[72:75]
	v_mfma_f32_16x16x32_bf16 v[116:119], v[170:173], v[192:195], v[116:119]
	v_mfma_f32_16x16x32_bf16 v[112:115], v[178:181], v[192:195], v[112:115]
	v_mfma_f32_16x16x32_bf16 v[100:103], v[170:173], v[200:203], v[100:103]
	v_mfma_f32_16x16x32_bf16 v[96:99], v[178:181], v[200:203], v[96:99]
	v_mfma_f32_16x16x32_bf16 v[84:87], v[170:173], v[208:211], v[84:87]
	v_mfma_f32_16x16x32_bf16 v[80:83], v[178:181], v[208:211], v[80:83]
	v_mfma_f32_16x16x32_bf16 v[68:71], v[170:173], v[216:219], v[68:71]
	v_mfma_f32_16x16x32_bf16 v[64:67], v[178:181], v[216:219], v[64:67]
	v_mfma_f32_16x16x32_bf16 v[116:119], v[174:177], v[196:199], v[116:119]
	v_mfma_f32_16x16x32_bf16 v[112:115], v[188:191], v[196:199], v[112:115]
	v_mfma_f32_16x16x32_bf16 v[100:103], v[174:177], v[204:207], v[100:103]
	v_mfma_f32_16x16x32_bf16 v[96:99], v[188:191], v[204:207], v[96:99]
	v_mfma_f32_16x16x32_bf16 v[84:87], v[174:177], v[212:215], v[84:87]
	v_mfma_f32_16x16x32_bf16 v[80:83], v[188:191], v[212:215], v[80:83]
	v_mfma_f32_16x16x32_bf16 v[68:71], v[174:177], v[220:223], v[68:71]
	v_mfma_f32_16x16x32_bf16 v[64:67], v[188:191], v[220:223], v[64:67]
	s_barrier
	s_add_i32 s21, s69, s83
	v_lshl_add_u64 v[182:183], s[52:53], 0, v[132:133]
	s_mov_b32 m0, s21
	ds_read_b128 v[192:195], v152 offset:16384
	ds_read_b128 v[196:199], v152 offset:17408
	ds_read_b128 v[200:203], v152 offset:18432
	ds_read_b128 v[204:207], v152 offset:19456
	ds_read_b128 v[208:211], v152 offset:20480
	ds_read_b128 v[212:215], v152 offset:21504
	ds_read_b128 v[216:219], v152 offset:22528
	ds_read_b128 v[220:223], v152 offset:23552
	global_load_lds_dwordx4 v[182:183], off
	s_add_i32 m0, s21, 0x2000
	s_add_u32 s90, s52, 0x20000
	v_lshl_add_u64 v[224:225], s[52:53], 0, v[128:129]
	s_addc_u32 s91, s53, 0
	s_add_i32 s21, s70, s83
	global_load_lds_dwordx4 v[224:225], off
	v_lshl_add_u64 v[226:227], s[90:91], 0, v[132:133]
	s_mov_b32 m0, s21
	v_lshl_add_u64 v[228:229], s[54:55], 0, v[130:131]
	global_load_lds_dwordx4 v[226:227], off
	v_lshl_add_u64 v[226:227], s[90:91], 0, v[128:129]
	s_add_i32 m0, s21, 0x2000
	s_nop 0
	global_load_lds_dwordx4 v[226:227], off
	v_lshl_add_u64 v[226:227], s[54:55], 0, v[134:135]
	s_mov_b32 m0, s58
	s_nop 0
	global_load_lds_dwordx4 v[226:227], off
	s_mov_b32 m0, s59
	s_nop 0
	global_load_lds_dwordx4 v[228:229], off
	s_waitcnt vmcnt(8)
	s_waitcnt lgkmcnt(0)
	s_barrier
; #define PG8_STAGE(bufoff, gbase, voff) do { _Pragma("unroll") for (int _i = 0; _i < 2; ++_i) \
;         __builtin_amdgcn_global_load_lds((const GAS unsigned*)((const char*)(gbase) + (voff)[_i]), (LAS unsigned*)(lds + (bufoff) + ldsw + _i * 8192), 16, 0, 0); } while (0)
; #define PG8_LDA(dst, b, h) do { _Pragma("unroll") for (int m = 0; m < 4; ++m) _Pragma("unroll") for (int k = 0; k < 2; ++k) dst[m][k] = *(const LAS bf16x8*)(lds + PG8_SA(b, h) + aoff + m * 2048 + k * 1024); } while (0)
; #define PG8_LDB(dst, b, h) do { _Pragma("unroll") for (int n = 0; n < 2; ++n) _Pragma("unroll") for (int k = 0; k < 2; ++k) dst[n][k] = *(const LAS bf16x8*)(lds + PG8_SB(b, h) + boff + n * 2048 + k * 1024); } while (0)
; #define PG8_MMA(ai, bj, At, Bt) do { __builtin_amdgcn_s_setprio(1); _Pragma("unroll") for (int m = 0; m < 4; ++m) _Pragma("unroll") for (int n = 0; n < 2; ++n) _Pragma("unroll") for (int k = 0; k < 2; ++k) \
;         acc[ai][bj][m][n] = __builtin_amdgcn_mfma_f32_16x16x32_bf16(Bt[n][k], At[m][k], acc[ai][bj][m][n], 0, 0, 0); __builtin_amdgcn_s_setprio(0); } while (0)
; #define PG8_WAIT_V(n) asm volatile("s_waitcnt vmcnt(" #n ")" ::: "memory")
; #define PG8_WAIT_L(n) asm volatile("s_waitcnt lgkmcnt(" #n ")" ::: "memory")
; #define PG8_BAR __builtin_amdgcn_s_barrier()
; #define PG8_SCHED __builtin_amdgcn_sched_barrier(0)
; template <class Epi, class Sched>
; __device__ __forceinline__ void gemm_phase(LAS unsigned char* lds, const Gemm g, const Sched& S, const Epi& E, const int wave_) {
;     ...
;             PG8_WAIT_V(8); PG8_WAIT_L(0); PG8_BAR; PG8_MMA(1, 0, At, B0); PG8_MMA(1, 1, At, B1); PG8_BAR; PG8_SCHED;
;             PG8_LDB(B0, 1, 0); PG8_LDB(B1, 1, 1); PG8_SCHED; PG8_LDA(At, 1, 0); PG8_STAGE(PG8_SA(0, 1), a2 + hstepA, voffA);
;             PG8_WAIT_V(8); PG8_WAIT_L(0); PG8_BAR; PG8_MMA(0, 0, At, B0); PG8_MMA(0, 1, At, B1); PG8_BAR; PG8_SCHED;
	s_waitcnt lgkmcnt(0)
	v_mfma_f32_16x16x32_bf16 v[60:63], v[154:157], v[192:195], v[60:63]
	v_mfma_f32_16x16x32_bf16 v[56:59], v[162:165], v[192:195], v[56:59]
	v_mfma_f32_16x16x32_bf16 v[44:47], v[154:157], v[200:203], v[44:47]
	v_mfma_f32_16x16x32_bf16 v[40:43], v[162:165], v[200:203], v[40:43]
	v_mfma_f32_16x16x32_bf16 v[28:31], v[154:157], v[208:211], v[28:31]
	v_mfma_f32_16x16x32_bf16 v[24:27], v[162:165], v[208:211], v[24:27]
	v_mfma_f32_16x16x32_bf16 v[12:15], v[154:157], v[216:219], v[12:15]
	v_mfma_f32_16x16x32_bf16 v[8:11], v[162:165], v[216:219], v[8:11]
	v_mfma_f32_16x16x32_bf16 v[60:63], v[158:161], v[196:199], v[60:63]
	v_mfma_f32_16x16x32_bf16 v[56:59], v[166:169], v[196:199], v[56:59]
	v_mfma_f32_16x16x32_bf16 v[44:47], v[158:161], v[204:207], v[44:47]
	v_mfma_f32_16x16x32_bf16 v[40:43], v[166:169], v[204:207], v[40:43]
	v_mfma_f32_16x16x32_bf16 v[28:31], v[158:161], v[212:215], v[28:31]
	v_mfma_f32_16x16x32_bf16 v[24:27], v[166:169], v[212:215], v[24:27]
	v_mfma_f32_16x16x32_bf16 v[12:15], v[158:161], v[220:223], v[12:15]
	v_mfma_f32_16x16x32_bf16 v[8:11], v[166:169], v[220:223], v[8:11]
	v_mfma_f32_16x16x32_bf16 v[52:55], v[170:173], v[192:195], v[52:55]
	v_mfma_f32_16x16x32_bf16 v[48:51], v[178:181], v[192:195], v[48:51]
	v_mfma_f32_16x16x32_bf16 v[36:39], v[170:173], v[200:203], v[36:39]
	v_mfma_f32_16x16x32_bf16 v[32:35], v[178:181], v[200:203], v[32:35]
	v_mfma_f32_16x16x32_bf16 v[20:23], v[170:173], v[208:211], v[20:23]
	v_mfma_f32_16x16x32_bf16 v[16:19], v[178:181], v[208:211], v[16:19]
	v_mfma_f32_16x16x32_bf16 v[4:7], v[170:173], v[216:219], v[4:7]
	v_mfma_f32_16x16x32_bf16 v[0:3], v[178:181], v[216:219], v[0:3]
	v_mfma_f32_16x16x32_bf16 v[52:55], v[174:177], v[196:199], v[52:55]
	v_mfma_f32_16x16x32_bf16 v[48:51], v[188:191], v[196:199], v[48:51]
	v_mfma_f32_16x16x32_bf16 v[36:39], v[174:177], v[204:207], v[36:39]
	v_mfma_f32_16x16x32_bf16 v[32:35], v[188:191], v[204:207], v[32:35]
	v_mfma_f32_16x16x32_bf16 v[20:23], v[174:177], v[212:215], v[20:23]
	v_mfma_f32_16x16x32_bf16 v[16:19], v[188:191], v[212:215], v[16:19]
	v_mfma_f32_16x16x32_bf16 v[4:7], v[174:177], v[220:223], v[4:7]
	v_mfma_f32_16x16x32_bf16 v[0:3], v[188:191], v[220:223], v[0:3]
	s_barrier
	s_add_i32 s21, 0, 0x18000
	v_add_u32_e32 v153, s21, v147
	s_add_i32 s89, 0, 0x1c000
	ds_read_b128 v[154:157], v153
	ds_read_b128 v[158:161], v153 offset:1024
	ds_read_b128 v[162:165], v153 offset:2048
	ds_read_b128 v[166:169], v153 offset:3072
	v_add_u32_e32 v153, s89, v147
	ds_read_b128 v[170:173], v153
	ds_read_b128 v[174:177], v153 offset:1024
	ds_read_b128 v[178:181], v153 offset:2048
	ds_read_b128 v[188:191], v153 offset:3072
	s_add_u32 s54, s54, 0x20000
	s_addc_u32 s55, s55, 0
	s_mov_b32 m0, s60
	v_lshl_add_u64 v[230:231], s[54:55], 0, v[134:135]
	ds_read_b128 v[192:195], v152 offset:32768
	ds_read_b128 v[196:199], v152 offset:33792
	ds_read_b128 v[200:203], v152 offset:34816
	ds_read_b128 v[204:207], v152 offset:35840
	ds_read_b128 v[208:211], v152 offset:36864
	ds_read_b128 v[212:215], v152 offset:37888
	ds_read_b128 v[216:219], v152 offset:38912
	ds_read_b128 v[220:223], v152 offset:39936
	global_load_lds_dwordx4 v[230:231], off
	v_lshl_add_u64 v[230:231], s[54:55], 0, v[130:131]
	s_mov_b32 m0, s61
	s_nop 0
	global_load_lds_dwordx4 v[230:231], off
	s_waitcnt vmcnt(8)
	s_waitcnt lgkmcnt(0)
	s_barrier
	s_waitcnt lgkmcnt(0)
	v_mfma_f32_16x16x32_bf16 v[124:127], v[154:157], v[192:195], v[124:127]
	v_mfma_f32_16x16x32_bf16 v[120:123], v[162:165], v[192:195], v[120:123]
	v_mfma_f32_16x16x32_bf16 v[108:111], v[154:157], v[200:203], v[108:111]
	v_mfma_f32_16x16x32_bf16 v[104:107], v[162:165], v[200:203], v[104:107]
	v_mfma_f32_16x16x32_bf16 v[92:95], v[154:157], v[208:211], v[92:95]
	v_mfma_f32_16x16x32_bf16 v[88:91], v[162:165], v[208:211], v[88:91]
	v_mfma_f32_16x16x32_bf16 v[76:79], v[154:157], v[216:219], v[76:79]
	v_mfma_f32_16x16x32_bf16 v[72:75], v[162:165], v[216:219], v[72:75]
	v_mfma_f32_16x16x32_bf16 v[124:127], v[158:161], v[196:199], v[124:127]
	v_mfma_f32_16x16x32_bf16 v[120:123], v[166:169], v[196:199], v[120:123]
	v_mfma_f32_16x16x32_bf16 v[108:111], v[158:161], v[204:207], v[108:111]
	v_mfma_f32_16x16x32_bf16 v[104:107], v[166:169], v[204:207], v[104:107]
	v_mfma_f32_16x16x32_bf16 v[92:95], v[158:161], v[212:215], v[92:95]
	v_mfma_f32_16x16x32_bf16 v[88:91], v[166:169], v[212:215], v[88:91]
	v_mfma_f32_16x16x32_bf16 v[76:79], v[158:161], v[220:223], v[76:79]
	v_mfma_f32_16x16x32_bf16 v[72:75], v[166:169], v[220:223], v[72:75]
	v_mfma_f32_16x16x32_bf16 v[116:119], v[170:173], v[192:195], v[116:119]
	v_mfma_f32_16x16x32_bf16 v[112:115], v[178:181], v[192:195], v[112:115]
	v_mfma_f32_16x16x32_bf16 v[100:103], v[170:173], v[200:203], v[100:103]
	v_mfma_f32_16x16x32_bf16 v[96:99], v[178:181], v[200:203], v[96:99]
	v_mfma_f32_16x16x32_bf16 v[84:87], v[170:173], v[208:211], v[84:87]
	v_mfma_f32_16x16x32_bf16 v[80:83], v[178:181], v[208:211], v[80:83]
	v_mfma_f32_16x16x32_bf16 v[68:71], v[170:173], v[216:219], v[68:71]
	v_mfma_f32_16x16x32_bf16 v[64:67], v[178:181], v[216:219], v[64:67]
	v_mfma_f32_16x16x32_bf16 v[116:119], v[174:177], v[196:199], v[116:119]
	v_mfma_f32_16x16x32_bf16 v[112:115], v[188:191], v[196:199], v[112:115]
	v_mfma_f32_16x16x32_bf16 v[100:103], v[174:177], v[204:207], v[100:103]
	v_mfma_f32_16x16x32_bf16 v[96:99], v[188:191], v[204:207], v[96:99]
	v_mfma_f32_16x16x32_bf16 v[84:87], v[174:177], v[212:215], v[84:87]
	v_mfma_f32_16x16x32_bf16 v[80:83], v[188:191], v[212:215], v[80:83]
	v_mfma_f32_16x16x32_bf16 v[68:71], v[174:177], v[220:223], v[68:71]
	v_mfma_f32_16x16x32_bf16 v[64:67], v[188:191], v[220:223], v[64:67]
	s_barrier
; #define PG8_STAGE(bufoff, gbase, voff) do { _Pragma("unroll") for (int _i = 0; _i < 2; ++_i) \
;         __builtin_amdgcn_global_load_lds((const GAS unsigned*)((const char*)(gbase) + (voff)[_i]), (LAS unsigned*)(lds + (bufoff) + ldsw + _i * 8192), 16, 0, 0); } while (0)
; #define PG8_LDA(dst, b, h) do { _Pragma("unroll") for (int m = 0; m < 4; ++m) _Pragma("unroll") for (int k = 0; k < 2; ++k) dst[m][k] = *(const LAS bf16x8*)(lds + PG8_SA(b, h) + aoff + m * 2048 + k * 1024); } while (0)
; #define PG8_MMA(ai, bj, At, Bt) do { __builtin_amdgcn_s_setprio(1); _Pragma("unroll") for (int m = 0; m < 4; ++m) _Pragma("unroll") for (int n = 0; n < 2; ++n) _Pragma("unroll") for (int k = 0; k < 2; ++k) \
;         acc[ai][bj][m][n] = __builtin_amdgcn_mfma_f32_16x16x32_bf16(Bt[n][k], At[m][k], acc[ai][bj][m][n], 0, 0, 0); __builtin_amdgcn_s_setprio(0); } while (0)
; #define PG8_WAIT_V(n) asm volatile("s_waitcnt vmcnt(" #n ")" ::: "memory")
; #define PG8_WAIT_L(n) asm volatile("s_waitcnt lgkmcnt(" #n ")" ::: "memory")
; #define PG8_BAR __builtin_amdgcn_s_barrier()
; #define PG8_SCHED __builtin_amdgcn_sched_barrier(0)
; template <class Epi, class Sched>
; __device__ __forceinline__ void gemm_phase(LAS unsigned char* lds, const Gemm g, const Sched& S, const Epi& E, const int wave_) {
;     ...
;         for (int t = 0; t < nt; t += 2) {
;     ...
;             PG8_LDA(At, 1, 1); PG8_STAGE(PG8_SB(1, 0), b3, voffB); PG8_STAGE(PG8_SB(1, 1), b3 + hstepB, voffB); PG8_STAGE(PG8_SA(1, 0), a3, voffA);
;             PG8_WAIT_V(8); PG8_WAIT_L(0); PG8_BAR; PG8_MMA(1, 0, At, B0); PG8_MMA(1, 1, At, B1); PG8_BAR; PG8_SCHED;
	s_add_i32 s21, s21, s83
	v_lshl_add_u64 v[182:183], v[182:183], 0, s[38:39]
	s_mov_b32 m0, s21
	ds_read_b128 v[192:195], v152 offset:49152
	ds_read_b128 v[196:199], v152 offset:50176
	ds_read_b128 v[200:203], v152 offset:51200
	ds_read_b128 v[204:207], v152 offset:52224
	ds_read_b128 v[208:211], v152 offset:53248
	ds_read_b128 v[212:215], v152 offset:54272
	ds_read_b128 v[216:219], v152 offset:55296
	ds_read_b128 v[220:223], v152 offset:56320
	global_load_lds_dwordx4 v[182:183], off
	s_add_i32 m0, s21, 0x2000
	s_add_u32 s52, s52, 0x20080
	v_lshl_add_u64 v[182:183], v[224:225], 0, s[38:39]
	s_addc_u32 s53, s53, 0
	s_add_i32 s21, s89, s83
	global_load_lds_dwordx4 v[182:183], off
	v_lshl_add_u64 v[182:183], s[52:53], 0, v[132:133]
	s_mov_b32 m0, s21
	s_nop 0
	global_load_lds_dwordx4 v[182:183], off
	v_lshl_add_u64 v[182:183], s[52:53], 0, v[128:129]
	s_add_i32 m0, s21, 0x2000
	s_nop 0
	global_load_lds_dwordx4 v[182:183], off
	v_lshl_add_u64 v[182:183], v[226:227], 0, s[38:39]
	s_mov_b32 m0, s63
	s_nop 0
	global_load_lds_dwordx4 v[182:183], off
	v_lshl_add_u64 v[182:183], v[228:229], 0, s[38:39]
	s_mov_b32 m0, s64
	s_nop 0
	global_load_lds_dwordx4 v[182:183], off
	s_waitcnt vmcnt(8)
	s_waitcnt lgkmcnt(0)
	s_barrier
	s_waitcnt lgkmcnt(0)
	v_mfma_f32_16x16x32_bf16 v[60:63], v[154:157], v[192:195], v[60:63]
	v_mfma_f32_16x16x32_bf16 v[56:59], v[162:165], v[192:195], v[56:59]
	v_mfma_f32_16x16x32_bf16 v[44:47], v[154:157], v[200:203], v[44:47]
	v_mfma_f32_16x16x32_bf16 v[40:43], v[162:165], v[200:203], v[40:43]
	v_mfma_f32_16x16x32_bf16 v[28:31], v[154:157], v[208:211], v[28:31]
	v_mfma_f32_16x16x32_bf16 v[24:27], v[162:165], v[208:211], v[24:27]
	v_mfma_f32_16x16x32_bf16 v[12:15], v[154:157], v[216:219], v[12:15]
	v_mfma_f32_16x16x32_bf16 v[8:11], v[162:165], v[216:219], v[8:11]
	v_mfma_f32_16x16x32_bf16 v[60:63], v[158:161], v[196:199], v[60:63]
	v_mfma_f32_16x16x32_bf16 v[56:59], v[166:169], v[196:199], v[56:59]
	v_mfma_f32_16x16x32_bf16 v[44:47], v[158:161], v[204:207], v[44:47]
	v_mfma_f32_16x16x32_bf16 v[40:43], v[166:169], v[204:207], v[40:43]
	v_mfma_f32_16x16x32_bf16 v[28:31], v[158:161], v[212:215], v[28:31]
	v_mfma_f32_16x16x32_bf16 v[24:27], v[166:169], v[212:215], v[24:27]
	v_mfma_f32_16x16x32_bf16 v[12:15], v[158:161], v[220:223], v[12:15]
	v_mfma_f32_16x16x32_bf16 v[8:11], v[166:169], v[220:223], v[8:11]
	v_mfma_f32_16x16x32_bf16 v[52:55], v[170:173], v[192:195], v[52:55]
	v_mfma_f32_16x16x32_bf16 v[48:51], v[178:181], v[192:195], v[48:51]
	v_mfma_f32_16x16x32_bf16 v[36:39], v[170:173], v[200:203], v[36:39]
	v_mfma_f32_16x16x32_bf16 v[32:35], v[178:181], v[200:203], v[32:35]
	v_mfma_f32_16x16x32_bf16 v[20:23], v[170:173], v[208:211], v[20:23]
	v_mfma_f32_16x16x32_bf16 v[16:19], v[178:181], v[208:211], v[16:19]
	v_mfma_f32_16x16x32_bf16 v[4:7], v[170:173], v[216:219], v[4:7]
	v_mfma_f32_16x16x32_bf16 v[0:3], v[178:181], v[216:219], v[0:3]
	v_mfma_f32_16x16x32_bf16 v[52:55], v[174:177], v[196:199], v[52:55]
	v_mfma_f32_16x16x32_bf16 v[48:51], v[188:191], v[196:199], v[48:51]
	v_mfma_f32_16x16x32_bf16 v[36:39], v[174:177], v[204:207], v[36:39]
	v_mfma_f32_16x16x32_bf16 v[32:35], v[188:191], v[204:207], v[32:35]
	v_mfma_f32_16x16x32_bf16 v[20:23], v[174:177], v[212:215], v[20:23]
	v_mfma_f32_16x16x32_bf16 v[16:19], v[188:191], v[212:215], v[16:19]
	v_mfma_f32_16x16x32_bf16 v[4:7], v[174:177], v[220:223], v[4:7]
	v_mfma_f32_16x16x32_bf16 v[0:3], v[188:191], v[220:223], v[0:3]
	s_barrier
	s_add_u32 s77, s77, 0x100
	s_addc_u32 s78, s78, 0
	s_add_u32 s50, s50, 0x100
	s_addc_u32 s51, s51, 0
	s_cmp_ge_i32 s81, s62
	s_mov_b32 s52, s81
	s_cbranch_scc0 .LBB0_696

; #define PG8_STAGE(bufoff, gbase, voff) do { _Pragma("unroll") for (int _i = 0; _i < 2; ++_i) \
;         __builtin_amdgcn_global_load_lds((const GAS unsigned*)((const char*)(gbase) + (voff)[_i]), (LAS unsigned*)(lds + (bufoff) + ldsw + _i * 8192), 16, 0, 0); } while (0)
; #define PG8_LDA(dst, b, h) do { _Pragma("unroll") for (int m = 0; m < 4; ++m) _Pragma("unroll") for (int k = 0; k < 2; ++k) dst[m][k] = *(const LAS bf16x8*)(lds + PG8_SA(b, h) + aoff + m * 2048 + k * 1024); } while (0)
; #define PG8_LDB(dst, b, h) do { _Pragma("unroll") for (int n = 0; n < 2; ++n) _Pragma("unroll") for (int k = 0; k < 2; ++k) dst[n][k] = *(const LAS bf16x8*)(lds + PG8_SB(b, h) + boff + n * 2048 + k * 1024); } while (0)
; #define PG8_MMA(ai, bj, At, Bt) do { __builtin_amdgcn_s_setprio(1); _Pragma("unroll") for (int m = 0; m < 4; ++m) _Pragma("unroll") for (int n = 0; n < 2; ++n) _Pragma("unroll") for (int k = 0; k < 2; ++k) \
;         acc[ai][bj][m][n] = __builtin_amdgcn_mfma_f32_16x16x32_bf16(Bt[n][k], At[m][k], acc[ai][bj][m][n], 0, 0, 0); __builtin_amdgcn_s_setprio(0); } while (0)
; #define PG8_WAIT_V(n) asm volatile("s_waitcnt vmcnt(" #n ")" ::: "memory")
; #define PG8_WAIT_L(n) asm volatile("s_waitcnt lgkmcnt(" #n ")" ::: "memory")
; #define PG8_BAR __builtin_amdgcn_s_barrier()
; #define PG8_SCHED __builtin_amdgcn_sched_barrier(0)
; template <class Epi, class Sched>
; __device__ __forceinline__ void gemm_phase(LAS unsigned char* lds, const Gemm g, const Sched& S, const Epi& E, const int wave_) {
;     ...
;             const bool last = (t == nt - 2);
;             const char* a1 = cA + (size_t)(t + 1) * kstep;
;             const char* a2 = last ? nA : cA + (size_t)(t + 2) * kstep; const char* b2 = last ? nB : cB + (size_t)(t + 2) * kstep;
;             const char* a3 = a2 + kstep; const char* b3 = b2 + kstep;
;             PG8_LDB(B0, 0, 0); PG8_LDB(B1, 0, 1); PG8_SCHED; PG8_LDA(At, 0, 0); PG8_STAGE(PG8_SA(1, 1), a1 + hstepA, voffA);
;             PG8_WAIT_V(8); PG8_WAIT_L(0); PG8_BAR; PG8_MMA(0, 0, At, B0); PG8_MMA(0, 1, At, B1); PG8_BAR; PG8_SCHED;
;             PG8_LDA(At, 0, 1); PG8_STAGE(PG8_SB(0, 0), b2, voffB); PG8_STAGE(PG8_SB(0, 1), b2 + hstepB, voffB); PG8_STAGE(PG8_SA(0, 0), a2, voffA);
;             PG8_WAIT_V(8); PG8_WAIT_L(0); PG8_BAR; PG8_MMA(1, 0, At, B0); PG8_MMA(1, 1, At, B1); PG8_BAR; PG8_SCHED;
.LBB0_715:
	ds_read_b128 v[130:133], v158
	ds_read_b128 v[134:137], v158 offset:1024
	ds_read_b128 v[162:165], v158 offset:2048
	ds_read_b128 v[166:169], v158 offset:3072
	ds_read_b128 v[170:173], v159
	ds_read_b128 v[174:177], v159 offset:1024
	ds_read_b128 v[178:181], v159 offset:2048
	ds_read_b128 v[188:191], v159 offset:3072
	s_add_i32 s91, s58, 2
	s_add_u32 s21, s10, 0xffff0080
	s_addc_u32 s59, s11, -1
	s_cmp_eq_u32 s71, s58
	s_cselect_b32 s58, s81, s89
	s_cselect_b32 s61, s9, s59
	s_cselect_b32 s60, s47, s21
	s_cselect_b32 s59, s49, s90
	v_lshl_add_u64 v[182:183], s[10:11], 0, v[150:151]
	s_add_i32 m0, s62, 0xc000
	ds_read_b128 v[192:195], v160
	ds_read_b128 v[196:199], v160 offset:1024
	ds_read_b128 v[200:203], v160 offset:2048
	ds_read_b128 v[204:207], v160 offset:3072
	ds_read_b128 v[208:211], v160 offset:4096
	ds_read_b128 v[212:215], v160 offset:5120
	ds_read_b128 v[216:219], v160 offset:6144
	ds_read_b128 v[220:223], v160 offset:7168
	global_load_lds_dwordx4 v[182:183], off
	v_lshl_add_u64 v[182:183], s[10:11], 0, v[148:149]
	s_add_i32 m0, s62, 0xe000
	s_nop 0
	global_load_lds_dwordx4 v[182:183], off
	s_waitcnt vmcnt(8)
	s_waitcnt lgkmcnt(0)
	s_barrier
	s_waitcnt lgkmcnt(0)
	v_mfma_f32_16x16x32_bf16 v[126:129], v[130:133], v[192:195], v[126:129]
	v_mfma_f32_16x16x32_bf16 v[122:125], v[162:165], v[192:195], v[122:125]
	v_mfma_f32_16x16x32_bf16 v[118:121], v[130:133], v[200:203], v[118:121]
	v_mfma_f32_16x16x32_bf16 v[110:113], v[162:165], v[200:203], v[110:113]
	v_mfma_f32_16x16x32_bf16 v[102:105], v[130:133], v[208:211], v[102:105]
	v_mfma_f32_16x16x32_bf16 v[94:97], v[162:165], v[208:211], v[94:97]
	v_mfma_f32_16x16x32_bf16 v[86:89], v[130:133], v[216:219], v[86:89]
	v_mfma_f32_16x16x32_bf16 v[78:81], v[162:165], v[216:219], v[78:81]
	v_mfma_f32_16x16x32_bf16 v[126:129], v[134:137], v[196:199], v[126:129]
	v_mfma_f32_16x16x32_bf16 v[122:125], v[166:169], v[196:199], v[122:125]
	v_mfma_f32_16x16x32_bf16 v[118:121], v[134:137], v[204:207], v[118:121]
	v_mfma_f32_16x16x32_bf16 v[110:113], v[166:169], v[204:207], v[110:113]
	v_mfma_f32_16x16x32_bf16 v[102:105], v[134:137], v[212:215], v[102:105]
	v_mfma_f32_16x16x32_bf16 v[94:97], v[166:169], v[212:215], v[94:97]
	v_mfma_f32_16x16x32_bf16 v[86:89], v[134:137], v[220:223], v[86:89]
	v_mfma_f32_16x16x32_bf16 v[78:81], v[166:169], v[220:223], v[78:81]
	v_mfma_f32_16x16x32_bf16 v[114:117], v[170:173], v[192:195], v[114:117]
	v_mfma_f32_16x16x32_bf16 v[106:109], v[178:181], v[192:195], v[106:109]
	v_mfma_f32_16x16x32_bf16 v[98:101], v[170:173], v[200:203], v[98:101]
	v_mfma_f32_16x16x32_bf16 v[90:93], v[178:181], v[200:203], v[90:93]
	v_mfma_f32_16x16x32_bf16 v[82:85], v[170:173], v[208:211], v[82:85]
	v_mfma_f32_16x16x32_bf16 v[74:77], v[178:181], v[208:211], v[74:77]
	v_mfma_f32_16x16x32_bf16 v[70:73], v[170:173], v[216:219], v[70:73]
	v_mfma_f32_16x16x32_bf16 v[66:69], v[178:181], v[216:219], v[66:69]
	v_mfma_f32_16x16x32_bf16 v[114:117], v[174:177], v[196:199], v[114:117]
	v_mfma_f32_16x16x32_bf16 v[106:109], v[188:191], v[196:199], v[106:109]
	v_mfma_f32_16x16x32_bf16 v[98:101], v[174:177], v[204:207], v[98:101]
	v_mfma_f32_16x16x32_bf16 v[90:93], v[188:191], v[204:207], v[90:93]
	v_mfma_f32_16x16x32_bf16 v[82:85], v[174:177], v[212:215], v[82:85]
	v_mfma_f32_16x16x32_bf16 v[74:77], v[188:191], v[212:215], v[74:77]
	v_mfma_f32_16x16x32_bf16 v[70:73], v[174:177], v[220:223], v[70:73]
	v_mfma_f32_16x16x32_bf16 v[66:69], v[188:191], v[220:223], v[66:69]
	s_barrier
	s_add_i32 s21, s75, s83
	v_lshl_add_u64 v[182:183], s[58:59], 0, v[138:139]
	s_mov_b32 m0, s21
	ds_read_b128 v[192:195], v160 offset:16384
	ds_read_b128 v[196:199], v160 offset:17408
	ds_read_b128 v[200:203], v160 offset:18432
	ds_read_b128 v[204:207], v160 offset:19456
	ds_read_b128 v[208:211], v160 offset:20480
	ds_read_b128 v[212:215], v160 offset:21504
	ds_read_b128 v[216:219], v160 offset:22528
	ds_read_b128 v[220:223], v160 offset:23552
	global_load_lds_dwordx4 v[182:183], off
	s_add_i32 m0, s21, 0x2000
	s_add_u32 s92, s58, 0x10000
	v_lshl_add_u64 v[224:225], s[58:59], 0, v[140:141]
	s_addc_u32 s93, s59, 0
	s_add_i32 s21, s76, s83
	global_load_lds_dwordx4 v[224:225], off
	v_lshl_add_u64 v[226:227], s[92:93], 0, v[138:139]
	s_mov_b32 m0, s21
	v_lshl_add_u64 v[228:229], s[60:61], 0, v[140:141]
	global_load_lds_dwordx4 v[226:227], off
	v_lshl_add_u64 v[226:227], s[92:93], 0, v[140:141]
	s_add_i32 m0, s21, 0x2000
	s_nop 0
	global_load_lds_dwordx4 v[226:227], off
	v_lshl_add_u64 v[226:227], s[60:61], 0, v[138:139]
	s_mov_b32 m0, s62
	s_nop 0
	global_load_lds_dwordx4 v[226:227], off
	s_mov_b32 m0, s63
	s_nop 0
	global_load_lds_dwordx4 v[228:229], off
	s_waitcnt vmcnt(8)
	s_waitcnt lgkmcnt(0)
	s_barrier
; #define PG8_STAGE(bufoff, gbase, voff) do { _Pragma("unroll") for (int _i = 0; _i < 2; ++_i) \
;         __builtin_amdgcn_global_load_lds((const GAS unsigned*)((const char*)(gbase) + (voff)[_i]), (LAS unsigned*)(lds + (bufoff) + ldsw + _i * 8192), 16, 0, 0); } while (0)
; #define PG8_LDA(dst, b, h) do { _Pragma("unroll") for (int m = 0; m < 4; ++m) _Pragma("unroll") for (int k = 0; k < 2; ++k) dst[m][k] = *(const LAS bf16x8*)(lds + PG8_SA(b, h) + aoff + m * 2048 + k * 1024); } while (0)
; #define PG8_LDB(dst, b, h) do { _Pragma("unroll") for (int n = 0; n < 2; ++n) _Pragma("unroll") for (int k = 0; k < 2; ++k) dst[n][k] = *(const LAS bf16x8*)(lds + PG8_SB(b, h) + boff + n * 2048 + k * 1024); } while (0)
; #define PG8_MMA(ai, bj, At, Bt) do { __builtin_amdgcn_s_setprio(1); _Pragma("unroll") for (int m = 0; m < 4; ++m) _Pragma("unroll") for (int n = 0; n < 2; ++n) _Pragma("unroll") for (int k = 0; k < 2; ++k) \
;         acc[ai][bj][m][n] = __builtin_amdgcn_mfma_f32_16x16x32_bf16(Bt[n][k], At[m][k], acc[ai][bj][m][n], 0, 0, 0); __builtin_amdgcn_s_setprio(0); } while (0)
; #define PG8_WAIT_V(n) asm volatile("s_waitcnt vmcnt(" #n ")" ::: "memory")
; #define PG8_WAIT_L(n) asm volatile("s_waitcnt lgkmcnt(" #n ")" ::: "memory")
; #define PG8_BAR __builtin_amdgcn_s_barrier()
; #define PG8_SCHED __builtin_amdgcn_sched_barrier(0)
; template <class Epi, class Sched>
; __device__ __forceinline__ void gemm_phase(LAS unsigned char* lds, const Gemm g, const Sched& S, const Epi& E, const int wave_) {
;     ...
;             PG8_WAIT_V(8); PG8_WAIT_L(0); PG8_BAR; PG8_MMA(1, 0, At, B0); PG8_MMA(1, 1, At, B1); PG8_BAR; PG8_SCHED;
;             PG8_LDB(B0, 1, 0); PG8_LDB(B1, 1, 1); PG8_SCHED; PG8_LDA(At, 1, 0); PG8_STAGE(PG8_SA(0, 1), a2 + hstepA, voffA);
;             PG8_WAIT_V(8); PG8_WAIT_L(0); PG8_BAR; PG8_MMA(0, 0, At, B0); PG8_MMA(0, 1, At, B1); PG8_BAR; PG8_SCHED;
	s_waitcnt lgkmcnt(0)
	v_mfma_f32_16x16x32_bf16 v[62:65], v[130:133], v[192:195], v[62:65]
	v_mfma_f32_16x16x32_bf16 v[58:61], v[162:165], v[192:195], v[58:61]
	v_mfma_f32_16x16x32_bf16 v[54:57], v[130:133], v[200:203], v[54:57]
	v_mfma_f32_16x16x32_bf16 v[46:49], v[162:165], v[200:203], v[46:49]
	v_mfma_f32_16x16x32_bf16 v[38:41], v[130:133], v[208:211], v[38:41]
	v_mfma_f32_16x16x32_bf16 v[30:33], v[162:165], v[208:211], v[30:33]
	v_mfma_f32_16x16x32_bf16 v[22:25], v[130:133], v[216:219], v[22:25]
	v_mfma_f32_16x16x32_bf16 v[14:17], v[162:165], v[216:219], v[14:17]
	v_mfma_f32_16x16x32_bf16 v[62:65], v[134:137], v[196:199], v[62:65]
	v_mfma_f32_16x16x32_bf16 v[58:61], v[166:169], v[196:199], v[58:61]
	v_mfma_f32_16x16x32_bf16 v[54:57], v[134:137], v[204:207], v[54:57]
	v_mfma_f32_16x16x32_bf16 v[46:49], v[166:169], v[204:207], v[46:49]
	v_mfma_f32_16x16x32_bf16 v[38:41], v[134:137], v[212:215], v[38:41]
	v_mfma_f32_16x16x32_bf16 v[30:33], v[166:169], v[212:215], v[30:33]
	v_mfma_f32_16x16x32_bf16 v[22:25], v[134:137], v[220:223], v[22:25]
	v_mfma_f32_16x16x32_bf16 v[14:17], v[166:169], v[220:223], v[14:17]
	v_mfma_f32_16x16x32_bf16 v[50:53], v[170:173], v[192:195], v[50:53]
	v_mfma_f32_16x16x32_bf16 v[42:45], v[178:181], v[192:195], v[42:45]
	v_mfma_f32_16x16x32_bf16 v[34:37], v[170:173], v[200:203], v[34:37]
	v_mfma_f32_16x16x32_bf16 v[26:29], v[178:181], v[200:203], v[26:29]
	v_mfma_f32_16x16x32_bf16 v[18:21], v[170:173], v[208:211], v[18:21]
	v_mfma_f32_16x16x32_bf16 v[10:13], v[178:181], v[208:211], v[10:13]
	v_mfma_f32_16x16x32_bf16 v[6:9], v[170:173], v[216:219], v[6:9]
	v_mfma_f32_16x16x32_bf16 v[2:5], v[178:181], v[216:219], v[2:5]
	v_mfma_f32_16x16x32_bf16 v[50:53], v[174:177], v[196:199], v[50:53]
	v_mfma_f32_16x16x32_bf16 v[42:45], v[188:191], v[196:199], v[42:45]
	v_mfma_f32_16x16x32_bf16 v[34:37], v[174:177], v[204:207], v[34:37]
	v_mfma_f32_16x16x32_bf16 v[26:29], v[188:191], v[204:207], v[26:29]
	v_mfma_f32_16x16x32_bf16 v[18:21], v[174:177], v[212:215], v[18:21]
	v_mfma_f32_16x16x32_bf16 v[10:13], v[188:191], v[212:215], v[10:13]
	v_mfma_f32_16x16x32_bf16 v[6:9], v[174:177], v[220:223], v[6:9]
	v_mfma_f32_16x16x32_bf16 v[2:5], v[188:191], v[220:223], v[2:5]
	s_barrier
	s_add_i32 s21, 0, 0x18000
	v_add_u32_e32 v1, s21, v157
	s_add_i32 s92, 0, 0x1c000
	ds_read_b128 v[130:133], v1
	ds_read_b128 v[134:137], v1 offset:1024
	ds_read_b128 v[162:165], v1 offset:2048
	ds_read_b128 v[166:169], v1 offset:3072
	v_add_u32_e32 v1, s92, v157
	ds_read_b128 v[170:173], v1
	ds_read_b128 v[174:177], v1 offset:1024
	ds_read_b128 v[178:181], v1 offset:2048
	ds_read_b128 v[188:191], v1 offset:3072
	s_add_u32 s60, s60, 0x10000
	s_addc_u32 s61, s61, 0
	s_mov_b32 m0, s64
	v_lshl_add_u64 v[230:231], s[60:61], 0, v[138:139]
	ds_read_b128 v[192:195], v160 offset:32768
	ds_read_b128 v[196:199], v160 offset:33792
	ds_read_b128 v[200:203], v160 offset:34816
	ds_read_b128 v[204:207], v160 offset:35840
	ds_read_b128 v[208:211], v160 offset:36864
	ds_read_b128 v[212:215], v160 offset:37888
	ds_read_b128 v[216:219], v160 offset:38912
	ds_read_b128 v[220:223], v160 offset:39936
	global_load_lds_dwordx4 v[230:231], off
	v_lshl_add_u64 v[230:231], s[60:61], 0, v[140:141]
	s_mov_b32 m0, s65
	s_nop 0
	global_load_lds_dwordx4 v[230:231], off
	s_waitcnt vmcnt(8)
	s_waitcnt lgkmcnt(0)
	s_barrier
	s_waitcnt lgkmcnt(0)
	v_mfma_f32_16x16x32_bf16 v[126:129], v[130:133], v[192:195], v[126:129]
	v_mfma_f32_16x16x32_bf16 v[122:125], v[162:165], v[192:195], v[122:125]
	v_mfma_f32_16x16x32_bf16 v[118:121], v[130:133], v[200:203], v[118:121]
	v_mfma_f32_16x16x32_bf16 v[110:113], v[162:165], v[200:203], v[110:113]
	v_mfma_f32_16x16x32_bf16 v[102:105], v[130:133], v[208:211], v[102:105]
	v_mfma_f32_16x16x32_bf16 v[94:97], v[162:165], v[208:211], v[94:97]
	v_mfma_f32_16x16x32_bf16 v[86:89], v[130:133], v[216:219], v[86:89]
	v_mfma_f32_16x16x32_bf16 v[78:81], v[162:165], v[216:219], v[78:81]
	v_mfma_f32_16x16x32_bf16 v[126:129], v[134:137], v[196:199], v[126:129]
	v_mfma_f32_16x16x32_bf16 v[122:125], v[166:169], v[196:199], v[122:125]
	v_mfma_f32_16x16x32_bf16 v[118:121], v[134:137], v[204:207], v[118:121]
	v_mfma_f32_16x16x32_bf16 v[110:113], v[166:169], v[204:207], v[110:113]
	v_mfma_f32_16x16x32_bf16 v[102:105], v[134:137], v[212:215], v[102:105]
	v_mfma_f32_16x16x32_bf16 v[94:97], v[166:169], v[212:215], v[94:97]
	v_mfma_f32_16x16x32_bf16 v[86:89], v[134:137], v[220:223], v[86:89]
	v_mfma_f32_16x16x32_bf16 v[78:81], v[166:169], v[220:223], v[78:81]
	v_mfma_f32_16x16x32_bf16 v[114:117], v[170:173], v[192:195], v[114:117]
	v_mfma_f32_16x16x32_bf16 v[106:109], v[178:181], v[192:195], v[106:109]
	v_mfma_f32_16x16x32_bf16 v[98:101], v[170:173], v[200:203], v[98:101]
	v_mfma_f32_16x16x32_bf16 v[90:93], v[178:181], v[200:203], v[90:93]
	v_mfma_f32_16x16x32_bf16 v[82:85], v[170:173], v[208:211], v[82:85]
	v_mfma_f32_16x16x32_bf16 v[74:77], v[178:181], v[208:211], v[74:77]
	v_mfma_f32_16x16x32_bf16 v[70:73], v[170:173], v[216:219], v[70:73]
	v_mfma_f32_16x16x32_bf16 v[66:69], v[178:181], v[216:219], v[66:69]
	v_mfma_f32_16x16x32_bf16 v[114:117], v[174:177], v[196:199], v[114:117]
	v_mfma_f32_16x16x32_bf16 v[106:109], v[188:191], v[196:199], v[106:109]
	v_mfma_f32_16x16x32_bf16 v[98:101], v[174:177], v[204:207], v[98:101]
	v_mfma_f32_16x16x32_bf16 v[90:93], v[188:191], v[204:207], v[90:93]
	v_mfma_f32_16x16x32_bf16 v[82:85], v[174:177], v[212:215], v[82:85]
	v_mfma_f32_16x16x32_bf16 v[74:77], v[188:191], v[212:215], v[74:77]
	v_mfma_f32_16x16x32_bf16 v[70:73], v[174:177], v[220:223], v[70:73]
	v_mfma_f32_16x16x32_bf16 v[66:69], v[188:191], v[220:223], v[66:69]
	s_barrier
; #define PG8_STAGE(bufoff, gbase, voff) do { _Pragma("unroll") for (int _i = 0; _i < 2; ++_i) \
;         __builtin_amdgcn_global_load_lds((const GAS unsigned*)((const char*)(gbase) + (voff)[_i]), (LAS unsigned*)(lds + (bufoff) + ldsw + _i * 8192), 16, 0, 0); } while (0)
; #define PG8_LDA(dst, b, h) do { _Pragma("unroll") for (int m = 0; m < 4; ++m) _Pragma("unroll") for (int k = 0; k < 2; ++k) dst[m][k] = *(const LAS bf16x8*)(lds + PG8_SA(b, h) + aoff + m * 2048 + k * 1024); } while (0)
; #define PG8_MMA(ai, bj, At, Bt) do { __builtin_amdgcn_s_setprio(1); _Pragma("unroll") for (int m = 0; m < 4; ++m) _Pragma("unroll") for (int n = 0; n < 2; ++n) _Pragma("unroll") for (int k = 0; k < 2; ++k) \
;         acc[ai][bj][m][n] = __builtin_amdgcn_mfma_f32_16x16x32_bf16(Bt[n][k], At[m][k], acc[ai][bj][m][n], 0, 0, 0); __builtin_amdgcn_s_setprio(0); } while (0)
; #define PG8_WAIT_V(n) asm volatile("s_waitcnt vmcnt(" #n ")" ::: "memory")
; #define PG8_WAIT_L(n) asm volatile("s_waitcnt lgkmcnt(" #n ")" ::: "memory")
; #define PG8_BAR __builtin_amdgcn_s_barrier()
; #define PG8_SCHED __builtin_amdgcn_sched_barrier(0)
; template <class Epi, class Sched>
; __device__ __forceinline__ void gemm_phase(LAS unsigned char* lds, const Gemm g, const Sched& S, const Epi& E, const int wave_) {
;     ...
;         for (int t = 0; t < nt; t += 2) {
;     ...
;             PG8_LDA(At, 1, 1); PG8_STAGE(PG8_SB(1, 0), b3, voffB); PG8_STAGE(PG8_SB(1, 1), b3 + hstepB, voffB); PG8_STAGE(PG8_SA(1, 0), a3, voffA);
;             PG8_WAIT_V(8); PG8_WAIT_L(0); PG8_BAR; PG8_MMA(1, 0, At, B0); PG8_MMA(1, 1, At, B1); PG8_BAR; PG8_SCHED;
	s_add_i32 s21, s21, s83
	v_lshl_add_u64 v[182:183], v[182:183], 0, s[38:39]
	s_mov_b32 m0, s21
	ds_read_b128 v[192:195], v160 offset:49152
	ds_read_b128 v[196:199], v160 offset:50176
	ds_read_b128 v[200:203], v160 offset:51200
	ds_read_b128 v[204:207], v160 offset:52224
	ds_read_b128 v[208:211], v160 offset:53248
	ds_read_b128 v[212:215], v160 offset:54272
	ds_read_b128 v[216:219], v160 offset:55296
	ds_read_b128 v[220:223], v160 offset:56320
	global_load_lds_dwordx4 v[182:183], off
	s_add_i32 m0, s21, 0x2000
	s_add_u32 s58, s58, 0x10080
	v_lshl_add_u64 v[182:183], v[224:225], 0, s[38:39]
	s_addc_u32 s59, s59, 0
	s_add_i32 s21, s92, s83
	global_load_lds_dwordx4 v[182:183], off
	v_lshl_add_u64 v[182:183], s[58:59], 0, v[138:139]
	s_mov_b32 m0, s21
	s_nop 0
	global_load_lds_dwordx4 v[182:183], off
	v_lshl_add_u64 v[182:183], s[58:59], 0, v[140:141]
	s_add_i32 m0, s21, 0x2000
	s_nop 0
	global_load_lds_dwordx4 v[182:183], off
	v_lshl_add_u64 v[182:183], v[226:227], 0, s[38:39]
	s_mov_b32 m0, s69
	s_nop 0
	global_load_lds_dwordx4 v[182:183], off
	v_lshl_add_u64 v[182:183], v[228:229], 0, s[38:39]
	s_mov_b32 m0, s70
	s_nop 0
	global_load_lds_dwordx4 v[182:183], off
	s_waitcnt vmcnt(8)
	s_waitcnt lgkmcnt(0)
	s_barrier
	s_waitcnt lgkmcnt(0)
	v_mfma_f32_16x16x32_bf16 v[62:65], v[130:133], v[192:195], v[62:65]
	v_mfma_f32_16x16x32_bf16 v[58:61], v[162:165], v[192:195], v[58:61]
	v_mfma_f32_16x16x32_bf16 v[54:57], v[130:133], v[200:203], v[54:57]
	v_mfma_f32_16x16x32_bf16 v[46:49], v[162:165], v[200:203], v[46:49]
	v_mfma_f32_16x16x32_bf16 v[38:41], v[130:133], v[208:211], v[38:41]
	v_mfma_f32_16x16x32_bf16 v[30:33], v[162:165], v[208:211], v[30:33]
	v_mfma_f32_16x16x32_bf16 v[22:25], v[130:133], v[216:219], v[22:25]
	v_mfma_f32_16x16x32_bf16 v[14:17], v[162:165], v[216:219], v[14:17]
	v_mfma_f32_16x16x32_bf16 v[62:65], v[134:137], v[196:199], v[62:65]
	v_mfma_f32_16x16x32_bf16 v[58:61], v[166:169], v[196:199], v[58:61]
	v_mfma_f32_16x16x32_bf16 v[54:57], v[134:137], v[204:207], v[54:57]
	v_mfma_f32_16x16x32_bf16 v[46:49], v[166:169], v[204:207], v[46:49]
	v_mfma_f32_16x16x32_bf16 v[38:41], v[134:137], v[212:215], v[38:41]
	v_mfma_f32_16x16x32_bf16 v[30:33], v[166:169], v[212:215], v[30:33]
	v_mfma_f32_16x16x32_bf16 v[22:25], v[134:137], v[220:223], v[22:25]
	v_mfma_f32_16x16x32_bf16 v[14:17], v[166:169], v[220:223], v[14:17]
	v_mfma_f32_16x16x32_bf16 v[50:53], v[170:173], v[192:195], v[50:53]
	v_mfma_f32_16x16x32_bf16 v[42:45], v[178:181], v[192:195], v[42:45]
	v_mfma_f32_16x16x32_bf16 v[34:37], v[170:173], v[200:203], v[34:37]
	v_mfma_f32_16x16x32_bf16 v[26:29], v[178:181], v[200:203], v[26:29]
	v_mfma_f32_16x16x32_bf16 v[18:21], v[170:173], v[208:211], v[18:21]
	v_mfma_f32_16x16x32_bf16 v[10:13], v[178:181], v[208:211], v[10:13]
	v_mfma_f32_16x16x32_bf16 v[6:9], v[170:173], v[216:219], v[6:9]
	v_mfma_f32_16x16x32_bf16 v[2:5], v[178:181], v[216:219], v[2:5]
	v_mfma_f32_16x16x32_bf16 v[50:53], v[174:177], v[196:199], v[50:53]
	v_mfma_f32_16x16x32_bf16 v[42:45], v[188:191], v[196:199], v[42:45]
	v_mfma_f32_16x16x32_bf16 v[34:37], v[174:177], v[204:207], v[34:37]
	v_mfma_f32_16x16x32_bf16 v[26:29], v[188:191], v[204:207], v[26:29]
	v_mfma_f32_16x16x32_bf16 v[18:21], v[174:177], v[212:215], v[18:21]
	v_mfma_f32_16x16x32_bf16 v[10:13], v[188:191], v[212:215], v[10:13]
	v_mfma_f32_16x16x32_bf16 v[6:9], v[174:177], v[220:223], v[6:9]
	v_mfma_f32_16x16x32_bf16 v[2:5], v[188:191], v[220:223], v[2:5]
	s_barrier
	s_add_u32 s89, s89, 0x100
	s_addc_u32 s90, s90, 0
	s_add_u32 s10, s10, 0x100
	s_addc_u32 s11, s11, 0
	s_cmp_ge_i32 s91, s68
	s_mov_b32 s58, s91
	s_cbranch_scc0 .LBB0_715
;     __device__ __forceinline__ void operator()(const f32x4 (&acc)[2][2][4][2], const Unit& u, int wr, int wc, int fr, int fq) const {
;         const float sc = 0.10206207261596577f * LOG2E;
; #pragma unroll
;         for (int ai = 0; ai < 2; ++ai)
; #pragma unroll
;             for (int m = 0; m < 4; ++m) {
;                 const int row = u.pm * 256 + ai * 128 + wr * 64 + m * 16 + fr;
; #pragma unroll
;                 for (int bj = 0; bj < 2; ++bj) {
;                     const int c0 = u.pn * 256 + bj * 128 + wc * 32;
;                     f32x4 a = acc[ai][bj][m][0] * sc, b = acc[ai][bj][m][1] * sc;
	v_pk_mul_f32 v[136:137], v[128:129], s[44:45] op_sel_hi:[1,0]
	v_pk_mul_f32 v[134:135], v[126:127], s[44:45] op_sel_hi:[1,0]
	v_pk_mul_f32 v[132:133], v[124:125], s[44:45] op_sel_hi:[1,0]
	v_pk_mul_f32 v[130:131], v[122:123], s[44:45] op_sel_hi:[1,0]
	v_pk_mul_f32 v[128:129], v[116:117], s[44:45] op_sel_hi:[1,0]
	v_pk_mul_f32 v[126:127], v[114:115], s[44:45] op_sel_hi:[1,0]
	v_pk_mul_f32 v[124:125], v[108:109], s[44:45] op_sel_hi:[1,0]
	v_pk_mul_f32 v[122:123], v[106:107], s[44:45] op_sel_hi:[1,0]
	v_pk_mul_f32 v[120:121], v[120:121], s[44:45] op_sel_hi:[1,0]
	v_pk_mul_f32 v[118:119], v[118:119], s[44:45] op_sel_hi:[1,0]
	v_pk_mul_f32 v[116:117], v[112:113], s[44:45] op_sel_hi:[1,0]
	v_pk_mul_f32 v[114:115], v[110:111], s[44:45] op_sel_hi:[1,0]
	v_pk_mul_f32 v[112:113], v[100:101], s[44:45] op_sel_hi:[1,0]
	v_pk_mul_f32 v[110:111], v[98:99], s[44:45] op_sel_hi:[1,0]
	v_pk_mul_f32 v[108:109], v[92:93], s[44:45] op_sel_hi:[1,0]
	v_pk_mul_f32 v[106:107], v[90:91], s[44:45] op_sel_hi:[1,0]
	v_pk_mul_f32 v[104:105], v[104:105], s[44:45] op_sel_hi:[1,0]
	v_pk_mul_f32 v[102:103], v[102:103], s[44:45] op_sel_hi:[1,0]
	v_pk_mul_f32 v[100:101], v[96:97], s[44:45] op_sel_hi:[1,0]
	v_pk_mul_f32 v[98:99], v[94:95], s[44:45] op_sel_hi:[1,0]
	v_pk_mul_f32 v[96:97], v[84:85], s[44:45] op_sel_hi:[1,0]
	v_pk_mul_f32 v[94:95], v[82:83], s[44:45] op_sel_hi:[1,0]
	v_pk_mul_f32 v[92:93], v[76:77], s[44:45] op_sel_hi:[1,0]
	v_pk_mul_f32 v[90:91], v[74:75], s[44:45] op_sel_hi:[1,0]
	v_pk_mul_f32 v[88:89], v[88:89], s[44:45] op_sel_hi:[1,0]
	v_pk_mul_f32 v[86:87], v[86:87], s[44:45] op_sel_hi:[1,0]
	v_pk_mul_f32 v[84:85], v[80:81], s[44:45] op_sel_hi:[1,0]
	v_pk_mul_f32 v[82:83], v[78:79], s[44:45] op_sel_hi:[1,0]
	v_pk_mul_f32 v[80:81], v[72:73], s[44:45] op_sel_hi:[1,0]
	v_pk_mul_f32 v[78:79], v[70:71], s[44:45] op_sel_hi:[1,0]
	v_pk_mul_f32 v[76:77], v[68:69], s[44:45] op_sel_hi:[1,0]
	v_pk_mul_f32 v[74:75], v[66:67], s[44:45] op_sel_hi:[1,0]
	v_pk_mul_f32 v[72:73], v[64:65], s[44:45] op_sel_hi:[1,0]
	v_pk_mul_f32 v[70:71], v[62:63], s[44:45] op_sel_hi:[1,0]
	v_pk_mul_f32 v[68:69], v[60:61], s[44:45] op_sel_hi:[1,0]
	v_pk_mul_f32 v[66:67], v[58:59], s[44:45] op_sel_hi:[1,0]
	v_pk_mul_f32 v[64:65], v[52:53], s[44:45] op_sel_hi:[1,0]
	v_pk_mul_f32 v[62:63], v[50:51], s[44:45] op_sel_hi:[1,0]
	v_pk_mul_f32 v[60:61], v[44:45], s[44:45] op_sel_hi:[1,0]
	v_pk_mul_f32 v[58:59], v[42:43], s[44:45] op_sel_hi:[1,0]
	v_pk_mul_f32 v[56:57], v[56:57], s[44:45] op_sel_hi:[1,0]
	v_pk_mul_f32 v[54:55], v[54:55], s[44:45] op_sel_hi:[1,0]
	v_pk_mul_f32 v[52:53], v[48:49], s[44:45] op_sel_hi:[1,0]
	v_pk_mul_f32 v[50:51], v[46:47], s[44:45] op_sel_hi:[1,0]
	v_pk_mul_f32 v[48:49], v[36:37], s[44:45] op_sel_hi:[1,0]
	v_pk_mul_f32 v[46:47], v[34:35], s[44:45] op_sel_hi:[1,0]
	v_pk_mul_f32 v[44:45], v[28:29], s[44:45] op_sel_hi:[1,0]
	v_pk_mul_f32 v[42:43], v[26:27], s[44:45] op_sel_hi:[1,0]
	v_pk_mul_f32 v[40:41], v[40:41], s[44:45] op_sel_hi:[1,0]
	v_pk_mul_f32 v[38:39], v[38:39], s[44:45] op_sel_hi:[1,0]
	v_pk_mul_f32 v[36:37], v[32:33], s[44:45] op_sel_hi:[1,0]
	v_pk_mul_f32 v[34:35], v[30:31], s[44:45] op_sel_hi:[1,0]
	v_pk_mul_f32 v[32:33], v[20:21], s[44:45] op_sel_hi:[1,0]
	v_pk_mul_f32 v[30:31], v[18:19], s[44:45] op_sel_hi:[1,0]
	v_pk_mul_f32 v[28:29], v[12:13], s[44:45] op_sel_hi:[1,0]
	v_pk_mul_f32 v[26:27], v[10:11], s[44:45] op_sel_hi:[1,0]
	v_pk_mul_f32 v[20:21], v[24:25], s[44:45] op_sel_hi:[1,0]
	v_pk_mul_f32 v[18:19], v[22:23], s[44:45] op_sel_hi:[1,0]
	v_pk_mul_f32 v[12:13], v[16:17], s[44:45] op_sel_hi:[1,0]
	v_pk_mul_f32 v[10:11], v[14:15], s[44:45] op_sel_hi:[1,0]
	v_pk_mul_f32 v[8:9], v[8:9], s[44:45] op_sel_hi:[1,0]
	v_pk_mul_f32 v[6:7], v[6:7], s[44:45] op_sel_hi:[1,0]
	v_pk_mul_f32 v[4:5], v[4:5], s[44:45] op_sel_hi:[1,0]
	v_pk_mul_f32 v[2:3], v[2:3], s[44:45] op_sel_hi:[1,0]

; #define PG8_STAGE(bufoff, gbase, voff) do { _Pragma("unroll") for (int _i = 0; _i < 2; ++_i) \
;         __builtin_amdgcn_global_load_lds((const GAS unsigned*)((const char*)(gbase) + (voff)[_i]), (LAS unsigned*)(lds + (bufoff) + ldsw + _i * 8192), 16, 0, 0); } while (0)
; #define PG8_LDA(dst, b, h) do { _Pragma("unroll") for (int m = 0; m < 4; ++m) _Pragma("unroll") for (int k = 0; k < 2; ++k) dst[m][k] = *(const LAS bf16x8*)(lds + PG8_SA(b, h) + aoff + m * 2048 + k * 1024); } while (0)
; #define PG8_LDB(dst, b, h) do { _Pragma("unroll") for (int n = 0; n < 2; ++n) _Pragma("unroll") for (int k = 0; k < 2; ++k) dst[n][k] = *(const LAS bf16x8*)(lds + PG8_SB(b, h) + boff + n * 2048 + k * 1024); } while (0)
; #define PG8_MMA(ai, bj, At, Bt) do { __builtin_amdgcn_s_setprio(1); _Pragma("unroll") for (int m = 0; m < 4; ++m) _Pragma("unroll") for (int n = 0; n < 2; ++n) _Pragma("unroll") for (int k = 0; k < 2; ++k) \
;         acc[ai][bj][m][n] = __builtin_amdgcn_mfma_f32_16x16x32_bf16(Bt[n][k], At[m][k], acc[ai][bj][m][n], 0, 0, 0); __builtin_amdgcn_s_setprio(0); } while (0)
; #define PG8_WAIT_V(n) asm volatile("s_waitcnt vmcnt(" #n ")" ::: "memory")
; #define PG8_WAIT_L(n) asm volatile("s_waitcnt lgkmcnt(" #n ")" ::: "memory")
; #define PG8_BAR __builtin_amdgcn_s_barrier()
; #define PG8_SCHED __builtin_amdgcn_sched_barrier(0)
; template <class Epi, class Sched>
; __device__ __forceinline__ void gemm_phase(LAS unsigned char* lds, const Gemm g, const Sched& S, const Epi& E, const int wave_) {
;     ...
;             const bool last = (t == nt - 2);
;             const char* a1 = cA + (size_t)(t + 1) * kstep;
;             const char* a2 = last ? nA : cA + (size_t)(t + 2) * kstep; const char* b2 = last ? nB : cB + (size_t)(t + 2) * kstep;
;             const char* a3 = a2 + kstep; const char* b3 = b2 + kstep;
;             PG8_LDB(B0, 0, 0); PG8_LDB(B1, 0, 1); PG8_SCHED; PG8_LDA(At, 0, 0); PG8_STAGE(PG8_SA(1, 1), a1 + hstepA, voffA);
;             PG8_WAIT_V(8); PG8_WAIT_L(0); PG8_BAR; PG8_MMA(0, 0, At, B0); PG8_MMA(0, 1, At, B1); PG8_BAR; PG8_SCHED;
;             PG8_LDA(At, 0, 1); PG8_STAGE(PG8_SB(0, 0), b2, voffB); PG8_STAGE(PG8_SB(0, 1), b2 + hstepB, voffB); PG8_STAGE(PG8_SA(0, 0), a2, voffA);
;             PG8_WAIT_V(8); PG8_WAIT_L(0); PG8_BAR; PG8_MMA(1, 0, At, B0); PG8_MMA(1, 1, At, B1); PG8_BAR; PG8_SCHED;
.LBB0_773:
	ds_read_b128 v[152:155], v149
	ds_read_b128 v[156:159], v149 offset:1024
	ds_read_b128 v[160:163], v149 offset:2048
	ds_read_b128 v[164:167], v149 offset:3072
	ds_read_b128 v[168:171], v150
	ds_read_b128 v[172:175], v150 offset:1024
	ds_read_b128 v[176:179], v150 offset:2048
	ds_read_b128 v[180:183], v150 offset:3072
	s_add_i32 s81, s54, 2
	s_add_u32 s21, s52, 0xffff8080
	s_addc_u32 s55, s53, -1
	s_cmp_eq_u32 s67, s54
	s_cselect_b32 s54, s76, s77
	s_cselect_b32 s57, s41, s55
	s_cselect_b32 s56, s43, s21
	s_cselect_b32 s55, s75, s78
	v_lshl_add_u64 v[220:221], s[52:53], 0, v[140:141]
	s_add_i32 m0, s39, 0xc000
	ds_read_b128 v[188:191], v151
	ds_read_b128 v[192:195], v151 offset:1024
	ds_read_b128 v[196:199], v151 offset:2048
	ds_read_b128 v[200:203], v151 offset:3072
	ds_read_b128 v[204:207], v151 offset:4096
	ds_read_b128 v[208:211], v151 offset:5120
	ds_read_b128 v[212:215], v151 offset:6144
	ds_read_b128 v[216:219], v151 offset:7168
	global_load_lds_dwordx4 v[220:221], off
	v_lshl_add_u64 v[220:221], s[52:53], 0, v[138:139]
	s_add_i32 m0, s39, 0xe000
	s_nop 0
	global_load_lds_dwordx4 v[220:221], off
	s_waitcnt vmcnt(8)
	s_waitcnt lgkmcnt(0)
	s_barrier
	s_waitcnt lgkmcnt(0)
	v_mfma_f32_16x16x32_bf16 v[120:123], v[152:155], v[188:191], v[120:123]
	v_mfma_f32_16x16x32_bf16 v[124:127], v[160:163], v[188:191], v[124:127]
	v_mfma_f32_16x16x32_bf16 v[108:111], v[152:155], v[196:199], v[108:111]
	v_mfma_f32_16x16x32_bf16 v[104:107], v[160:163], v[196:199], v[104:107]
	v_mfma_f32_16x16x32_bf16 v[92:95], v[152:155], v[204:207], v[92:95]
	v_mfma_f32_16x16x32_bf16 v[88:91], v[160:163], v[204:207], v[88:91]
	v_mfma_f32_16x16x32_bf16 v[76:79], v[152:155], v[212:215], v[76:79]
	v_mfma_f32_16x16x32_bf16 v[72:75], v[160:163], v[212:215], v[72:75]
	v_mfma_f32_16x16x32_bf16 v[120:123], v[156:159], v[192:195], v[120:123]
	v_mfma_f32_16x16x32_bf16 v[124:127], v[164:167], v[192:195], v[124:127]
	v_mfma_f32_16x16x32_bf16 v[108:111], v[156:159], v[200:203], v[108:111]
	v_mfma_f32_16x16x32_bf16 v[104:107], v[164:167], v[200:203], v[104:107]
	v_mfma_f32_16x16x32_bf16 v[92:95], v[156:159], v[208:211], v[92:95]
	v_mfma_f32_16x16x32_bf16 v[88:91], v[164:167], v[208:211], v[88:91]
	v_mfma_f32_16x16x32_bf16 v[76:79], v[156:159], v[216:219], v[76:79]
	v_mfma_f32_16x16x32_bf16 v[72:75], v[164:167], v[216:219], v[72:75]
	v_mfma_f32_16x16x32_bf16 v[116:119], v[168:171], v[188:191], v[116:119]
	v_mfma_f32_16x16x32_bf16 v[112:115], v[176:179], v[188:191], v[112:115]
	v_mfma_f32_16x16x32_bf16 v[100:103], v[168:171], v[196:199], v[100:103]
	v_mfma_f32_16x16x32_bf16 v[96:99], v[176:179], v[196:199], v[96:99]
	v_mfma_f32_16x16x32_bf16 v[84:87], v[168:171], v[204:207], v[84:87]
	v_mfma_f32_16x16x32_bf16 v[80:83], v[176:179], v[204:207], v[80:83]
	v_mfma_f32_16x16x32_bf16 v[68:71], v[168:171], v[212:215], v[68:71]
	v_mfma_f32_16x16x32_bf16 v[64:67], v[176:179], v[212:215], v[64:67]
	v_mfma_f32_16x16x32_bf16 v[116:119], v[172:175], v[192:195], v[116:119]
	v_mfma_f32_16x16x32_bf16 v[112:115], v[180:183], v[192:195], v[112:115]
	v_mfma_f32_16x16x32_bf16 v[100:103], v[172:175], v[200:203], v[100:103]
	v_mfma_f32_16x16x32_bf16 v[96:99], v[180:183], v[200:203], v[96:99]
	v_mfma_f32_16x16x32_bf16 v[84:87], v[172:175], v[208:211], v[84:87]
	v_mfma_f32_16x16x32_bf16 v[80:83], v[180:183], v[208:211], v[80:83]
	v_mfma_f32_16x16x32_bf16 v[68:71], v[172:175], v[216:219], v[68:71]
	v_mfma_f32_16x16x32_bf16 v[64:67], v[180:183], v[216:219], v[64:67]
	s_barrier
	s_add_i32 s21, s70, s83
	v_lshl_add_u64 v[220:221], s[54:55], 0, v[130:131]
	s_mov_b32 m0, s21
	ds_read_b128 v[188:191], v151 offset:16384
	ds_read_b128 v[192:195], v151 offset:17408
	ds_read_b128 v[196:199], v151 offset:18432
	ds_read_b128 v[200:203], v151 offset:19456
	ds_read_b128 v[204:207], v151 offset:20480
	ds_read_b128 v[208:211], v151 offset:21504
	ds_read_b128 v[212:215], v151 offset:22528
	ds_read_b128 v[216:219], v151 offset:23552
	global_load_lds_dwordx4 v[220:221], off
	s_add_i32 m0, s21, 0x2000
	s_add_u32 s90, s54, 0x8000
	v_lshl_add_u64 v[222:223], s[54:55], 0, v[134:135]
	s_addc_u32 s91, s55, 0
	s_add_i32 s21, s71, s83
	global_load_lds_dwordx4 v[222:223], off
	v_lshl_add_u64 v[224:225], s[90:91], 0, v[130:131]
	s_mov_b32 m0, s21
	v_lshl_add_u64 v[226:227], s[56:57], 0, v[132:133]
	global_load_lds_dwordx4 v[224:225], off
	v_lshl_add_u64 v[224:225], s[90:91], 0, v[134:135]
	s_add_i32 m0, s21, 0x2000
	s_nop 0
	global_load_lds_dwordx4 v[224:225], off
	v_lshl_add_u64 v[224:225], s[56:57], 0, v[128:129]
	s_mov_b32 m0, s39
	s_nop 0
	global_load_lds_dwordx4 v[224:225], off
	s_mov_b32 m0, s59
	s_nop 0
	global_load_lds_dwordx4 v[226:227], off
	s_waitcnt vmcnt(8)
	s_waitcnt lgkmcnt(0)
	s_barrier
; #define PG8_STAGE(bufoff, gbase, voff) do { _Pragma("unroll") for (int _i = 0; _i < 2; ++_i) \
;         __builtin_amdgcn_global_load_lds((const GAS unsigned*)((const char*)(gbase) + (voff)[_i]), (LAS unsigned*)(lds + (bufoff) + ldsw + _i * 8192), 16, 0, 0); } while (0)
; #define PG8_LDA(dst, b, h) do { _Pragma("unroll") for (int m = 0; m < 4; ++m) _Pragma("unroll") for (int k = 0; k < 2; ++k) dst[m][k] = *(const LAS bf16x8*)(lds + PG8_SA(b, h) + aoff + m * 2048 + k * 1024); } while (0)
; #define PG8_LDB(dst, b, h) do { _Pragma("unroll") for (int n = 0; n < 2; ++n) _Pragma("unroll") for (int k = 0; k < 2; ++k) dst[n][k] = *(const LAS bf16x8*)(lds + PG8_SB(b, h) + boff + n * 2048 + k * 1024); } while (0)
; #define PG8_MMA(ai, bj, At, Bt) do { __builtin_amdgcn_s_setprio(1); _Pragma("unroll") for (int m = 0; m < 4; ++m) _Pragma("unroll") for (int n = 0; n < 2; ++n) _Pragma("unroll") for (int k = 0; k < 2; ++k) \
;         acc[ai][bj][m][n] = __builtin_amdgcn_mfma_f32_16x16x32_bf16(Bt[n][k], At[m][k], acc[ai][bj][m][n], 0, 0, 0); __builtin_amdgcn_s_setprio(0); } while (0)
; #define PG8_WAIT_V(n) asm volatile("s_waitcnt vmcnt(" #n ")" ::: "memory")
; #define PG8_WAIT_L(n) asm volatile("s_waitcnt lgkmcnt(" #n ")" ::: "memory")
; #define PG8_BAR __builtin_amdgcn_s_barrier()
; #define PG8_SCHED __builtin_amdgcn_sched_barrier(0)
; template <class Epi, class Sched>
; __device__ __forceinline__ void gemm_phase(LAS unsigned char* lds, const Gemm g, const Sched& S, const Epi& E, const int wave_) {
;     ...
;             PG8_WAIT_V(8); PG8_WAIT_L(0); PG8_BAR; PG8_MMA(1, 0, At, B0); PG8_MMA(1, 1, At, B1); PG8_BAR; PG8_SCHED;
;             PG8_LDB(B0, 1, 0); PG8_LDB(B1, 1, 1); PG8_SCHED; PG8_LDA(At, 1, 0); PG8_STAGE(PG8_SA(0, 1), a2 + hstepA, voffA);
;             PG8_WAIT_V(8); PG8_WAIT_L(0); PG8_BAR; PG8_MMA(0, 0, At, B0); PG8_MMA(0, 1, At, B1); PG8_BAR; PG8_SCHED;
	s_waitcnt lgkmcnt(0)
	v_mfma_f32_16x16x32_bf16 v[60:63], v[152:155], v[188:191], v[60:63]
	v_mfma_f32_16x16x32_bf16 v[56:59], v[160:163], v[188:191], v[56:59]
	v_mfma_f32_16x16x32_bf16 v[44:47], v[152:155], v[196:199], v[44:47]
	v_mfma_f32_16x16x32_bf16 v[40:43], v[160:163], v[196:199], v[40:43]
	v_mfma_f32_16x16x32_bf16 v[28:31], v[152:155], v[204:207], v[28:31]
	v_mfma_f32_16x16x32_bf16 v[24:27], v[160:163], v[204:207], v[24:27]
	v_mfma_f32_16x16x32_bf16 v[12:15], v[152:155], v[212:215], v[12:15]
	v_mfma_f32_16x16x32_bf16 v[8:11], v[160:163], v[212:215], v[8:11]
	v_mfma_f32_16x16x32_bf16 v[60:63], v[156:159], v[192:195], v[60:63]
	v_mfma_f32_16x16x32_bf16 v[56:59], v[164:167], v[192:195], v[56:59]
	v_mfma_f32_16x16x32_bf16 v[44:47], v[156:159], v[200:203], v[44:47]
	v_mfma_f32_16x16x32_bf16 v[40:43], v[164:167], v[200:203], v[40:43]
	v_mfma_f32_16x16x32_bf16 v[28:31], v[156:159], v[208:211], v[28:31]
	v_mfma_f32_16x16x32_bf16 v[24:27], v[164:167], v[208:211], v[24:27]
	v_mfma_f32_16x16x32_bf16 v[12:15], v[156:159], v[216:219], v[12:15]
	v_mfma_f32_16x16x32_bf16 v[8:11], v[164:167], v[216:219], v[8:11]
	v_mfma_f32_16x16x32_bf16 v[52:55], v[168:171], v[188:191], v[52:55]
	v_mfma_f32_16x16x32_bf16 v[48:51], v[176:179], v[188:191], v[48:51]
	v_mfma_f32_16x16x32_bf16 v[36:39], v[168:171], v[196:199], v[36:39]
	v_mfma_f32_16x16x32_bf16 v[32:35], v[176:179], v[196:199], v[32:35]
	v_mfma_f32_16x16x32_bf16 v[20:23], v[168:171], v[204:207], v[20:23]
	v_mfma_f32_16x16x32_bf16 v[16:19], v[176:179], v[204:207], v[16:19]
	v_mfma_f32_16x16x32_bf16 v[4:7], v[168:171], v[212:215], v[4:7]
	v_mfma_f32_16x16x32_bf16 v[0:3], v[176:179], v[212:215], v[0:3]
	v_mfma_f32_16x16x32_bf16 v[52:55], v[172:175], v[192:195], v[52:55]
	v_mfma_f32_16x16x32_bf16 v[48:51], v[180:183], v[192:195], v[48:51]
	v_mfma_f32_16x16x32_bf16 v[36:39], v[172:175], v[200:203], v[36:39]
	v_mfma_f32_16x16x32_bf16 v[32:35], v[180:183], v[200:203], v[32:35]
	v_mfma_f32_16x16x32_bf16 v[20:23], v[172:175], v[208:211], v[20:23]
	v_mfma_f32_16x16x32_bf16 v[16:19], v[180:183], v[208:211], v[16:19]
	v_mfma_f32_16x16x32_bf16 v[4:7], v[172:175], v[216:219], v[4:7]
	v_mfma_f32_16x16x32_bf16 v[0:3], v[180:183], v[216:219], v[0:3]
	s_barrier
	s_add_i32 s21, 0, 0x18000
	s_add_i32 s89, 0, 0x1c000
	v_add_u32_e32 v164, s21, v147
	v_add_u32_e32 v180, s89, v147
	ds_read_b128 v[152:155], v164
	ds_read_b128 v[156:159], v164 offset:1024
	ds_read_b128 v[160:163], v164 offset:2048
	ds_read_b128 v[164:167], v164 offset:3072
	ds_read_b128 v[168:171], v180
	ds_read_b128 v[172:175], v180 offset:1024
	ds_read_b128 v[176:179], v180 offset:2048
	ds_read_b128 v[180:183], v180 offset:3072
	s_add_u32 s56, s56, 0x8000
	s_addc_u32 s57, s57, 0
	s_mov_b32 m0, s60
	v_lshl_add_u64 v[228:229], s[56:57], 0, v[128:129]
	ds_read_b128 v[188:191], v151 offset:32768
	ds_read_b128 v[192:195], v151 offset:33792
	ds_read_b128 v[196:199], v151 offset:34816
	ds_read_b128 v[200:203], v151 offset:35840
	ds_read_b128 v[204:207], v151 offset:36864
	ds_read_b128 v[208:211], v151 offset:37888
	ds_read_b128 v[212:215], v151 offset:38912
	ds_read_b128 v[216:219], v151 offset:39936
	global_load_lds_dwordx4 v[228:229], off
	v_lshl_add_u64 v[228:229], s[56:57], 0, v[132:133]
	s_mov_b32 m0, s61
	s_nop 0
	global_load_lds_dwordx4 v[228:229], off
	s_waitcnt vmcnt(8)
	s_waitcnt lgkmcnt(0)
	s_barrier
	s_waitcnt lgkmcnt(0)
	v_mfma_f32_16x16x32_bf16 v[120:123], v[152:155], v[188:191], v[120:123]
	v_mfma_f32_16x16x32_bf16 v[124:127], v[160:163], v[188:191], v[124:127]
	v_mfma_f32_16x16x32_bf16 v[108:111], v[152:155], v[196:199], v[108:111]
	v_mfma_f32_16x16x32_bf16 v[104:107], v[160:163], v[196:199], v[104:107]
	v_mfma_f32_16x16x32_bf16 v[92:95], v[152:155], v[204:207], v[92:95]
	v_mfma_f32_16x16x32_bf16 v[88:91], v[160:163], v[204:207], v[88:91]
	v_mfma_f32_16x16x32_bf16 v[76:79], v[152:155], v[212:215], v[76:79]
	v_mfma_f32_16x16x32_bf16 v[72:75], v[160:163], v[212:215], v[72:75]
	v_mfma_f32_16x16x32_bf16 v[120:123], v[156:159], v[192:195], v[120:123]
	v_mfma_f32_16x16x32_bf16 v[124:127], v[164:167], v[192:195], v[124:127]
	v_mfma_f32_16x16x32_bf16 v[108:111], v[156:159], v[200:203], v[108:111]
	v_mfma_f32_16x16x32_bf16 v[104:107], v[164:167], v[200:203], v[104:107]
	v_mfma_f32_16x16x32_bf16 v[92:95], v[156:159], v[208:211], v[92:95]
	v_mfma_f32_16x16x32_bf16 v[88:91], v[164:167], v[208:211], v[88:91]
	v_mfma_f32_16x16x32_bf16 v[76:79], v[156:159], v[216:219], v[76:79]
	v_mfma_f32_16x16x32_bf16 v[72:75], v[164:167], v[216:219], v[72:75]
	v_mfma_f32_16x16x32_bf16 v[116:119], v[168:171], v[188:191], v[116:119]
	v_mfma_f32_16x16x32_bf16 v[112:115], v[176:179], v[188:191], v[112:115]
	v_mfma_f32_16x16x32_bf16 v[100:103], v[168:171], v[196:199], v[100:103]
	v_mfma_f32_16x16x32_bf16 v[96:99], v[176:179], v[196:199], v[96:99]
	v_mfma_f32_16x16x32_bf16 v[84:87], v[168:171], v[204:207], v[84:87]
	v_mfma_f32_16x16x32_bf16 v[80:83], v[176:179], v[204:207], v[80:83]
	v_mfma_f32_16x16x32_bf16 v[68:71], v[168:171], v[212:215], v[68:71]
	v_mfma_f32_16x16x32_bf16 v[64:67], v[176:179], v[212:215], v[64:67]
	v_mfma_f32_16x16x32_bf16 v[116:119], v[172:175], v[192:195], v[116:119]
	v_mfma_f32_16x16x32_bf16 v[112:115], v[180:183], v[192:195], v[112:115]
	v_mfma_f32_16x16x32_bf16 v[100:103], v[172:175], v[200:203], v[100:103]
	v_mfma_f32_16x16x32_bf16 v[96:99], v[180:183], v[200:203], v[96:99]
	v_mfma_f32_16x16x32_bf16 v[84:87], v[172:175], v[208:211], v[84:87]
	v_mfma_f32_16x16x32_bf16 v[80:83], v[180:183], v[208:211], v[80:83]
	v_mfma_f32_16x16x32_bf16 v[68:71], v[172:175], v[216:219], v[68:71]
	v_mfma_f32_16x16x32_bf16 v[64:67], v[180:183], v[216:219], v[64:67]
	s_barrier
; #define PG8_STAGE(bufoff, gbase, voff) do { _Pragma("unroll") for (int _i = 0; _i < 2; ++_i) \
;         __builtin_amdgcn_global_load_lds((const GAS unsigned*)((const char*)(gbase) + (voff)[_i]), (LAS unsigned*)(lds + (bufoff) + ldsw + _i * 8192), 16, 0, 0); } while (0)
; #define PG8_LDA(dst, b, h) do { _Pragma("unroll") for (int m = 0; m < 4; ++m) _Pragma("unroll") for (int k = 0; k < 2; ++k) dst[m][k] = *(const LAS bf16x8*)(lds + PG8_SA(b, h) + aoff + m * 2048 + k * 1024); } while (0)
; #define PG8_MMA(ai, bj, At, Bt) do { __builtin_amdgcn_s_setprio(1); _Pragma("unroll") for (int m = 0; m < 4; ++m) _Pragma("unroll") for (int n = 0; n < 2; ++n) _Pragma("unroll") for (int k = 0; k < 2; ++k) \
;         acc[ai][bj][m][n] = __builtin_amdgcn_mfma_f32_16x16x32_bf16(Bt[n][k], At[m][k], acc[ai][bj][m][n], 0, 0, 0); __builtin_amdgcn_s_setprio(0); } while (0)
; #define PG8_WAIT_V(n) asm volatile("s_waitcnt vmcnt(" #n ")" ::: "memory")
; #define PG8_WAIT_L(n) asm volatile("s_waitcnt lgkmcnt(" #n ")" ::: "memory")
; #define PG8_BAR __builtin_amdgcn_s_barrier()
; #define PG8_SCHED __builtin_amdgcn_sched_barrier(0)
; template <class Epi, class Sched>
; __device__ __forceinline__ void gemm_phase(LAS unsigned char* lds, const Gemm g, const Sched& S, const Epi& E, const int wave_) {
;     ...
;         for (int t = 0; t < nt; t += 2) {
;     ...
;             PG8_LDA(At, 1, 1); PG8_STAGE(PG8_SB(1, 0), b3, voffB); PG8_STAGE(PG8_SB(1, 1), b3 + hstepB, voffB); PG8_STAGE(PG8_SA(1, 0), a3, voffA);
;             PG8_WAIT_V(8); PG8_WAIT_L(0); PG8_BAR; PG8_MMA(1, 0, At, B0); PG8_MMA(1, 1, At, B1); PG8_BAR; PG8_SCHED;
	s_add_i32 s21, s21, s83
	v_lshl_add_u64 v[220:221], v[220:221], 0, s[30:31]
	s_mov_b32 m0, s21
	ds_read_b128 v[188:191], v151 offset:49152
	ds_read_b128 v[192:195], v151 offset:50176
	ds_read_b128 v[196:199], v151 offset:51200
	ds_read_b128 v[200:203], v151 offset:52224
	ds_read_b128 v[204:207], v151 offset:53248
	ds_read_b128 v[208:211], v151 offset:54272
	ds_read_b128 v[212:215], v151 offset:55296
	ds_read_b128 v[216:219], v151 offset:56320
	global_load_lds_dwordx4 v[220:221], off
	s_add_i32 m0, s21, 0x2000
	s_add_u32 s54, s54, 0x8080
	v_lshl_add_u64 v[220:221], v[222:223], 0, s[30:31]
	s_addc_u32 s55, s55, 0
	s_add_i32 s21, s89, s83
	global_load_lds_dwordx4 v[220:221], off
	v_lshl_add_u64 v[220:221], s[54:55], 0, v[130:131]
	s_mov_b32 m0, s21
	s_nop 0
	global_load_lds_dwordx4 v[220:221], off
	v_lshl_add_u64 v[220:221], s[54:55], 0, v[134:135]
	s_add_i32 m0, s21, 0x2000
	s_nop 0
	global_load_lds_dwordx4 v[220:221], off
	v_lshl_add_u64 v[220:221], v[224:225], 0, s[30:31]
	s_mov_b32 m0, s64
	s_nop 0
	global_load_lds_dwordx4 v[220:221], off
	v_lshl_add_u64 v[220:221], v[226:227], 0, s[30:31]
	s_mov_b32 m0, s65
	s_nop 0
	global_load_lds_dwordx4 v[220:221], off
	s_waitcnt vmcnt(8)
	s_waitcnt lgkmcnt(0)
	s_barrier
	s_waitcnt lgkmcnt(0)
	v_mfma_f32_16x16x32_bf16 v[60:63], v[152:155], v[188:191], v[60:63]
	v_mfma_f32_16x16x32_bf16 v[56:59], v[160:163], v[188:191], v[56:59]
	v_mfma_f32_16x16x32_bf16 v[44:47], v[152:155], v[196:199], v[44:47]
	v_mfma_f32_16x16x32_bf16 v[40:43], v[160:163], v[196:199], v[40:43]
	v_mfma_f32_16x16x32_bf16 v[28:31], v[152:155], v[204:207], v[28:31]
	v_mfma_f32_16x16x32_bf16 v[24:27], v[160:163], v[204:207], v[24:27]
	v_mfma_f32_16x16x32_bf16 v[12:15], v[152:155], v[212:215], v[12:15]
	v_mfma_f32_16x16x32_bf16 v[8:11], v[160:163], v[212:215], v[8:11]
	v_mfma_f32_16x16x32_bf16 v[60:63], v[156:159], v[192:195], v[60:63]
	v_mfma_f32_16x16x32_bf16 v[56:59], v[164:167], v[192:195], v[56:59]
	v_mfma_f32_16x16x32_bf16 v[44:47], v[156:159], v[200:203], v[44:47]
	v_mfma_f32_16x16x32_bf16 v[40:43], v[164:167], v[200:203], v[40:43]
	v_mfma_f32_16x16x32_bf16 v[28:31], v[156:159], v[208:211], v[28:31]
	v_mfma_f32_16x16x32_bf16 v[24:27], v[164:167], v[208:211], v[24:27]
	v_mfma_f32_16x16x32_bf16 v[12:15], v[156:159], v[216:219], v[12:15]
	v_mfma_f32_16x16x32_bf16 v[8:11], v[164:167], v[216:219], v[8:11]
	v_mfma_f32_16x16x32_bf16 v[52:55], v[168:171], v[188:191], v[52:55]
	v_mfma_f32_16x16x32_bf16 v[48:51], v[176:179], v[188:191], v[48:51]
	v_mfma_f32_16x16x32_bf16 v[36:39], v[168:171], v[196:199], v[36:39]
	v_mfma_f32_16x16x32_bf16 v[32:35], v[176:179], v[196:199], v[32:35]
	v_mfma_f32_16x16x32_bf16 v[20:23], v[168:171], v[204:207], v[20:23]
	v_mfma_f32_16x16x32_bf16 v[16:19], v[176:179], v[204:207], v[16:19]
	v_mfma_f32_16x16x32_bf16 v[4:7], v[168:171], v[212:215], v[4:7]
	v_mfma_f32_16x16x32_bf16 v[0:3], v[176:179], v[212:215], v[0:3]
	v_mfma_f32_16x16x32_bf16 v[52:55], v[172:175], v[192:195], v[52:55]
	v_mfma_f32_16x16x32_bf16 v[48:51], v[180:183], v[192:195], v[48:51]
	v_mfma_f32_16x16x32_bf16 v[36:39], v[172:175], v[200:203], v[36:39]
	v_mfma_f32_16x16x32_bf16 v[32:35], v[180:183], v[200:203], v[32:35]
	v_mfma_f32_16x16x32_bf16 v[20:23], v[172:175], v[208:211], v[20:23]
	v_mfma_f32_16x16x32_bf16 v[16:19], v[180:183], v[208:211], v[16:19]
	v_mfma_f32_16x16x32_bf16 v[4:7], v[172:175], v[216:219], v[4:7]
	v_mfma_f32_16x16x32_bf16 v[0:3], v[180:183], v[216:219], v[0:3]
	s_barrier
	s_add_u32 s77, s77, 0x100
	s_addc_u32 s78, s78, 0
	s_add_u32 s52, s52, 0x100
	s_addc_u32 s53, s53, 0
	s_cmp_ge_i32 s81, s63
	s_mov_b32 s54, s81
	s_cbranch_scc0 .LBB0_773

; #define PG8_STAGE(bufoff, gbase, voff) do { _Pragma("unroll") for (int _i = 0; _i < 2; ++_i) \
;         __builtin_amdgcn_global_load_lds((const GAS unsigned*)((const char*)(gbase) + (voff)[_i]), (LAS unsigned*)(lds + (bufoff) + ldsw + _i * 8192), 16, 0, 0); } while (0)
; #define PG8_LDA(dst, b, h) do { _Pragma("unroll") for (int m = 0; m < 4; ++m) _Pragma("unroll") for (int k = 0; k < 2; ++k) dst[m][k] = *(const LAS bf16x8*)(lds + PG8_SA(b, h) + aoff + m * 2048 + k * 1024); } while (0)
; #define PG8_LDB(dst, b, h) do { _Pragma("unroll") for (int n = 0; n < 2; ++n) _Pragma("unroll") for (int k = 0; k < 2; ++k) dst[n][k] = *(const LAS bf16x8*)(lds + PG8_SB(b, h) + boff + n * 2048 + k * 1024); } while (0)
; #define PG8_MMA(ai, bj, At, Bt) do { __builtin_amdgcn_s_setprio(1); _Pragma("unroll") for (int m = 0; m < 4; ++m) _Pragma("unroll") for (int n = 0; n < 2; ++n) _Pragma("unroll") for (int k = 0; k < 2; ++k) \
;         acc[ai][bj][m][n] = __builtin_amdgcn_mfma_f32_16x16x32_bf16(Bt[n][k], At[m][k], acc[ai][bj][m][n], 0, 0, 0); __builtin_amdgcn_s_setprio(0); } while (0)
; #define PG8_WAIT_V(n) asm volatile("s_waitcnt vmcnt(" #n ")" ::: "memory")
; #define PG8_WAIT_L(n) asm volatile("s_waitcnt lgkmcnt(" #n ")" ::: "memory")
; #define PG8_BAR __builtin_amdgcn_s_barrier()
; #define PG8_SCHED __builtin_amdgcn_sched_barrier(0)
; template <class Epi, class Sched>
; __device__ __forceinline__ void gemm_phase(LAS unsigned char* lds, const Gemm g, const Sched& S, const Epi& E, const int wave_) {
;     ...
;             const bool last = (t == nt - 2);
;             const char* a1 = cA + (size_t)(t + 1) * kstep;
;             const char* a2 = last ? nA : cA + (size_t)(t + 2) * kstep; const char* b2 = last ? nB : cB + (size_t)(t + 2) * kstep;
;             const char* a3 = a2 + kstep; const char* b3 = b2 + kstep;
;             PG8_LDB(B0, 0, 0); PG8_LDB(B1, 0, 1); PG8_SCHED; PG8_LDA(At, 0, 0); PG8_STAGE(PG8_SA(1, 1), a1 + hstepA, voffA);
;             PG8_WAIT_V(8); PG8_WAIT_L(0); PG8_BAR; PG8_MMA(0, 0, At, B0); PG8_MMA(0, 1, At, B1); PG8_BAR; PG8_SCHED;
;             PG8_LDA(At, 0, 1); PG8_STAGE(PG8_SB(0, 0), b2, voffB); PG8_STAGE(PG8_SB(0, 1), b2 + hstepB, voffB); PG8_STAGE(PG8_SA(0, 0), a2, voffA);
;             PG8_WAIT_V(8); PG8_WAIT_L(0); PG8_BAR; PG8_MMA(1, 0, At, B0); PG8_MMA(1, 1, At, B1); PG8_BAR; PG8_SCHED;
.LBB0_798:
	ds_read_b128 v[150:153], v147
	ds_read_b128 v[154:157], v147 offset:1024
	ds_read_b128 v[158:161], v147 offset:2048
	ds_read_b128 v[162:165], v147 offset:3072
	ds_read_b128 v[166:169], v148
	ds_read_b128 v[170:173], v148 offset:1024
	ds_read_b128 v[174:177], v148 offset:2048
	ds_read_b128 v[178:181], v148 offset:3072
	s_add_i32 s76, s54, 2
	s_add_u32 s21, s52, 0xffff8080
	s_addc_u32 s55, s53, -1
	s_cmp_eq_u32 s3, s54
	s_cselect_b32 s54, s73, s74
	s_cselect_b32 s57, s41, s55
	s_cselect_b32 s56, s43, s21
	s_cselect_b32 s55, s72, s75
	v_lshl_add_u64 v[182:183], s[52:53], 0, v[138:139]
	s_add_i32 m0, s39, 0xc000
	ds_read_b128 v[188:191], v149
	ds_read_b128 v[192:195], v149 offset:1024
	ds_read_b128 v[196:199], v149 offset:2048
	ds_read_b128 v[200:203], v149 offset:3072
	ds_read_b128 v[204:207], v149 offset:4096
	ds_read_b128 v[208:211], v149 offset:5120
	ds_read_b128 v[212:215], v149 offset:6144
	ds_read_b128 v[216:219], v149 offset:7168
	global_load_lds_dwordx4 v[182:183], off
	v_lshl_add_u64 v[182:183], s[52:53], 0, v[136:137]
	s_add_i32 m0, s39, 0xe000
	s_nop 0
	global_load_lds_dwordx4 v[182:183], off
	s_waitcnt vmcnt(8)
	s_waitcnt lgkmcnt(0)
	s_barrier
	s_waitcnt lgkmcnt(0)
	v_mfma_f32_16x16x32_bf16 v[120:123], v[150:153], v[188:191], v[120:123]
	v_mfma_f32_16x16x32_bf16 v[124:127], v[158:161], v[188:191], v[124:127]
	v_mfma_f32_16x16x32_bf16 v[108:111], v[150:153], v[196:199], v[108:111]
	v_mfma_f32_16x16x32_bf16 v[104:107], v[158:161], v[196:199], v[104:107]
	v_mfma_f32_16x16x32_bf16 v[92:95], v[150:153], v[204:207], v[92:95]
	v_mfma_f32_16x16x32_bf16 v[88:91], v[158:161], v[204:207], v[88:91]
	v_mfma_f32_16x16x32_bf16 v[76:79], v[150:153], v[212:215], v[76:79]
	v_mfma_f32_16x16x32_bf16 v[72:75], v[158:161], v[212:215], v[72:75]
	v_mfma_f32_16x16x32_bf16 v[120:123], v[154:157], v[192:195], v[120:123]
	v_mfma_f32_16x16x32_bf16 v[124:127], v[162:165], v[192:195], v[124:127]
	v_mfma_f32_16x16x32_bf16 v[108:111], v[154:157], v[200:203], v[108:111]
	v_mfma_f32_16x16x32_bf16 v[104:107], v[162:165], v[200:203], v[104:107]
	v_mfma_f32_16x16x32_bf16 v[92:95], v[154:157], v[208:211], v[92:95]
	v_mfma_f32_16x16x32_bf16 v[88:91], v[162:165], v[208:211], v[88:91]
	v_mfma_f32_16x16x32_bf16 v[76:79], v[154:157], v[216:219], v[76:79]
	v_mfma_f32_16x16x32_bf16 v[72:75], v[162:165], v[216:219], v[72:75]
	v_mfma_f32_16x16x32_bf16 v[116:119], v[166:169], v[188:191], v[116:119]
	v_mfma_f32_16x16x32_bf16 v[112:115], v[174:177], v[188:191], v[112:115]
	v_mfma_f32_16x16x32_bf16 v[100:103], v[166:169], v[196:199], v[100:103]
	v_mfma_f32_16x16x32_bf16 v[96:99], v[174:177], v[196:199], v[96:99]
	v_mfma_f32_16x16x32_bf16 v[84:87], v[166:169], v[204:207], v[84:87]
	v_mfma_f32_16x16x32_bf16 v[80:83], v[174:177], v[204:207], v[80:83]
	v_mfma_f32_16x16x32_bf16 v[68:71], v[166:169], v[212:215], v[68:71]
	v_mfma_f32_16x16x32_bf16 v[64:67], v[174:177], v[212:215], v[64:67]
	v_mfma_f32_16x16x32_bf16 v[116:119], v[170:173], v[192:195], v[116:119]
	v_mfma_f32_16x16x32_bf16 v[112:115], v[178:181], v[192:195], v[112:115]
	v_mfma_f32_16x16x32_bf16 v[100:103], v[170:173], v[200:203], v[100:103]
	v_mfma_f32_16x16x32_bf16 v[96:99], v[178:181], v[200:203], v[96:99]
	v_mfma_f32_16x16x32_bf16 v[84:87], v[170:173], v[208:211], v[84:87]
	v_mfma_f32_16x16x32_bf16 v[80:83], v[178:181], v[208:211], v[80:83]
	v_mfma_f32_16x16x32_bf16 v[68:71], v[170:173], v[216:219], v[68:71]
	v_mfma_f32_16x16x32_bf16 v[64:67], v[178:181], v[216:219], v[64:67]
	s_barrier
	s_add_i32 s21, s69, s83
	v_lshl_add_u64 v[182:183], s[54:55], 0, v[130:131]
	s_mov_b32 m0, s21
	ds_read_b128 v[188:191], v149 offset:16384
	ds_read_b128 v[192:195], v149 offset:17408
	ds_read_b128 v[196:199], v149 offset:18432
	ds_read_b128 v[200:203], v149 offset:19456
	ds_read_b128 v[204:207], v149 offset:20480
	ds_read_b128 v[208:211], v149 offset:21504
	ds_read_b128 v[212:215], v149 offset:22528
	ds_read_b128 v[216:219], v149 offset:23552
	global_load_lds_dwordx4 v[182:183], off
	s_add_i32 m0, s21, 0x2000
	s_add_u32 s90, s54, 0x8000
	v_lshl_add_u64 v[220:221], s[54:55], 0, v[134:135]
	s_addc_u32 s91, s55, 0
	s_add_i32 s21, s70, s83
	global_load_lds_dwordx4 v[220:221], off
	v_lshl_add_u64 v[222:223], s[90:91], 0, v[130:131]
	s_mov_b32 m0, s21
	v_lshl_add_u64 v[224:225], s[56:57], 0, v[132:133]
	global_load_lds_dwordx4 v[222:223], off
	v_lshl_add_u64 v[222:223], s[90:91], 0, v[134:135]
	s_add_i32 m0, s21, 0x2000
	s_nop 0
	global_load_lds_dwordx4 v[222:223], off
	v_lshl_add_u64 v[222:223], s[56:57], 0, v[128:129]
	s_mov_b32 m0, s39
	s_nop 0
	global_load_lds_dwordx4 v[222:223], off
	s_mov_b32 m0, s59
	s_nop 0
	global_load_lds_dwordx4 v[224:225], off
	s_waitcnt vmcnt(8)
	s_waitcnt lgkmcnt(0)
	s_barrier
; #define PG8_STAGE(bufoff, gbase, voff) do { _Pragma("unroll") for (int _i = 0; _i < 2; ++_i) \
;         __builtin_amdgcn_global_load_lds((const GAS unsigned*)((const char*)(gbase) + (voff)[_i]), (LAS unsigned*)(lds + (bufoff) + ldsw + _i * 8192), 16, 0, 0); } while (0)
; #define PG8_LDA(dst, b, h) do { _Pragma("unroll") for (int m = 0; m < 4; ++m) _Pragma("unroll") for (int k = 0; k < 2; ++k) dst[m][k] = *(const LAS bf16x8*)(lds + PG8_SA(b, h) + aoff + m * 2048 + k * 1024); } while (0)
; #define PG8_LDB(dst, b, h) do { _Pragma("unroll") for (int n = 0; n < 2; ++n) _Pragma("unroll") for (int k = 0; k < 2; ++k) dst[n][k] = *(const LAS bf16x8*)(lds + PG8_SB(b, h) + boff + n * 2048 + k * 1024); } while (0)
; #define PG8_MMA(ai, bj, At, Bt) do { __builtin_amdgcn_s_setprio(1); _Pragma("unroll") for (int m = 0; m < 4; ++m) _Pragma("unroll") for (int n = 0; n < 2; ++n) _Pragma("unroll") for (int k = 0; k < 2; ++k) \
;         acc[ai][bj][m][n] = __builtin_amdgcn_mfma_f32_16x16x32_bf16(Bt[n][k], At[m][k], acc[ai][bj][m][n], 0, 0, 0); __builtin_amdgcn_s_setprio(0); } while (0)
; #define PG8_WAIT_V(n) asm volatile("s_waitcnt vmcnt(" #n ")" ::: "memory")
; #define PG8_WAIT_L(n) asm volatile("s_waitcnt lgkmcnt(" #n ")" ::: "memory")
; #define PG8_BAR __builtin_amdgcn_s_barrier()
; #define PG8_SCHED __builtin_amdgcn_sched_barrier(0)
; template <class Epi, class Sched>
; __device__ __forceinline__ void gemm_phase(LAS unsigned char* lds, const Gemm g, const Sched& S, const Epi& E, const int wave_) {
;     ...
;             PG8_WAIT_V(8); PG8_WAIT_L(0); PG8_BAR; PG8_MMA(1, 0, At, B0); PG8_MMA(1, 1, At, B1); PG8_BAR; PG8_SCHED;
;             PG8_LDB(B0, 1, 0); PG8_LDB(B1, 1, 1); PG8_SCHED; PG8_LDA(At, 1, 0); PG8_STAGE(PG8_SA(0, 1), a2 + hstepA, voffA);
;             PG8_WAIT_V(8); PG8_WAIT_L(0); PG8_BAR; PG8_MMA(0, 0, At, B0); PG8_MMA(0, 1, At, B1); PG8_BAR; PG8_SCHED;
	s_waitcnt lgkmcnt(0)
	v_mfma_f32_16x16x32_bf16 v[60:63], v[150:153], v[188:191], v[60:63]
	v_mfma_f32_16x16x32_bf16 v[56:59], v[158:161], v[188:191], v[56:59]
	v_mfma_f32_16x16x32_bf16 v[44:47], v[150:153], v[196:199], v[44:47]
	v_mfma_f32_16x16x32_bf16 v[40:43], v[158:161], v[196:199], v[40:43]
	v_mfma_f32_16x16x32_bf16 v[28:31], v[150:153], v[204:207], v[28:31]
	v_mfma_f32_16x16x32_bf16 v[24:27], v[158:161], v[204:207], v[24:27]
	v_mfma_f32_16x16x32_bf16 v[12:15], v[150:153], v[212:215], v[12:15]
	v_mfma_f32_16x16x32_bf16 v[8:11], v[158:161], v[212:215], v[8:11]
	v_mfma_f32_16x16x32_bf16 v[60:63], v[154:157], v[192:195], v[60:63]
	v_mfma_f32_16x16x32_bf16 v[56:59], v[162:165], v[192:195], v[56:59]
	v_mfma_f32_16x16x32_bf16 v[44:47], v[154:157], v[200:203], v[44:47]
	v_mfma_f32_16x16x32_bf16 v[40:43], v[162:165], v[200:203], v[40:43]
	v_mfma_f32_16x16x32_bf16 v[28:31], v[154:157], v[208:211], v[28:31]
	v_mfma_f32_16x16x32_bf16 v[24:27], v[162:165], v[208:211], v[24:27]
	v_mfma_f32_16x16x32_bf16 v[12:15], v[154:157], v[216:219], v[12:15]
	v_mfma_f32_16x16x32_bf16 v[8:11], v[162:165], v[216:219], v[8:11]
	v_mfma_f32_16x16x32_bf16 v[52:55], v[166:169], v[188:191], v[52:55]
	v_mfma_f32_16x16x32_bf16 v[48:51], v[174:177], v[188:191], v[48:51]
	v_mfma_f32_16x16x32_bf16 v[36:39], v[166:169], v[196:199], v[36:39]
	v_mfma_f32_16x16x32_bf16 v[32:35], v[174:177], v[196:199], v[32:35]
	v_mfma_f32_16x16x32_bf16 v[20:23], v[166:169], v[204:207], v[20:23]
	v_mfma_f32_16x16x32_bf16 v[16:19], v[174:177], v[204:207], v[16:19]
	v_mfma_f32_16x16x32_bf16 v[4:7], v[166:169], v[212:215], v[4:7]
	v_mfma_f32_16x16x32_bf16 v[0:3], v[174:177], v[212:215], v[0:3]
	v_mfma_f32_16x16x32_bf16 v[52:55], v[170:173], v[192:195], v[52:55]
	v_mfma_f32_16x16x32_bf16 v[48:51], v[178:181], v[192:195], v[48:51]
	v_mfma_f32_16x16x32_bf16 v[36:39], v[170:173], v[200:203], v[36:39]
	v_mfma_f32_16x16x32_bf16 v[32:35], v[178:181], v[200:203], v[32:35]
	v_mfma_f32_16x16x32_bf16 v[20:23], v[170:173], v[208:211], v[20:23]
	v_mfma_f32_16x16x32_bf16 v[16:19], v[178:181], v[208:211], v[16:19]
	v_mfma_f32_16x16x32_bf16 v[4:7], v[170:173], v[216:219], v[4:7]
	v_mfma_f32_16x16x32_bf16 v[0:3], v[178:181], v[216:219], v[0:3]
	s_barrier
	s_add_i32 s21, 0, 0x18000
	s_add_i32 s77, 0, 0x1c000
	v_add_u32_e32 v162, s21, v146
	v_add_u32_e32 v178, s77, v146
	ds_read_b128 v[150:153], v162
	ds_read_b128 v[154:157], v162 offset:1024
	ds_read_b128 v[158:161], v162 offset:2048
	ds_read_b128 v[162:165], v162 offset:3072
	ds_read_b128 v[166:169], v178
	ds_read_b128 v[170:173], v178 offset:1024
	ds_read_b128 v[174:177], v178 offset:2048
	ds_read_b128 v[178:181], v178 offset:3072
	s_add_u32 s56, s56, 0x8000
	s_addc_u32 s57, s57, 0
	s_mov_b32 m0, s60
	v_lshl_add_u64 v[226:227], s[56:57], 0, v[128:129]
	ds_read_b128 v[188:191], v149 offset:32768
	ds_read_b128 v[192:195], v149 offset:33792
	ds_read_b128 v[196:199], v149 offset:34816
	ds_read_b128 v[200:203], v149 offset:35840
	ds_read_b128 v[204:207], v149 offset:36864
	ds_read_b128 v[208:211], v149 offset:37888
	ds_read_b128 v[212:215], v149 offset:38912
	ds_read_b128 v[216:219], v149 offset:39936
	global_load_lds_dwordx4 v[226:227], off
	v_lshl_add_u64 v[226:227], s[56:57], 0, v[132:133]
	s_mov_b32 m0, s61
	s_nop 0
	global_load_lds_dwordx4 v[226:227], off
	s_waitcnt vmcnt(8)
	s_waitcnt lgkmcnt(0)
	s_barrier
	s_waitcnt lgkmcnt(0)
	v_mfma_f32_16x16x32_bf16 v[120:123], v[150:153], v[188:191], v[120:123]
	v_mfma_f32_16x16x32_bf16 v[124:127], v[158:161], v[188:191], v[124:127]
	v_mfma_f32_16x16x32_bf16 v[108:111], v[150:153], v[196:199], v[108:111]
	v_mfma_f32_16x16x32_bf16 v[104:107], v[158:161], v[196:199], v[104:107]
	v_mfma_f32_16x16x32_bf16 v[92:95], v[150:153], v[204:207], v[92:95]
	v_mfma_f32_16x16x32_bf16 v[88:91], v[158:161], v[204:207], v[88:91]
	v_mfma_f32_16x16x32_bf16 v[76:79], v[150:153], v[212:215], v[76:79]
	v_mfma_f32_16x16x32_bf16 v[72:75], v[158:161], v[212:215], v[72:75]
	v_mfma_f32_16x16x32_bf16 v[120:123], v[154:157], v[192:195], v[120:123]
	v_mfma_f32_16x16x32_bf16 v[124:127], v[162:165], v[192:195], v[124:127]
	v_mfma_f32_16x16x32_bf16 v[108:111], v[154:157], v[200:203], v[108:111]
	v_mfma_f32_16x16x32_bf16 v[104:107], v[162:165], v[200:203], v[104:107]
	v_mfma_f32_16x16x32_bf16 v[92:95], v[154:157], v[208:211], v[92:95]
	v_mfma_f32_16x16x32_bf16 v[88:91], v[162:165], v[208:211], v[88:91]
	v_mfma_f32_16x16x32_bf16 v[76:79], v[154:157], v[216:219], v[76:79]
	v_mfma_f32_16x16x32_bf16 v[72:75], v[162:165], v[216:219], v[72:75]
	v_mfma_f32_16x16x32_bf16 v[116:119], v[166:169], v[188:191], v[116:119]
	v_mfma_f32_16x16x32_bf16 v[112:115], v[174:177], v[188:191], v[112:115]
	v_mfma_f32_16x16x32_bf16 v[100:103], v[166:169], v[196:199], v[100:103]
	v_mfma_f32_16x16x32_bf16 v[96:99], v[174:177], v[196:199], v[96:99]
	v_mfma_f32_16x16x32_bf16 v[84:87], v[166:169], v[204:207], v[84:87]
	v_mfma_f32_16x16x32_bf16 v[80:83], v[174:177], v[204:207], v[80:83]
	v_mfma_f32_16x16x32_bf16 v[68:71], v[166:169], v[212:215], v[68:71]
	v_mfma_f32_16x16x32_bf16 v[64:67], v[174:177], v[212:215], v[64:67]
	v_mfma_f32_16x16x32_bf16 v[116:119], v[170:173], v[192:195], v[116:119]
	v_mfma_f32_16x16x32_bf16 v[112:115], v[178:181], v[192:195], v[112:115]
	v_mfma_f32_16x16x32_bf16 v[100:103], v[170:173], v[200:203], v[100:103]
	v_mfma_f32_16x16x32_bf16 v[96:99], v[178:181], v[200:203], v[96:99]
	v_mfma_f32_16x16x32_bf16 v[84:87], v[170:173], v[208:211], v[84:87]
	v_mfma_f32_16x16x32_bf16 v[80:83], v[178:181], v[208:211], v[80:83]
	v_mfma_f32_16x16x32_bf16 v[68:71], v[170:173], v[216:219], v[68:71]
	v_mfma_f32_16x16x32_bf16 v[64:67], v[178:181], v[216:219], v[64:67]
	s_barrier
; #define PG8_STAGE(bufoff, gbase, voff) do { _Pragma("unroll") for (int _i = 0; _i < 2; ++_i) \
;         __builtin_amdgcn_global_load_lds((const GAS unsigned*)((const char*)(gbase) + (voff)[_i]), (LAS unsigned*)(lds + (bufoff) + ldsw + _i * 8192), 16, 0, 0); } while (0)
; #define PG8_LDA(dst, b, h) do { _Pragma("unroll") for (int m = 0; m < 4; ++m) _Pragma("unroll") for (int k = 0; k < 2; ++k) dst[m][k] = *(const LAS bf16x8*)(lds + PG8_SA(b, h) + aoff + m * 2048 + k * 1024); } while (0)
; #define PG8_MMA(ai, bj, At, Bt) do { __builtin_amdgcn_s_setprio(1); _Pragma("unroll") for (int m = 0; m < 4; ++m) _Pragma("unroll") for (int n = 0; n < 2; ++n) _Pragma("unroll") for (int k = 0; k < 2; ++k) \
;         acc[ai][bj][m][n] = __builtin_amdgcn_mfma_f32_16x16x32_bf16(Bt[n][k], At[m][k], acc[ai][bj][m][n], 0, 0, 0); __builtin_amdgcn_s_setprio(0); } while (0)
; #define PG8_WAIT_V(n) asm volatile("s_waitcnt vmcnt(" #n ")" ::: "memory")
; #define PG8_WAIT_L(n) asm volatile("s_waitcnt lgkmcnt(" #n ")" ::: "memory")
; #define PG8_BAR __builtin_amdgcn_s_barrier()
; #define PG8_SCHED __builtin_amdgcn_sched_barrier(0)
; template <class Epi, class Sched>
; __device__ __forceinline__ void gemm_phase(LAS unsigned char* lds, const Gemm g, const Sched& S, const Epi& E, const int wave_) {
;     ...
;         for (int t = 0; t < nt; t += 2) {
;     ...
;             PG8_LDA(At, 1, 1); PG8_STAGE(PG8_SB(1, 0), b3, voffB); PG8_STAGE(PG8_SB(1, 1), b3 + hstepB, voffB); PG8_STAGE(PG8_SA(1, 0), a3, voffA);
;             PG8_WAIT_V(8); PG8_WAIT_L(0); PG8_BAR; PG8_MMA(1, 0, At, B0); PG8_MMA(1, 1, At, B1); PG8_BAR; PG8_SCHED;
	s_add_i32 s21, s21, s83
	v_lshl_add_u64 v[182:183], v[182:183], 0, s[30:31]
	s_mov_b32 m0, s21
	ds_read_b128 v[188:191], v149 offset:49152
	ds_read_b128 v[192:195], v149 offset:50176
	ds_read_b128 v[196:199], v149 offset:51200
	ds_read_b128 v[200:203], v149 offset:52224
	ds_read_b128 v[204:207], v149 offset:53248
	ds_read_b128 v[208:211], v149 offset:54272
	ds_read_b128 v[212:215], v149 offset:55296
	ds_read_b128 v[216:219], v149 offset:56320
	global_load_lds_dwordx4 v[182:183], off
	s_add_i32 m0, s21, 0x2000
	s_add_u32 s54, s54, 0x8080
	v_lshl_add_u64 v[182:183], v[220:221], 0, s[30:31]
	s_addc_u32 s55, s55, 0
	s_add_i32 s21, s77, s83
	global_load_lds_dwordx4 v[182:183], off
	v_lshl_add_u64 v[182:183], s[54:55], 0, v[130:131]
	s_mov_b32 m0, s21
	s_nop 0
	global_load_lds_dwordx4 v[182:183], off
	v_lshl_add_u64 v[182:183], s[54:55], 0, v[134:135]
	s_add_i32 m0, s21, 0x2000
	s_nop 0
	global_load_lds_dwordx4 v[182:183], off
	v_lshl_add_u64 v[182:183], v[222:223], 0, s[30:31]
	s_mov_b32 m0, s64
	s_nop 0
	global_load_lds_dwordx4 v[182:183], off
	v_lshl_add_u64 v[182:183], v[224:225], 0, s[30:31]
	s_mov_b32 m0, s65
	s_nop 0
	global_load_lds_dwordx4 v[182:183], off
	s_waitcnt vmcnt(8)
	s_waitcnt lgkmcnt(0)
	s_barrier
	s_waitcnt lgkmcnt(0)
	v_mfma_f32_16x16x32_bf16 v[60:63], v[150:153], v[188:191], v[60:63]
	v_mfma_f32_16x16x32_bf16 v[56:59], v[158:161], v[188:191], v[56:59]
	v_mfma_f32_16x16x32_bf16 v[44:47], v[150:153], v[196:199], v[44:47]
	v_mfma_f32_16x16x32_bf16 v[40:43], v[158:161], v[196:199], v[40:43]
	v_mfma_f32_16x16x32_bf16 v[28:31], v[150:153], v[204:207], v[28:31]
	v_mfma_f32_16x16x32_bf16 v[24:27], v[158:161], v[204:207], v[24:27]
	v_mfma_f32_16x16x32_bf16 v[12:15], v[150:153], v[212:215], v[12:15]
	v_mfma_f32_16x16x32_bf16 v[8:11], v[158:161], v[212:215], v[8:11]
	v_mfma_f32_16x16x32_bf16 v[60:63], v[154:157], v[192:195], v[60:63]
	v_mfma_f32_16x16x32_bf16 v[56:59], v[162:165], v[192:195], v[56:59]
	v_mfma_f32_16x16x32_bf16 v[44:47], v[154:157], v[200:203], v[44:47]
	v_mfma_f32_16x16x32_bf16 v[40:43], v[162:165], v[200:203], v[40:43]
	v_mfma_f32_16x16x32_bf16 v[28:31], v[154:157], v[208:211], v[28:31]
	v_mfma_f32_16x16x32_bf16 v[24:27], v[162:165], v[208:211], v[24:27]
	v_mfma_f32_16x16x32_bf16 v[12:15], v[154:157], v[216:219], v[12:15]
	v_mfma_f32_16x16x32_bf16 v[8:11], v[162:165], v[216:219], v[8:11]
	v_mfma_f32_16x16x32_bf16 v[52:55], v[166:169], v[188:191], v[52:55]
	v_mfma_f32_16x16x32_bf16 v[48:51], v[174:177], v[188:191], v[48:51]
	v_mfma_f32_16x16x32_bf16 v[36:39], v[166:169], v[196:199], v[36:39]
	v_mfma_f32_16x16x32_bf16 v[32:35], v[174:177], v[196:199], v[32:35]
	v_mfma_f32_16x16x32_bf16 v[20:23], v[166:169], v[204:207], v[20:23]
	v_mfma_f32_16x16x32_bf16 v[16:19], v[174:177], v[204:207], v[16:19]
	v_mfma_f32_16x16x32_bf16 v[4:7], v[166:169], v[212:215], v[4:7]
	v_mfma_f32_16x16x32_bf16 v[0:3], v[174:177], v[212:215], v[0:3]
	v_mfma_f32_16x16x32_bf16 v[52:55], v[170:173], v[192:195], v[52:55]
	v_mfma_f32_16x16x32_bf16 v[48:51], v[178:181], v[192:195], v[48:51]
	v_mfma_f32_16x16x32_bf16 v[36:39], v[170:173], v[200:203], v[36:39]
	v_mfma_f32_16x16x32_bf16 v[32:35], v[178:181], v[200:203], v[32:35]
	v_mfma_f32_16x16x32_bf16 v[20:23], v[170:173], v[208:211], v[20:23]
	v_mfma_f32_16x16x32_bf16 v[16:19], v[178:181], v[208:211], v[16:19]
	v_mfma_f32_16x16x32_bf16 v[4:7], v[170:173], v[216:219], v[4:7]
	v_mfma_f32_16x16x32_bf16 v[0:3], v[178:181], v[216:219], v[0:3]
	s_barrier
	s_add_u32 s74, s74, 0x100
	s_addc_u32 s75, s75, 0
	s_add_u32 s52, s52, 0x100
	s_addc_u32 s53, s53, 0
	s_cmp_ge_i32 s76, s63
	s_mov_b32 s54, s76
	s_cbranch_scc0 .LBB0_798

; #define PG8_STAGE(bufoff, gbase, voff) do { _Pragma("unroll") for (int _i = 0; _i < 2; ++_i) \
;         __builtin_amdgcn_global_load_lds((const GAS unsigned*)((const char*)(gbase) + (voff)[_i]), (LAS unsigned*)(lds + (bufoff) + ldsw + _i * 8192), 16, 0, 0); } while (0)
; #define PG8_LDA(dst, b, h) do { _Pragma("unroll") for (int m = 0; m < 4; ++m) _Pragma("unroll") for (int k = 0; k < 2; ++k) dst[m][k] = *(const LAS bf16x8*)(lds + PG8_SA(b, h) + aoff + m * 2048 + k * 1024); } while (0)
; #define PG8_LDB(dst, b, h) do { _Pragma("unroll") for (int n = 0; n < 2; ++n) _Pragma("unroll") for (int k = 0; k < 2; ++k) dst[n][k] = *(const LAS bf16x8*)(lds + PG8_SB(b, h) + boff + n * 2048 + k * 1024); } while (0)
; #define PG8_MMA(ai, bj, At, Bt) do { __builtin_amdgcn_s_setprio(1); _Pragma("unroll") for (int m = 0; m < 4; ++m) _Pragma("unroll") for (int n = 0; n < 2; ++n) _Pragma("unroll") for (int k = 0; k < 2; ++k) \
;         acc[ai][bj][m][n] = __builtin_amdgcn_mfma_f32_16x16x32_bf16(Bt[n][k], At[m][k], acc[ai][bj][m][n], 0, 0, 0); __builtin_amdgcn_s_setprio(0); } while (0)
; #define PG8_WAIT_V(n) asm volatile("s_waitcnt vmcnt(" #n ")" ::: "memory")
; #define PG8_WAIT_L(n) asm volatile("s_waitcnt lgkmcnt(" #n ")" ::: "memory")
; #define PG8_BAR __builtin_amdgcn_s_barrier()
; #define PG8_SCHED __builtin_amdgcn_sched_barrier(0)
; template <class Epi, class Sched>
; __device__ __forceinline__ void gemm_phase(LAS unsigned char* lds, const Gemm g, const Sched& S, const Epi& E, const int wave_) {
;     ...
;             const bool last = (t == nt - 2);
;             const char* a1 = cA + (size_t)(t + 1) * kstep;
;             const char* a2 = last ? nA : cA + (size_t)(t + 2) * kstep; const char* b2 = last ? nB : cB + (size_t)(t + 2) * kstep;
;             const char* a3 = a2 + kstep; const char* b3 = b2 + kstep;
;             PG8_LDB(B0, 0, 0); PG8_LDB(B1, 0, 1); PG8_SCHED; PG8_LDA(At, 0, 0); PG8_STAGE(PG8_SA(1, 1), a1 + hstepA, voffA);
;             PG8_WAIT_V(8); PG8_WAIT_L(0); PG8_BAR; PG8_MMA(0, 0, At, B0); PG8_MMA(0, 1, At, B1); PG8_BAR; PG8_SCHED;
;             PG8_LDA(At, 0, 1); PG8_STAGE(PG8_SB(0, 0), b2, voffB); PG8_STAGE(PG8_SB(0, 1), b2 + hstepB, voffB); PG8_STAGE(PG8_SA(0, 0), a2, voffA);
;             PG8_WAIT_V(8); PG8_WAIT_L(0); PG8_BAR; PG8_MMA(1, 0, At, B0); PG8_MMA(1, 1, At, B1); PG8_BAR; PG8_SCHED;
.LBB0_948:
	ds_read_b128 v[144:147], v157
	ds_read_b128 v[148:151], v157 offset:1024
	ds_read_b128 v[160:163], v157 offset:2048
	ds_read_b128 v[164:167], v157 offset:3072
	ds_read_b128 v[168:171], v158
	ds_read_b128 v[172:175], v158 offset:1024
	ds_read_b128 v[176:179], v158 offset:2048
	ds_read_b128 v[180:183], v158 offset:3072
	s_add_i32 s77, s54, 2
	s_add_u32 s21, s52, 0xfffe0080
	s_addc_u32 s55, s53, -1
	s_cmp_eq_u32 s65, s54
	s_cselect_b32 s54, s74, s75
	s_cselect_b32 s57, s39, s55
	s_cselect_b32 s56, s41, s21
	s_cselect_b32 s55, s73, s76
	v_lshl_add_u64 v[152:153], s[52:53], 0, v[138:139]
	s_add_i32 m0, s51, 0xc000
	ds_read_b128 v[188:191], v159
	ds_read_b128 v[192:195], v159 offset:1024
	ds_read_b128 v[196:199], v159 offset:2048
	ds_read_b128 v[200:203], v159 offset:3072
	ds_read_b128 v[204:207], v159 offset:4096
	ds_read_b128 v[208:211], v159 offset:5120
	ds_read_b128 v[212:215], v159 offset:6144
	ds_read_b128 v[216:219], v159 offset:7168
	global_load_lds_dwordx4 v[152:153], off
	v_lshl_add_u64 v[152:153], s[52:53], 0, v[136:137]
	s_add_i32 m0, s51, 0xe000
	s_nop 0
	global_load_lds_dwordx4 v[152:153], off
	s_waitcnt vmcnt(8)
	s_waitcnt lgkmcnt(0)
	s_barrier
	s_waitcnt lgkmcnt(0)
	v_mfma_f32_16x16x32_bf16 v[120:123], v[144:147], v[188:191], v[120:123]
	v_mfma_f32_16x16x32_bf16 v[124:127], v[160:163], v[188:191], v[124:127]
	v_mfma_f32_16x16x32_bf16 v[108:111], v[144:147], v[196:199], v[108:111]
	v_mfma_f32_16x16x32_bf16 v[104:107], v[160:163], v[196:199], v[104:107]
	v_mfma_f32_16x16x32_bf16 v[92:95], v[144:147], v[204:207], v[92:95]
	v_mfma_f32_16x16x32_bf16 v[88:91], v[160:163], v[204:207], v[88:91]
	v_mfma_f32_16x16x32_bf16 v[76:79], v[144:147], v[212:215], v[76:79]
	v_mfma_f32_16x16x32_bf16 v[72:75], v[160:163], v[212:215], v[72:75]
	v_mfma_f32_16x16x32_bf16 v[120:123], v[148:151], v[192:195], v[120:123]
	v_mfma_f32_16x16x32_bf16 v[124:127], v[164:167], v[192:195], v[124:127]
	v_mfma_f32_16x16x32_bf16 v[108:111], v[148:151], v[200:203], v[108:111]
	v_mfma_f32_16x16x32_bf16 v[104:107], v[164:167], v[200:203], v[104:107]
	v_mfma_f32_16x16x32_bf16 v[92:95], v[148:151], v[208:211], v[92:95]
	v_mfma_f32_16x16x32_bf16 v[88:91], v[164:167], v[208:211], v[88:91]
	v_mfma_f32_16x16x32_bf16 v[76:79], v[148:151], v[216:219], v[76:79]
	v_mfma_f32_16x16x32_bf16 v[72:75], v[164:167], v[216:219], v[72:75]
	v_mfma_f32_16x16x32_bf16 v[116:119], v[168:171], v[188:191], v[116:119]
	v_mfma_f32_16x16x32_bf16 v[112:115], v[176:179], v[188:191], v[112:115]
	v_mfma_f32_16x16x32_bf16 v[100:103], v[168:171], v[196:199], v[100:103]
	v_mfma_f32_16x16x32_bf16 v[96:99], v[176:179], v[196:199], v[96:99]
	v_mfma_f32_16x16x32_bf16 v[84:87], v[168:171], v[204:207], v[84:87]
	v_mfma_f32_16x16x32_bf16 v[80:83], v[176:179], v[204:207], v[80:83]
	v_mfma_f32_16x16x32_bf16 v[68:71], v[168:171], v[212:215], v[68:71]
	v_mfma_f32_16x16x32_bf16 v[64:67], v[176:179], v[212:215], v[64:67]
	v_mfma_f32_16x16x32_bf16 v[116:119], v[172:175], v[192:195], v[116:119]
	v_mfma_f32_16x16x32_bf16 v[112:115], v[180:183], v[192:195], v[112:115]
	v_mfma_f32_16x16x32_bf16 v[100:103], v[172:175], v[200:203], v[100:103]
	v_mfma_f32_16x16x32_bf16 v[96:99], v[180:183], v[200:203], v[96:99]
	v_mfma_f32_16x16x32_bf16 v[84:87], v[172:175], v[208:211], v[84:87]
	v_mfma_f32_16x16x32_bf16 v[80:83], v[180:183], v[208:211], v[80:83]
	v_mfma_f32_16x16x32_bf16 v[68:71], v[172:175], v[216:219], v[68:71]
	v_mfma_f32_16x16x32_bf16 v[64:67], v[180:183], v[216:219], v[64:67]
	s_barrier
	s_add_i32 s21, s69, s83
	v_lshl_add_u64 v[152:153], s[54:55], 0, v[130:131]
	s_mov_b32 m0, s21
	ds_read_b128 v[188:191], v159 offset:16384
	ds_read_b128 v[192:195], v159 offset:17408
	ds_read_b128 v[196:199], v159 offset:18432
	ds_read_b128 v[200:203], v159 offset:19456
	ds_read_b128 v[204:207], v159 offset:20480
	ds_read_b128 v[208:211], v159 offset:21504
	ds_read_b128 v[212:215], v159 offset:22528
	ds_read_b128 v[216:219], v159 offset:23552
	global_load_lds_dwordx4 v[152:153], off
	s_add_i32 m0, s21, 0x2000
	s_add_u32 s88, s54, 0x20000
	v_lshl_add_u64 v[220:221], s[54:55], 0, v[134:135]
	s_addc_u32 s89, s55, 0
	s_add_i32 s21, s70, s83
	global_load_lds_dwordx4 v[220:221], off
	v_lshl_add_u64 v[222:223], s[88:89], 0, v[130:131]
	s_mov_b32 m0, s21
	v_lshl_add_u64 v[224:225], s[56:57], 0, v[132:133]
	global_load_lds_dwordx4 v[222:223], off
	v_lshl_add_u64 v[222:223], s[88:89], 0, v[134:135]
	s_add_i32 m0, s21, 0x2000
	s_nop 0
	global_load_lds_dwordx4 v[222:223], off
	v_lshl_add_u64 v[222:223], s[56:57], 0, v[128:129]
	s_mov_b32 m0, s51
	s_nop 0
	global_load_lds_dwordx4 v[222:223], off
	s_mov_b32 m0, s58
	s_nop 0
	global_load_lds_dwordx4 v[224:225], off
	s_waitcnt vmcnt(8)
	s_waitcnt lgkmcnt(0)
	s_barrier
; #define PG8_STAGE(bufoff, gbase, voff) do { _Pragma("unroll") for (int _i = 0; _i < 2; ++_i) \
;         __builtin_amdgcn_global_load_lds((const GAS unsigned*)((const char*)(gbase) + (voff)[_i]), (LAS unsigned*)(lds + (bufoff) + ldsw + _i * 8192), 16, 0, 0); } while (0)
; #define PG8_LDA(dst, b, h) do { _Pragma("unroll") for (int m = 0; m < 4; ++m) _Pragma("unroll") for (int k = 0; k < 2; ++k) dst[m][k] = *(const LAS bf16x8*)(lds + PG8_SA(b, h) + aoff + m * 2048 + k * 1024); } while (0)
; #define PG8_LDB(dst, b, h) do { _Pragma("unroll") for (int n = 0; n < 2; ++n) _Pragma("unroll") for (int k = 0; k < 2; ++k) dst[n][k] = *(const LAS bf16x8*)(lds + PG8_SB(b, h) + boff + n * 2048 + k * 1024); } while (0)
; #define PG8_MMA(ai, bj, At, Bt) do { __builtin_amdgcn_s_setprio(1); _Pragma("unroll") for (int m = 0; m < 4; ++m) _Pragma("unroll") for (int n = 0; n < 2; ++n) _Pragma("unroll") for (int k = 0; k < 2; ++k) \
;         acc[ai][bj][m][n] = __builtin_amdgcn_mfma_f32_16x16x32_bf16(Bt[n][k], At[m][k], acc[ai][bj][m][n], 0, 0, 0); __builtin_amdgcn_s_setprio(0); } while (0)
; #define PG8_WAIT_V(n) asm volatile("s_waitcnt vmcnt(" #n ")" ::: "memory")
; #define PG8_WAIT_L(n) asm volatile("s_waitcnt lgkmcnt(" #n ")" ::: "memory")
; #define PG8_BAR __builtin_amdgcn_s_barrier()
; #define PG8_SCHED __builtin_amdgcn_sched_barrier(0)
; template <class Epi, class Sched>
; __device__ __forceinline__ void gemm_phase(LAS unsigned char* lds, const Gemm g, const Sched& S, const Epi& E, const int wave_) {
;     ...
;             PG8_WAIT_V(8); PG8_WAIT_L(0); PG8_BAR; PG8_MMA(1, 0, At, B0); PG8_MMA(1, 1, At, B1); PG8_BAR; PG8_SCHED;
;             PG8_LDB(B0, 1, 0); PG8_LDB(B1, 1, 1); PG8_SCHED; PG8_LDA(At, 1, 0); PG8_STAGE(PG8_SA(0, 1), a2 + hstepA, voffA);
;             PG8_WAIT_V(8); PG8_WAIT_L(0); PG8_BAR; PG8_MMA(0, 0, At, B0); PG8_MMA(0, 1, At, B1); PG8_BAR; PG8_SCHED;
	s_waitcnt lgkmcnt(0)
	v_mfma_f32_16x16x32_bf16 v[60:63], v[144:147], v[188:191], v[60:63]
	v_mfma_f32_16x16x32_bf16 v[56:59], v[160:163], v[188:191], v[56:59]
	v_mfma_f32_16x16x32_bf16 v[44:47], v[144:147], v[196:199], v[44:47]
	v_mfma_f32_16x16x32_bf16 v[40:43], v[160:163], v[196:199], v[40:43]
	v_mfma_f32_16x16x32_bf16 v[28:31], v[144:147], v[204:207], v[28:31]
	v_mfma_f32_16x16x32_bf16 v[24:27], v[160:163], v[204:207], v[24:27]
	v_mfma_f32_16x16x32_bf16 v[12:15], v[144:147], v[212:215], v[12:15]
	v_mfma_f32_16x16x32_bf16 v[8:11], v[160:163], v[212:215], v[8:11]
	v_mfma_f32_16x16x32_bf16 v[60:63], v[148:151], v[192:195], v[60:63]
	v_mfma_f32_16x16x32_bf16 v[56:59], v[164:167], v[192:195], v[56:59]
	v_mfma_f32_16x16x32_bf16 v[44:47], v[148:151], v[200:203], v[44:47]
	v_mfma_f32_16x16x32_bf16 v[40:43], v[164:167], v[200:203], v[40:43]
	v_mfma_f32_16x16x32_bf16 v[28:31], v[148:151], v[208:211], v[28:31]
	v_mfma_f32_16x16x32_bf16 v[24:27], v[164:167], v[208:211], v[24:27]
	v_mfma_f32_16x16x32_bf16 v[12:15], v[148:151], v[216:219], v[12:15]
	v_mfma_f32_16x16x32_bf16 v[8:11], v[164:167], v[216:219], v[8:11]
	v_mfma_f32_16x16x32_bf16 v[52:55], v[168:171], v[188:191], v[52:55]
	v_mfma_f32_16x16x32_bf16 v[48:51], v[176:179], v[188:191], v[48:51]
	v_mfma_f32_16x16x32_bf16 v[36:39], v[168:171], v[196:199], v[36:39]
	v_mfma_f32_16x16x32_bf16 v[32:35], v[176:179], v[196:199], v[32:35]
	v_mfma_f32_16x16x32_bf16 v[20:23], v[168:171], v[204:207], v[20:23]
	v_mfma_f32_16x16x32_bf16 v[16:19], v[176:179], v[204:207], v[16:19]
	v_mfma_f32_16x16x32_bf16 v[4:7], v[168:171], v[212:215], v[4:7]
	v_mfma_f32_16x16x32_bf16 v[0:3], v[176:179], v[212:215], v[0:3]
	v_mfma_f32_16x16x32_bf16 v[52:55], v[172:175], v[192:195], v[52:55]
	v_mfma_f32_16x16x32_bf16 v[48:51], v[180:183], v[192:195], v[48:51]
	v_mfma_f32_16x16x32_bf16 v[36:39], v[172:175], v[200:203], v[36:39]
	v_mfma_f32_16x16x32_bf16 v[32:35], v[180:183], v[200:203], v[32:35]
	v_mfma_f32_16x16x32_bf16 v[20:23], v[172:175], v[208:211], v[20:23]
	v_mfma_f32_16x16x32_bf16 v[16:19], v[180:183], v[208:211], v[16:19]
	v_mfma_f32_16x16x32_bf16 v[4:7], v[172:175], v[216:219], v[4:7]
	v_mfma_f32_16x16x32_bf16 v[0:3], v[180:183], v[216:219], v[0:3]
	s_barrier
	s_add_i32 s21, 0, 0x18000
	s_add_i32 s78, 0, 0x1c000
	v_add_u32_e32 v164, s21, v155
	v_add_u32_e32 v180, s78, v155
	ds_read_b128 v[144:147], v164
	ds_read_b128 v[148:151], v164 offset:1024
	ds_read_b128 v[160:163], v164 offset:2048
	ds_read_b128 v[164:167], v164 offset:3072
	ds_read_b128 v[168:171], v180
	ds_read_b128 v[172:175], v180 offset:1024
	ds_read_b128 v[176:179], v180 offset:2048
	ds_read_b128 v[180:183], v180 offset:3072
	s_add_u32 s56, s56, 0x20000
	s_addc_u32 s57, s57, 0
	s_mov_b32 m0, s59
	v_lshl_add_u64 v[226:227], s[56:57], 0, v[128:129]
	ds_read_b128 v[188:191], v159 offset:32768
	ds_read_b128 v[192:195], v159 offset:33792
	ds_read_b128 v[196:199], v159 offset:34816
	ds_read_b128 v[200:203], v159 offset:35840
	ds_read_b128 v[204:207], v159 offset:36864
	ds_read_b128 v[208:211], v159 offset:37888
	ds_read_b128 v[212:215], v159 offset:38912
	ds_read_b128 v[216:219], v159 offset:39936
	global_load_lds_dwordx4 v[226:227], off
	v_lshl_add_u64 v[226:227], s[56:57], 0, v[132:133]
	s_mov_b32 m0, s60
	s_nop 0
	global_load_lds_dwordx4 v[226:227], off
	s_waitcnt vmcnt(8)
	s_waitcnt lgkmcnt(0)
	s_barrier
	s_waitcnt lgkmcnt(0)
	v_mfma_f32_16x16x32_bf16 v[120:123], v[144:147], v[188:191], v[120:123]
	v_mfma_f32_16x16x32_bf16 v[124:127], v[160:163], v[188:191], v[124:127]
	v_mfma_f32_16x16x32_bf16 v[108:111], v[144:147], v[196:199], v[108:111]
	v_mfma_f32_16x16x32_bf16 v[104:107], v[160:163], v[196:199], v[104:107]
	v_mfma_f32_16x16x32_bf16 v[92:95], v[144:147], v[204:207], v[92:95]
	v_mfma_f32_16x16x32_bf16 v[88:91], v[160:163], v[204:207], v[88:91]
	v_mfma_f32_16x16x32_bf16 v[76:79], v[144:147], v[212:215], v[76:79]
	v_mfma_f32_16x16x32_bf16 v[72:75], v[160:163], v[212:215], v[72:75]
	v_mfma_f32_16x16x32_bf16 v[120:123], v[148:151], v[192:195], v[120:123]
	v_mfma_f32_16x16x32_bf16 v[124:127], v[164:167], v[192:195], v[124:127]
	v_mfma_f32_16x16x32_bf16 v[108:111], v[148:151], v[200:203], v[108:111]
	v_mfma_f32_16x16x32_bf16 v[104:107], v[164:167], v[200:203], v[104:107]
	v_mfma_f32_16x16x32_bf16 v[92:95], v[148:151], v[208:211], v[92:95]
	v_mfma_f32_16x16x32_bf16 v[88:91], v[164:167], v[208:211], v[88:91]
	v_mfma_f32_16x16x32_bf16 v[76:79], v[148:151], v[216:219], v[76:79]
	v_mfma_f32_16x16x32_bf16 v[72:75], v[164:167], v[216:219], v[72:75]
	v_mfma_f32_16x16x32_bf16 v[116:119], v[168:171], v[188:191], v[116:119]
	v_mfma_f32_16x16x32_bf16 v[112:115], v[176:179], v[188:191], v[112:115]
	v_mfma_f32_16x16x32_bf16 v[100:103], v[168:171], v[196:199], v[100:103]
	v_mfma_f32_16x16x32_bf16 v[96:99], v[176:179], v[196:199], v[96:99]
	v_mfma_f32_16x16x32_bf16 v[84:87], v[168:171], v[204:207], v[84:87]
	v_mfma_f32_16x16x32_bf16 v[80:83], v[176:179], v[204:207], v[80:83]
	v_mfma_f32_16x16x32_bf16 v[68:71], v[168:171], v[212:215], v[68:71]
	v_mfma_f32_16x16x32_bf16 v[64:67], v[176:179], v[212:215], v[64:67]
	v_mfma_f32_16x16x32_bf16 v[116:119], v[172:175], v[192:195], v[116:119]
	v_mfma_f32_16x16x32_bf16 v[112:115], v[180:183], v[192:195], v[112:115]
	v_mfma_f32_16x16x32_bf16 v[100:103], v[172:175], v[200:203], v[100:103]
	v_mfma_f32_16x16x32_bf16 v[96:99], v[180:183], v[200:203], v[96:99]
	v_mfma_f32_16x16x32_bf16 v[84:87], v[172:175], v[208:211], v[84:87]
	v_mfma_f32_16x16x32_bf16 v[80:83], v[180:183], v[208:211], v[80:83]
	v_mfma_f32_16x16x32_bf16 v[68:71], v[172:175], v[216:219], v[68:71]
	v_mfma_f32_16x16x32_bf16 v[64:67], v[180:183], v[216:219], v[64:67]
	s_barrier
; #define PG8_STAGE(bufoff, gbase, voff) do { _Pragma("unroll") for (int _i = 0; _i < 2; ++_i) \
;         __builtin_amdgcn_global_load_lds((const GAS unsigned*)((const char*)(gbase) + (voff)[_i]), (LAS unsigned*)(lds + (bufoff) + ldsw + _i * 8192), 16, 0, 0); } while (0)
; #define PG8_LDA(dst, b, h) do { _Pragma("unroll") for (int m = 0; m < 4; ++m) _Pragma("unroll") for (int k = 0; k < 2; ++k) dst[m][k] = *(const LAS bf16x8*)(lds + PG8_SA(b, h) + aoff + m * 2048 + k * 1024); } while (0)
; #define PG8_MMA(ai, bj, At, Bt) do { __builtin_amdgcn_s_setprio(1); _Pragma("unroll") for (int m = 0; m < 4; ++m) _Pragma("unroll") for (int n = 0; n < 2; ++n) _Pragma("unroll") for (int k = 0; k < 2; ++k) \
;         acc[ai][bj][m][n] = __builtin_amdgcn_mfma_f32_16x16x32_bf16(Bt[n][k], At[m][k], acc[ai][bj][m][n], 0, 0, 0); __builtin_amdgcn_s_setprio(0); } while (0)
; #define PG8_WAIT_V(n) asm volatile("s_waitcnt vmcnt(" #n ")" ::: "memory")
; #define PG8_WAIT_L(n) asm volatile("s_waitcnt lgkmcnt(" #n ")" ::: "memory")
; #define PG8_BAR __builtin_amdgcn_s_barrier()
; #define PG8_SCHED __builtin_amdgcn_sched_barrier(0)
; template <class Epi, class Sched>
; __device__ __forceinline__ void gemm_phase(LAS unsigned char* lds, const Gemm g, const Sched& S, const Epi& E, const int wave_) {
;     ...
;         for (int t = 0; t < nt; t += 2) {
;     ...
;             PG8_LDA(At, 1, 1); PG8_STAGE(PG8_SB(1, 0), b3, voffB); PG8_STAGE(PG8_SB(1, 1), b3 + hstepB, voffB); PG8_STAGE(PG8_SA(1, 0), a3, voffA);
;             PG8_WAIT_V(8); PG8_WAIT_L(0); PG8_BAR; PG8_MMA(1, 0, At, B0); PG8_MMA(1, 1, At, B1); PG8_BAR; PG8_SCHED;
	s_add_i32 s21, s21, s83
	v_lshl_add_u64 v[152:153], v[152:153], 0, s[30:31]
	s_mov_b32 m0, s21
	ds_read_b128 v[188:191], v159 offset:49152
	ds_read_b128 v[192:195], v159 offset:50176
	ds_read_b128 v[196:199], v159 offset:51200
	ds_read_b128 v[200:203], v159 offset:52224
	ds_read_b128 v[204:207], v159 offset:53248
	ds_read_b128 v[208:211], v159 offset:54272
	ds_read_b128 v[212:215], v159 offset:55296
	ds_read_b128 v[216:219], v159 offset:56320
	global_load_lds_dwordx4 v[152:153], off
	s_add_i32 m0, s21, 0x2000
	s_add_u32 s54, s54, 0x20080
	v_lshl_add_u64 v[152:153], v[220:221], 0, s[30:31]
	s_addc_u32 s55, s55, 0
	s_add_i32 s21, s78, s83
	global_load_lds_dwordx4 v[152:153], off
	v_lshl_add_u64 v[152:153], s[54:55], 0, v[130:131]
	s_mov_b32 m0, s21
	s_nop 0
	global_load_lds_dwordx4 v[152:153], off
	v_lshl_add_u64 v[152:153], s[54:55], 0, v[134:135]
	s_add_i32 m0, s21, 0x2000
	s_nop 0
	global_load_lds_dwordx4 v[152:153], off
	v_lshl_add_u64 v[152:153], v[222:223], 0, s[30:31]
	s_mov_b32 m0, s63
	s_nop 0
	global_load_lds_dwordx4 v[152:153], off
	v_lshl_add_u64 v[152:153], v[224:225], 0, s[30:31]
	s_mov_b32 m0, s64
	s_nop 0
	global_load_lds_dwordx4 v[152:153], off
	s_waitcnt vmcnt(8)
	s_waitcnt lgkmcnt(0)
	s_barrier
	s_waitcnt lgkmcnt(0)
	v_mfma_f32_16x16x32_bf16 v[60:63], v[144:147], v[188:191], v[60:63]
	v_mfma_f32_16x16x32_bf16 v[56:59], v[160:163], v[188:191], v[56:59]
	v_mfma_f32_16x16x32_bf16 v[44:47], v[144:147], v[196:199], v[44:47]
	v_mfma_f32_16x16x32_bf16 v[40:43], v[160:163], v[196:199], v[40:43]
	v_mfma_f32_16x16x32_bf16 v[28:31], v[144:147], v[204:207], v[28:31]
	v_mfma_f32_16x16x32_bf16 v[24:27], v[160:163], v[204:207], v[24:27]
	v_mfma_f32_16x16x32_bf16 v[12:15], v[144:147], v[212:215], v[12:15]
	v_mfma_f32_16x16x32_bf16 v[8:11], v[160:163], v[212:215], v[8:11]
	v_mfma_f32_16x16x32_bf16 v[60:63], v[148:151], v[192:195], v[60:63]
	v_mfma_f32_16x16x32_bf16 v[56:59], v[164:167], v[192:195], v[56:59]
	v_mfma_f32_16x16x32_bf16 v[44:47], v[148:151], v[200:203], v[44:47]
	v_mfma_f32_16x16x32_bf16 v[40:43], v[164:167], v[200:203], v[40:43]
	v_mfma_f32_16x16x32_bf16 v[28:31], v[148:151], v[208:211], v[28:31]
	v_mfma_f32_16x16x32_bf16 v[24:27], v[164:167], v[208:211], v[24:27]
	v_mfma_f32_16x16x32_bf16 v[12:15], v[148:151], v[216:219], v[12:15]
	v_mfma_f32_16x16x32_bf16 v[8:11], v[164:167], v[216:219], v[8:11]
	v_mfma_f32_16x16x32_bf16 v[52:55], v[168:171], v[188:191], v[52:55]
	v_mfma_f32_16x16x32_bf16 v[48:51], v[176:179], v[188:191], v[48:51]
	v_mfma_f32_16x16x32_bf16 v[36:39], v[168:171], v[196:199], v[36:39]
	v_mfma_f32_16x16x32_bf16 v[32:35], v[176:179], v[196:199], v[32:35]
	v_mfma_f32_16x16x32_bf16 v[20:23], v[168:171], v[204:207], v[20:23]
	v_mfma_f32_16x16x32_bf16 v[16:19], v[176:179], v[204:207], v[16:19]
	v_mfma_f32_16x16x32_bf16 v[4:7], v[168:171], v[212:215], v[4:7]
	v_mfma_f32_16x16x32_bf16 v[0:3], v[176:179], v[212:215], v[0:3]
	v_mfma_f32_16x16x32_bf16 v[52:55], v[172:175], v[192:195], v[52:55]
	v_mfma_f32_16x16x32_bf16 v[48:51], v[180:183], v[192:195], v[48:51]
	v_mfma_f32_16x16x32_bf16 v[36:39], v[172:175], v[200:203], v[36:39]
	v_mfma_f32_16x16x32_bf16 v[32:35], v[180:183], v[200:203], v[32:35]
	v_mfma_f32_16x16x32_bf16 v[20:23], v[172:175], v[208:211], v[20:23]
	v_mfma_f32_16x16x32_bf16 v[16:19], v[180:183], v[208:211], v[16:19]
	v_mfma_f32_16x16x32_bf16 v[4:7], v[172:175], v[216:219], v[4:7]
	v_mfma_f32_16x16x32_bf16 v[0:3], v[180:183], v[216:219], v[0:3]
	s_barrier
	s_add_u32 s75, s75, 0x100
	s_addc_u32 s76, s76, 0
	s_add_u32 s52, s52, 0x100
	s_addc_u32 s53, s53, 0
	s_cmp_ge_i32 s77, s62
	s_mov_b32 s54, s77
	s_cbranch_scc0 .LBB0_948

; #define PG8_STAGE(bufoff, gbase, voff) do { _Pragma("unroll") for (int _i = 0; _i < 2; ++_i) \
;         __builtin_amdgcn_global_load_lds((const GAS unsigned*)((const char*)(gbase) + (voff)[_i]), (LAS unsigned*)(lds + (bufoff) + ldsw + _i * 8192), 16, 0, 0); } while (0)
; #define PG8_LDA(dst, b, h) do { _Pragma("unroll") for (int m = 0; m < 4; ++m) _Pragma("unroll") for (int k = 0; k < 2; ++k) dst[m][k] = *(const LAS bf16x8*)(lds + PG8_SA(b, h) + aoff + m * 2048 + k * 1024); } while (0)
; #define PG8_WAIT_V(n) asm volatile("s_waitcnt vmcnt(" #n ")" ::: "memory")
; #define PG8_WAIT_L(n) asm volatile("s_waitcnt lgkmcnt(" #n ")" ::: "memory")
; #define PG8_BAR __builtin_amdgcn_s_barrier()
; template <class Epi, class Sched>
; __device__ __forceinline__ void gemm_phase(LAS unsigned char* lds, const Gemm g, const Sched& S, const Epi& E, const int wave_) {
;     ...
;         for (int t = 0; t < nt; t += 2) {
;             if constexpr (Epi::HOOK) { if (t == 8 || t == 16) { E.hook(acc, cur, t >> 3, wr, wc, fr, fq); PG8_WAIT_V(0); } }
;             const bool last = (t == nt - 2);
;             const char* a1 = cA + (size_t)(t + 1) * kstep;
;             const char* a2 = last ? nA : cA + (size_t)(t + 2) * kstep; const char* b2 = last ? nB : cB + (size_t)(t + 2) * kstep;
;             const char* a3 = a2 + kstep; const char* b3 = b2 + kstep;
;             PG8_LDB(B0, 0, 0); PG8_LDB(B1, 0, 1); PG8_SCHED; PG8_LDA(At, 0, 0); PG8_STAGE(PG8_SA(1, 1), a1 + hstepA, voffA);
;             PG8_WAIT_V(8); PG8_WAIT_L(0); PG8_BAR; PG8_MMA(0, 0, At, B0); PG8_MMA(0, 1, At, B1); PG8_BAR; PG8_SCHED;
;             PG8_LDA(At, 0, 1); PG8_STAGE(PG8_SB(0, 0), b2, voffB); PG8_STAGE(PG8_SB(0, 1), b2 + hstepB, voffB); PG8_STAGE(PG8_SA(0, 0), a2, voffA);
;             PG8_WAIT_V(8); PG8_WAIT_L(0); PG8_BAR; PG8_MMA(1, 0, At, B0); PG8_MMA(1, 1, At, B1); PG8_BAR; PG8_SCHED;
;             PG8_LDB(B0, 1, 0); PG8_LDB(B1, 1, 1); PG8_SCHED; PG8_LDA(At, 1, 0); PG8_STAGE(PG8_SA(0, 1), a2 + hstepA, voffA);
;             PG8_WAIT_V(8); PG8_WAIT_L(0); PG8_BAR; PG8_MMA(0, 0, At, B0); PG8_MMA(0, 1, At, B1); PG8_BAR; PG8_SCHED;
;             PG8_LDA(At, 1, 1); PG8_STAGE(PG8_SB(1, 0), b3, voffB); PG8_STAGE(PG8_SB(1, 1), b3 + hstepB, voffB); PG8_STAGE(PG8_SA(1, 0), a3, voffA);
;             PG8_WAIT_V(8); PG8_WAIT_L(0); PG8_BAR; PG8_MMA(1, 0, At, B0); PG8_MMA(1, 1, At, B1); PG8_BAR; PG8_SCHED;
;         }
.LBB0_1029:
	s_add_i32 s95, s56, 2
	s_add_u32 s52, s50, 0x100
	s_addc_u32 s53, s51, 0
	s_cmp_eq_u32 s67, s56
	s_cselect_b32 s57, s89, s53
	s_cselect_b32 s56, s90, s52
	s_cselect_b32 s55, s91, s94
	s_cselect_b32 s54, s92, s93
	s_add_i32 s21, 0, 0x14000
	v_add_u32_e32 v140, s77, v189
	v_add_u32_e32 v156, s21, v189
	ds_read_b128 v[128:131], v140
	ds_read_b128 v[132:135], v140 offset:1024
	ds_read_b128 v[136:139], v140 offset:2048
	ds_read_b128 v[140:143], v140 offset:3072
	ds_read_b128 v[144:147], v156
	ds_read_b128 v[148:151], v156 offset:1024
	ds_read_b128 v[152:155], v156 offset:2048
	ds_read_b128 v[156:159], v156 offset:3072
	v_lshl_add_u64 v[222:223], s[50:51], 0, v[174:175]
	s_add_i32 m0, s58, 0xc000
	ds_read_b128 v[160:163], v192
	ds_read_b128 v[194:197], v192 offset:1024
	ds_read_b128 v[198:201], v192 offset:2048
	ds_read_b128 v[202:205], v192 offset:3072
	ds_read_b128 v[206:209], v192 offset:4096
	ds_read_b128 v[210:213], v192 offset:5120
	ds_read_b128 v[214:217], v192 offset:6144
	ds_read_b128 v[218:221], v192 offset:7168
	global_load_lds_dwordx4 v[222:223], off
	v_lshl_add_u64 v[222:223], s[50:51], 0, v[172:173]
	s_add_i32 m0, s58, 0xe000
	s_nop 0
	global_load_lds_dwordx4 v[222:223], off
	s_waitcnt vmcnt(8)
	s_waitcnt lgkmcnt(0)
	s_barrier
	s_waitcnt lgkmcnt(0)
	v_mfma_f32_16x16x32_bf16 v[120:123], v[128:131], v[160:163], v[120:123]
	v_mfma_f32_16x16x32_bf16 v[124:127], v[136:139], v[160:163], v[124:127]
	v_mfma_f32_16x16x32_bf16 v[108:111], v[128:131], v[198:201], v[108:111]
	v_mfma_f32_16x16x32_bf16 v[104:107], v[136:139], v[198:201], v[104:107]
	v_mfma_f32_16x16x32_bf16 v[92:95], v[128:131], v[206:209], v[92:95]
	v_mfma_f32_16x16x32_bf16 v[88:91], v[136:139], v[206:209], v[88:91]
	v_mfma_f32_16x16x32_bf16 v[76:79], v[128:131], v[214:217], v[76:79]
	v_mfma_f32_16x16x32_bf16 v[72:75], v[136:139], v[214:217], v[72:75]
	v_mfma_f32_16x16x32_bf16 v[120:123], v[132:135], v[194:197], v[120:123]
	v_mfma_f32_16x16x32_bf16 v[124:127], v[140:143], v[194:197], v[124:127]
	v_mfma_f32_16x16x32_bf16 v[108:111], v[132:135], v[202:205], v[108:111]
	v_mfma_f32_16x16x32_bf16 v[104:107], v[140:143], v[202:205], v[104:107]
	v_mfma_f32_16x16x32_bf16 v[92:95], v[132:135], v[210:213], v[92:95]
	v_mfma_f32_16x16x32_bf16 v[88:91], v[140:143], v[210:213], v[88:91]
	v_mfma_f32_16x16x32_bf16 v[76:79], v[132:135], v[218:221], v[76:79]
	v_mfma_f32_16x16x32_bf16 v[72:75], v[140:143], v[218:221], v[72:75]
	v_mfma_f32_16x16x32_bf16 v[116:119], v[144:147], v[160:163], v[116:119]
	v_mfma_f32_16x16x32_bf16 v[112:115], v[152:155], v[160:163], v[112:115]
	v_mfma_f32_16x16x32_bf16 v[100:103], v[144:147], v[198:201], v[100:103]
	v_mfma_f32_16x16x32_bf16 v[96:99], v[152:155], v[198:201], v[96:99]
	v_mfma_f32_16x16x32_bf16 v[84:87], v[144:147], v[206:209], v[84:87]
	v_mfma_f32_16x16x32_bf16 v[80:83], v[152:155], v[206:209], v[80:83]
	v_mfma_f32_16x16x32_bf16 v[68:71], v[144:147], v[214:217], v[68:71]
	v_mfma_f32_16x16x32_bf16 v[64:67], v[152:155], v[214:217], v[64:67]
	v_mfma_f32_16x16x32_bf16 v[116:119], v[148:151], v[194:197], v[116:119]
	v_mfma_f32_16x16x32_bf16 v[112:115], v[156:159], v[194:197], v[112:115]
	v_mfma_f32_16x16x32_bf16 v[100:103], v[148:151], v[202:205], v[100:103]
	v_mfma_f32_16x16x32_bf16 v[96:99], v[156:159], v[202:205], v[96:99]
	v_mfma_f32_16x16x32_bf16 v[84:87], v[148:151], v[210:213], v[84:87]
	v_mfma_f32_16x16x32_bf16 v[80:83], v[156:159], v[210:213], v[80:83]
	v_mfma_f32_16x16x32_bf16 v[68:71], v[148:151], v[218:221], v[68:71]
	v_mfma_f32_16x16x32_bf16 v[64:67], v[156:159], v[218:221], v[64:67]
	s_barrier
	s_add_i32 s50, s77, s83
	v_lshl_add_u64 v[222:223], s[54:55], 0, v[166:167]
	s_mov_b32 m0, s50
	ds_read_b128 v[160:163], v192 offset:16384
	ds_read_b128 v[194:197], v192 offset:17408
	ds_read_b128 v[198:201], v192 offset:18432
	ds_read_b128 v[202:205], v192 offset:19456
	ds_read_b128 v[206:209], v192 offset:20480
	ds_read_b128 v[210:213], v192 offset:21504
	ds_read_b128 v[214:217], v192 offset:22528
	ds_read_b128 v[218:221], v192 offset:23552
	global_load_lds_dwordx4 v[222:223], off
	s_add_i32 m0, s50, 0x2000
	s_add_u32 s50, s54, 0x60000
	v_lshl_add_u64 v[224:225], s[54:55], 0, v[170:171]
	s_addc_u32 s51, s55, 0
	s_add_i32 s21, s21, s83
	global_load_lds_dwordx4 v[224:225], off
	v_lshl_add_u64 v[226:227], s[50:51], 0, v[166:167]
	s_mov_b32 m0, s21
	v_lshl_add_u64 v[228:229], s[56:57], 0, v[168:169]
	global_load_lds_dwordx4 v[226:227], off
	v_lshl_add_u64 v[226:227], s[50:51], 0, v[170:171]
	s_add_i32 m0, s21, 0x2000
	s_nop 0
	global_load_lds_dwordx4 v[226:227], off
	v_lshl_add_u64 v[226:227], s[56:57], 0, v[164:165]
	s_mov_b32 m0, s58
	s_nop 0
	global_load_lds_dwordx4 v[226:227], off
	s_mov_b32 m0, s59
	s_nop 0
	global_load_lds_dwordx4 v[228:229], off
	s_waitcnt vmcnt(8)
	s_waitcnt lgkmcnt(0)
	s_barrier
; #define PG8_STAGE(bufoff, gbase, voff) do { _Pragma("unroll") for (int _i = 0; _i < 2; ++_i) \
;         __builtin_amdgcn_global_load_lds((const GAS unsigned*)((const char*)(gbase) + (voff)[_i]), (LAS unsigned*)(lds + (bufoff) + ldsw + _i * 8192), 16, 0, 0); } while (0)
; #define PG8_LDA(dst, b, h) do { _Pragma("unroll") for (int m = 0; m < 4; ++m) _Pragma("unroll") for (int k = 0; k < 2; ++k) dst[m][k] = *(const LAS bf16x8*)(lds + PG8_SA(b, h) + aoff + m * 2048 + k * 1024); } while (0)
; #define PG8_WAIT_V(n) asm volatile("s_waitcnt vmcnt(" #n ")" ::: "memory")
; #define PG8_WAIT_L(n) asm volatile("s_waitcnt lgkmcnt(" #n ")" ::: "memory")
; #define PG8_BAR __builtin_amdgcn_s_barrier()
; template <class Epi, class Sched>
; __device__ __forceinline__ void gemm_phase(LAS unsigned char* lds, const Gemm g, const Sched& S, const Epi& E, const int wave_) {
;     ...
;         for (int t = 0; t < nt; t += 2) {
;             if constexpr (Epi::HOOK) { if (t == 8 || t == 16) { E.hook(acc, cur, t >> 3, wr, wc, fr, fq); PG8_WAIT_V(0); } }
;             const bool last = (t == nt - 2);
;             const char* a1 = cA + (size_t)(t + 1) * kstep;
;             const char* a2 = last ? nA : cA + (size_t)(t + 2) * kstep; const char* b2 = last ? nB : cB + (size_t)(t + 2) * kstep;
;             const char* a3 = a2 + kstep; const char* b3 = b2 + kstep;
;             PG8_LDB(B0, 0, 0); PG8_LDB(B1, 0, 1); PG8_SCHED; PG8_LDA(At, 0, 0); PG8_STAGE(PG8_SA(1, 1), a1 + hstepA, voffA);
;             PG8_WAIT_V(8); PG8_WAIT_L(0); PG8_BAR; PG8_MMA(0, 0, At, B0); PG8_MMA(0, 1, At, B1); PG8_BAR; PG8_SCHED;
;             PG8_LDA(At, 0, 1); PG8_STAGE(PG8_SB(0, 0), b2, voffB); PG8_STAGE(PG8_SB(0, 1), b2 + hstepB, voffB); PG8_STAGE(PG8_SA(0, 0), a2, voffA);
;             PG8_WAIT_V(8); PG8_WAIT_L(0); PG8_BAR; PG8_MMA(1, 0, At, B0); PG8_MMA(1, 1, At, B1); PG8_BAR; PG8_SCHED;
;             PG8_LDB(B0, 1, 0); PG8_LDB(B1, 1, 1); PG8_SCHED; PG8_LDA(At, 1, 0); PG8_STAGE(PG8_SA(0, 1), a2 + hstepA, voffA);
;             PG8_WAIT_V(8); PG8_WAIT_L(0); PG8_BAR; PG8_MMA(0, 0, At, B0); PG8_MMA(0, 1, At, B1); PG8_BAR; PG8_SCHED;
;             PG8_LDA(At, 1, 1); PG8_STAGE(PG8_SB(1, 0), b3, voffB); PG8_STAGE(PG8_SB(1, 1), b3 + hstepB, voffB); PG8_STAGE(PG8_SA(1, 0), a3, voffA);
;             PG8_WAIT_V(8); PG8_WAIT_L(0); PG8_BAR; PG8_MMA(1, 0, At, B0); PG8_MMA(1, 1, At, B1); PG8_BAR; PG8_SCHED;
;         }
	s_waitcnt lgkmcnt(0)
	v_mfma_f32_16x16x32_bf16 v[60:63], v[128:131], v[160:163], v[60:63]
	v_mfma_f32_16x16x32_bf16 v[56:59], v[136:139], v[160:163], v[56:59]
	v_mfma_f32_16x16x32_bf16 v[44:47], v[128:131], v[198:201], v[44:47]
	v_mfma_f32_16x16x32_bf16 v[40:43], v[136:139], v[198:201], v[40:43]
	v_mfma_f32_16x16x32_bf16 v[28:31], v[128:131], v[206:209], v[28:31]
	v_mfma_f32_16x16x32_bf16 v[24:27], v[136:139], v[206:209], v[24:27]
	v_mfma_f32_16x16x32_bf16 v[12:15], v[128:131], v[214:217], v[12:15]
	v_mfma_f32_16x16x32_bf16 v[8:11], v[136:139], v[214:217], v[8:11]
	v_mfma_f32_16x16x32_bf16 v[60:63], v[132:135], v[194:197], v[60:63]
	v_mfma_f32_16x16x32_bf16 v[56:59], v[140:143], v[194:197], v[56:59]
	v_mfma_f32_16x16x32_bf16 v[44:47], v[132:135], v[202:205], v[44:47]
	v_mfma_f32_16x16x32_bf16 v[40:43], v[140:143], v[202:205], v[40:43]
	v_mfma_f32_16x16x32_bf16 v[28:31], v[132:135], v[210:213], v[28:31]
	v_mfma_f32_16x16x32_bf16 v[24:27], v[140:143], v[210:213], v[24:27]
	v_mfma_f32_16x16x32_bf16 v[12:15], v[132:135], v[218:221], v[12:15]
	v_mfma_f32_16x16x32_bf16 v[8:11], v[140:143], v[218:221], v[8:11]
	v_mfma_f32_16x16x32_bf16 v[52:55], v[144:147], v[160:163], v[52:55]
	v_mfma_f32_16x16x32_bf16 v[48:51], v[152:155], v[160:163], v[48:51]
	v_mfma_f32_16x16x32_bf16 v[36:39], v[144:147], v[198:201], v[36:39]
	v_mfma_f32_16x16x32_bf16 v[32:35], v[152:155], v[198:201], v[32:35]
	v_mfma_f32_16x16x32_bf16 v[20:23], v[144:147], v[206:209], v[20:23]
	v_mfma_f32_16x16x32_bf16 v[16:19], v[152:155], v[206:209], v[16:19]
	v_mfma_f32_16x16x32_bf16 v[4:7], v[144:147], v[214:217], v[4:7]
	v_mfma_f32_16x16x32_bf16 v[0:3], v[152:155], v[214:217], v[0:3]
	v_mfma_f32_16x16x32_bf16 v[52:55], v[148:151], v[194:197], v[52:55]
	v_mfma_f32_16x16x32_bf16 v[48:51], v[156:159], v[194:197], v[48:51]
	v_mfma_f32_16x16x32_bf16 v[36:39], v[148:151], v[202:205], v[36:39]
	v_mfma_f32_16x16x32_bf16 v[32:35], v[156:159], v[202:205], v[32:35]
	v_mfma_f32_16x16x32_bf16 v[20:23], v[148:151], v[210:213], v[20:23]
	v_mfma_f32_16x16x32_bf16 v[16:19], v[156:159], v[210:213], v[16:19]
	v_mfma_f32_16x16x32_bf16 v[4:7], v[148:151], v[218:221], v[4:7]
	v_mfma_f32_16x16x32_bf16 v[0:3], v[156:159], v[218:221], v[0:3]
	s_barrier
	s_add_i32 s21, 0, 0x18000
	s_add_i32 s96, 0, 0x1c000
	v_add_u32_e32 v140, s21, v189
	v_add_u32_e32 v156, s96, v189
	ds_read_b128 v[128:131], v140
	ds_read_b128 v[132:135], v140 offset:1024
	ds_read_b128 v[136:139], v140 offset:2048
	ds_read_b128 v[140:143], v140 offset:3072
	ds_read_b128 v[144:147], v156
	ds_read_b128 v[148:151], v156 offset:1024
	ds_read_b128 v[152:155], v156 offset:2048
	ds_read_b128 v[156:159], v156 offset:3072
	s_add_u32 s50, s56, 0x140000
	s_addc_u32 s51, s57, 0
	s_mov_b32 m0, s60
	v_lshl_add_u64 v[230:231], s[50:51], 0, v[164:165]
	ds_read_b128 v[160:163], v192 offset:32768
	ds_read_b128 v[194:197], v192 offset:33792
	ds_read_b128 v[198:201], v192 offset:34816
	ds_read_b128 v[202:205], v192 offset:35840
	ds_read_b128 v[206:209], v192 offset:36864
	ds_read_b128 v[210:213], v192 offset:37888
	ds_read_b128 v[214:217], v192 offset:38912
	ds_read_b128 v[218:221], v192 offset:39936
	global_load_lds_dwordx4 v[230:231], off
	v_lshl_add_u64 v[230:231], s[50:51], 0, v[168:169]
	s_mov_b32 m0, s61
	s_nop 0
	global_load_lds_dwordx4 v[230:231], off
	s_waitcnt vmcnt(8)
	s_waitcnt lgkmcnt(0)
	s_barrier
	s_waitcnt lgkmcnt(0)
	v_mfma_f32_16x16x32_bf16 v[120:123], v[128:131], v[160:163], v[120:123]
	v_mfma_f32_16x16x32_bf16 v[124:127], v[136:139], v[160:163], v[124:127]
	v_mfma_f32_16x16x32_bf16 v[108:111], v[128:131], v[198:201], v[108:111]
	v_mfma_f32_16x16x32_bf16 v[104:107], v[136:139], v[198:201], v[104:107]
	v_mfma_f32_16x16x32_bf16 v[92:95], v[128:131], v[206:209], v[92:95]
	v_mfma_f32_16x16x32_bf16 v[88:91], v[136:139], v[206:209], v[88:91]
	v_mfma_f32_16x16x32_bf16 v[76:79], v[128:131], v[214:217], v[76:79]
	v_mfma_f32_16x16x32_bf16 v[72:75], v[136:139], v[214:217], v[72:75]
	v_mfma_f32_16x16x32_bf16 v[120:123], v[132:135], v[194:197], v[120:123]
	v_mfma_f32_16x16x32_bf16 v[124:127], v[140:143], v[194:197], v[124:127]
	v_mfma_f32_16x16x32_bf16 v[108:111], v[132:135], v[202:205], v[108:111]
	v_mfma_f32_16x16x32_bf16 v[104:107], v[140:143], v[202:205], v[104:107]
	v_mfma_f32_16x16x32_bf16 v[92:95], v[132:135], v[210:213], v[92:95]
	v_mfma_f32_16x16x32_bf16 v[88:91], v[140:143], v[210:213], v[88:91]
	v_mfma_f32_16x16x32_bf16 v[76:79], v[132:135], v[218:221], v[76:79]
	v_mfma_f32_16x16x32_bf16 v[72:75], v[140:143], v[218:221], v[72:75]
	v_mfma_f32_16x16x32_bf16 v[116:119], v[144:147], v[160:163], v[116:119]
	v_mfma_f32_16x16x32_bf16 v[112:115], v[152:155], v[160:163], v[112:115]
	v_mfma_f32_16x16x32_bf16 v[100:103], v[144:147], v[198:201], v[100:103]
	v_mfma_f32_16x16x32_bf16 v[96:99], v[152:155], v[198:201], v[96:99]
	v_mfma_f32_16x16x32_bf16 v[84:87], v[144:147], v[206:209], v[84:87]
	v_mfma_f32_16x16x32_bf16 v[80:83], v[152:155], v[206:209], v[80:83]
	v_mfma_f32_16x16x32_bf16 v[68:71], v[144:147], v[214:217], v[68:71]
	v_mfma_f32_16x16x32_bf16 v[64:67], v[152:155], v[214:217], v[64:67]
	v_mfma_f32_16x16x32_bf16 v[116:119], v[148:151], v[194:197], v[116:119]
	v_mfma_f32_16x16x32_bf16 v[112:115], v[156:159], v[194:197], v[112:115]
	v_mfma_f32_16x16x32_bf16 v[100:103], v[148:151], v[202:205], v[100:103]
	v_mfma_f32_16x16x32_bf16 v[96:99], v[156:159], v[202:205], v[96:99]
	v_mfma_f32_16x16x32_bf16 v[84:87], v[148:151], v[210:213], v[84:87]
	v_mfma_f32_16x16x32_bf16 v[80:83], v[156:159], v[210:213], v[80:83]
	v_mfma_f32_16x16x32_bf16 v[68:71], v[148:151], v[218:221], v[68:71]
	v_mfma_f32_16x16x32_bf16 v[64:67], v[156:159], v[218:221], v[64:67]
	s_barrier
; #define PG8_STAGE(bufoff, gbase, voff) do { _Pragma("unroll") for (int _i = 0; _i < 2; ++_i) \
;         __builtin_amdgcn_global_load_lds((const GAS unsigned*)((const char*)(gbase) + (voff)[_i]), (LAS unsigned*)(lds + (bufoff) + ldsw + _i * 8192), 16, 0, 0); } while (0)
; #define PG8_LDA(dst, b, h) do { _Pragma("unroll") for (int m = 0; m < 4; ++m) _Pragma("unroll") for (int k = 0; k < 2; ++k) dst[m][k] = *(const LAS bf16x8*)(lds + PG8_SA(b, h) + aoff + m * 2048 + k * 1024); } while (0)
; #define PG8_WAIT_V(n) asm volatile("s_waitcnt vmcnt(" #n ")" ::: "memory")
; #define PG8_WAIT_L(n) asm volatile("s_waitcnt lgkmcnt(" #n ")" ::: "memory")
; #define PG8_BAR __builtin_amdgcn_s_barrier()
; template <class Epi, class Sched>
; __device__ __forceinline__ void gemm_phase(LAS unsigned char* lds, const Gemm g, const Sched& S, const Epi& E, const int wave_) {
;     ...
;         for (int t = 0; t < nt; t += 2) {
;             if constexpr (Epi::HOOK) { if (t == 8 || t == 16) { E.hook(acc, cur, t >> 3, wr, wc, fr, fq); PG8_WAIT_V(0); } }
;             const bool last = (t == nt - 2);
;             const char* a1 = cA + (size_t)(t + 1) * kstep;
;             const char* a2 = last ? nA : cA + (size_t)(t + 2) * kstep; const char* b2 = last ? nB : cB + (size_t)(t + 2) * kstep;
;             const char* a3 = a2 + kstep; const char* b3 = b2 + kstep;
;             PG8_LDB(B0, 0, 0); PG8_LDB(B1, 0, 1); PG8_SCHED; PG8_LDA(At, 0, 0); PG8_STAGE(PG8_SA(1, 1), a1 + hstepA, voffA);
;             PG8_WAIT_V(8); PG8_WAIT_L(0); PG8_BAR; PG8_MMA(0, 0, At, B0); PG8_MMA(0, 1, At, B1); PG8_BAR; PG8_SCHED;
;             PG8_LDA(At, 0, 1); PG8_STAGE(PG8_SB(0, 0), b2, voffB); PG8_STAGE(PG8_SB(0, 1), b2 + hstepB, voffB); PG8_STAGE(PG8_SA(0, 0), a2, voffA);
;             PG8_WAIT_V(8); PG8_WAIT_L(0); PG8_BAR; PG8_MMA(1, 0, At, B0); PG8_MMA(1, 1, At, B1); PG8_BAR; PG8_SCHED;
;             PG8_LDB(B0, 1, 0); PG8_LDB(B1, 1, 1); PG8_SCHED; PG8_LDA(At, 1, 0); PG8_STAGE(PG8_SA(0, 1), a2 + hstepA, voffA);
;             PG8_WAIT_V(8); PG8_WAIT_L(0); PG8_BAR; PG8_MMA(0, 0, At, B0); PG8_MMA(0, 1, At, B1); PG8_BAR; PG8_SCHED;
;             PG8_LDA(At, 1, 1); PG8_STAGE(PG8_SB(1, 0), b3, voffB); PG8_STAGE(PG8_SB(1, 1), b3 + hstepB, voffB); PG8_STAGE(PG8_SA(1, 0), a3, voffA);
;             PG8_WAIT_V(8); PG8_WAIT_L(0); PG8_BAR; PG8_MMA(1, 0, At, B0); PG8_MMA(1, 1, At, B1); PG8_BAR; PG8_SCHED;
;         }
	s_add_i32 s21, s21, s83
	v_lshl_add_u64 v[222:223], v[222:223], 0, s[30:31]
	s_mov_b32 m0, s21
	ds_read_b128 v[160:163], v192 offset:49152
	ds_read_b128 v[194:197], v192 offset:50176
	ds_read_b128 v[198:201], v192 offset:51200
	ds_read_b128 v[202:205], v192 offset:52224
	ds_read_b128 v[206:209], v192 offset:53248
	ds_read_b128 v[210:213], v192 offset:54272
	ds_read_b128 v[214:217], v192 offset:55296
	ds_read_b128 v[218:221], v192 offset:56320
	global_load_lds_dwordx4 v[222:223], off
	s_add_i32 m0, s21, 0x2000
	s_add_u32 s50, s54, 0x60080
	v_lshl_add_u64 v[222:223], v[224:225], 0, s[30:31]
	s_addc_u32 s51, s55, 0
	s_add_i32 s21, s96, s83
	global_load_lds_dwordx4 v[222:223], off
	v_lshl_add_u64 v[222:223], s[50:51], 0, v[166:167]
	s_mov_b32 m0, s21
	s_nop 0
	global_load_lds_dwordx4 v[222:223], off
	v_lshl_add_u64 v[222:223], s[50:51], 0, v[170:171]
	s_add_i32 m0, s21, 0x2000
	s_nop 0
	global_load_lds_dwordx4 v[222:223], off
	v_lshl_add_u64 v[222:223], v[226:227], 0, s[30:31]
	s_mov_b32 m0, s64
	s_nop 0
	global_load_lds_dwordx4 v[222:223], off
	v_lshl_add_u64 v[222:223], v[228:229], 0, s[30:31]
	s_mov_b32 m0, s65
	s_nop 0
	global_load_lds_dwordx4 v[222:223], off
	s_waitcnt vmcnt(8)
	s_waitcnt lgkmcnt(0)
	s_barrier
	s_waitcnt lgkmcnt(0)
	v_mfma_f32_16x16x32_bf16 v[60:63], v[128:131], v[160:163], v[60:63]
	v_mfma_f32_16x16x32_bf16 v[56:59], v[136:139], v[160:163], v[56:59]
	v_mfma_f32_16x16x32_bf16 v[44:47], v[128:131], v[198:201], v[44:47]
	v_mfma_f32_16x16x32_bf16 v[40:43], v[136:139], v[198:201], v[40:43]
	v_mfma_f32_16x16x32_bf16 v[28:31], v[128:131], v[206:209], v[28:31]
	v_mfma_f32_16x16x32_bf16 v[24:27], v[136:139], v[206:209], v[24:27]
	v_mfma_f32_16x16x32_bf16 v[12:15], v[128:131], v[214:217], v[12:15]
	v_mfma_f32_16x16x32_bf16 v[8:11], v[136:139], v[214:217], v[8:11]
	v_mfma_f32_16x16x32_bf16 v[60:63], v[132:135], v[194:197], v[60:63]
	v_mfma_f32_16x16x32_bf16 v[56:59], v[140:143], v[194:197], v[56:59]
	v_mfma_f32_16x16x32_bf16 v[44:47], v[132:135], v[202:205], v[44:47]
	v_mfma_f32_16x16x32_bf16 v[40:43], v[140:143], v[202:205], v[40:43]
	v_mfma_f32_16x16x32_bf16 v[28:31], v[132:135], v[210:213], v[28:31]
	v_mfma_f32_16x16x32_bf16 v[24:27], v[140:143], v[210:213], v[24:27]
	v_mfma_f32_16x16x32_bf16 v[12:15], v[132:135], v[218:221], v[12:15]
	v_mfma_f32_16x16x32_bf16 v[8:11], v[140:143], v[218:221], v[8:11]
	v_mfma_f32_16x16x32_bf16 v[52:55], v[144:147], v[160:163], v[52:55]
	v_mfma_f32_16x16x32_bf16 v[48:51], v[152:155], v[160:163], v[48:51]
	v_mfma_f32_16x16x32_bf16 v[36:39], v[144:147], v[198:201], v[36:39]
	v_mfma_f32_16x16x32_bf16 v[32:35], v[152:155], v[198:201], v[32:35]
	v_mfma_f32_16x16x32_bf16 v[20:23], v[144:147], v[206:209], v[20:23]
	v_mfma_f32_16x16x32_bf16 v[16:19], v[152:155], v[206:209], v[16:19]
	v_mfma_f32_16x16x32_bf16 v[4:7], v[144:147], v[214:217], v[4:7]
	v_mfma_f32_16x16x32_bf16 v[0:3], v[152:155], v[214:217], v[0:3]
	v_mfma_f32_16x16x32_bf16 v[52:55], v[148:151], v[194:197], v[52:55]
	v_mfma_f32_16x16x32_bf16 v[48:51], v[156:159], v[194:197], v[48:51]
	v_mfma_f32_16x16x32_bf16 v[36:39], v[148:151], v[202:205], v[36:39]
	v_mfma_f32_16x16x32_bf16 v[32:35], v[156:159], v[202:205], v[32:35]
	v_mfma_f32_16x16x32_bf16 v[20:23], v[148:151], v[210:213], v[20:23]
	v_mfma_f32_16x16x32_bf16 v[16:19], v[156:159], v[210:213], v[16:19]
	v_mfma_f32_16x16x32_bf16 v[4:7], v[148:151], v[218:221], v[4:7]
	v_mfma_f32_16x16x32_bf16 v[0:3], v[156:159], v[218:221], v[0:3]
	s_barrier
	s_add_u32 s93, s93, 0x100
	s_addc_u32 s94, s94, 0
	s_cmp_ge_i32 s95, s63
	v_lshl_add_u64 v[182:183], v[182:183], 0, s[38:39]
	s_cbranch_scc1 .LBB0_1032
	s_mov_b64 s[50:51], s[52:53]
	s_mov_b32 s56, s95
	s_cmp_lt_i32 s56, 16
	s_cbranch_scc1 .LBB0_1025

; #define PG8_STAGE(bufoff, gbase, voff) do { _Pragma("unroll") for (int _i = 0; _i < 2; ++_i) \
;         __builtin_amdgcn_global_load_lds((const GAS unsigned*)((const char*)(gbase) + (voff)[_i]), (LAS unsigned*)(lds + (bufoff) + ldsw + _i * 8192), 16, 0, 0); } while (0)
; #define PG8_LDA(dst, b, h) do { _Pragma("unroll") for (int m = 0; m < 4; ++m) _Pragma("unroll") for (int k = 0; k < 2; ++k) dst[m][k] = *(const LAS bf16x8*)(lds + PG8_SA(b, h) + aoff + m * 2048 + k * 1024); } while (0)
; #define PG8_WAIT_V(n) asm volatile("s_waitcnt vmcnt(" #n ")" ::: "memory")
; #define PG8_WAIT_L(n) asm volatile("s_waitcnt lgkmcnt(" #n ")" ::: "memory")
; #define PG8_BAR __builtin_amdgcn_s_barrier()
; template <class Epi, class Sched>
; __device__ __forceinline__ void gemm_phase(LAS unsigned char* lds, const Gemm g, const Sched& S, const Epi& E, const int wave_) {
;     ...
;         for (int t = 0; t < nt; t += 2) {
;             if constexpr (Epi::HOOK) { if (t == 8 || t == 16) { E.hook(acc, cur, t >> 3, wr, wc, fr, fq); PG8_WAIT_V(0); } }
;             const bool last = (t == nt - 2);
;             const char* a1 = cA + (size_t)(t + 1) * kstep;
;             const char* a2 = last ? nA : cA + (size_t)(t + 2) * kstep; const char* b2 = last ? nB : cB + (size_t)(t + 2) * kstep;
;             const char* a3 = a2 + kstep; const char* b3 = b2 + kstep;
;             PG8_LDB(B0, 0, 0); PG8_LDB(B1, 0, 1); PG8_SCHED; PG8_LDA(At, 0, 0); PG8_STAGE(PG8_SA(1, 1), a1 + hstepA, voffA);
;             PG8_WAIT_V(8); PG8_WAIT_L(0); PG8_BAR; PG8_MMA(0, 0, At, B0); PG8_MMA(0, 1, At, B1); PG8_BAR; PG8_SCHED;
;             PG8_LDA(At, 0, 1); PG8_STAGE(PG8_SB(0, 0), b2, voffB); PG8_STAGE(PG8_SB(0, 1), b2 + hstepB, voffB); PG8_STAGE(PG8_SA(0, 0), a2, voffA);
;             PG8_WAIT_V(8); PG8_WAIT_L(0); PG8_BAR; PG8_MMA(1, 0, At, B0); PG8_MMA(1, 1, At, B1); PG8_BAR; PG8_SCHED;
;             PG8_LDB(B0, 1, 0); PG8_LDB(B1, 1, 1); PG8_SCHED; PG8_LDA(At, 1, 0); PG8_STAGE(PG8_SA(0, 1), a2 + hstepA, voffA);
;             PG8_WAIT_V(8); PG8_WAIT_L(0); PG8_BAR; PG8_MMA(0, 0, At, B0); PG8_MMA(0, 1, At, B1); PG8_BAR; PG8_SCHED;
;             PG8_LDA(At, 1, 1); PG8_STAGE(PG8_SB(1, 0), b3, voffB); PG8_STAGE(PG8_SB(1, 1), b3 + hstepB, voffB); PG8_STAGE(PG8_SA(1, 0), a3, voffA);
;             PG8_WAIT_V(8); PG8_WAIT_L(0); PG8_BAR; PG8_MMA(1, 0, At, B0); PG8_MMA(1, 1, At, B1); PG8_BAR; PG8_SCHED;
;         }
.LBB0_1109:
	ds_read_b128 v[154:157], v151
	ds_read_b128 v[158:161], v151 offset:1024
	ds_read_b128 v[162:165], v151 offset:2048
	ds_read_b128 v[166:169], v151 offset:3072
	ds_read_b128 v[170:173], v152
	ds_read_b128 v[174:177], v152 offset:1024
	ds_read_b128 v[178:181], v152 offset:2048
	ds_read_b128 v[188:191], v152 offset:3072
	s_add_i32 s72, s50, 2
	s_add_u32 s51, s48, 0xfffc0080
	s_addc_u32 s52, s49, -1
	s_cmp_eq_u32 s21, s50
	s_cselect_b32 s50, s69, s70
	s_cselect_b32 s53, s37, s52
	s_cselect_b32 s52, s39, s51
	s_cselect_b32 s51, s68, s71
	v_lshl_add_u64 v[182:183], s[48:49], 0, v[138:139]
	s_add_i32 m0, s56, 0xc000
	ds_read_b128 v[192:195], v153
	ds_read_b128 v[196:199], v153 offset:1024
	ds_read_b128 v[200:203], v153 offset:2048
	ds_read_b128 v[204:207], v153 offset:3072
	ds_read_b128 v[208:211], v153 offset:4096
	ds_read_b128 v[212:215], v153 offset:5120
	ds_read_b128 v[216:219], v153 offset:6144
	ds_read_b128 v[220:223], v153 offset:7168
	global_load_lds_dwordx4 v[182:183], off
	v_lshl_add_u64 v[182:183], s[48:49], 0, v[136:137]
	s_add_i32 m0, s56, 0xe000
	s_nop 0
	global_load_lds_dwordx4 v[182:183], off
	s_waitcnt vmcnt(8)
	s_waitcnt lgkmcnt(0)
	s_barrier
	s_waitcnt lgkmcnt(0)
	v_mfma_f32_16x16x32_bf16 v[120:123], v[154:157], v[192:195], v[120:123]
	v_mfma_f32_16x16x32_bf16 v[124:127], v[162:165], v[192:195], v[124:127]
	v_mfma_f32_16x16x32_bf16 v[108:111], v[154:157], v[200:203], v[108:111]
	v_mfma_f32_16x16x32_bf16 v[104:107], v[162:165], v[200:203], v[104:107]
	v_mfma_f32_16x16x32_bf16 v[92:95], v[154:157], v[208:211], v[92:95]
	v_mfma_f32_16x16x32_bf16 v[88:91], v[162:165], v[208:211], v[88:91]
	v_mfma_f32_16x16x32_bf16 v[76:79], v[154:157], v[216:219], v[76:79]
	v_mfma_f32_16x16x32_bf16 v[72:75], v[162:165], v[216:219], v[72:75]
	v_mfma_f32_16x16x32_bf16 v[120:123], v[158:161], v[196:199], v[120:123]
	v_mfma_f32_16x16x32_bf16 v[124:127], v[166:169], v[196:199], v[124:127]
	v_mfma_f32_16x16x32_bf16 v[108:111], v[158:161], v[204:207], v[108:111]
	v_mfma_f32_16x16x32_bf16 v[104:107], v[166:169], v[204:207], v[104:107]
	v_mfma_f32_16x16x32_bf16 v[92:95], v[158:161], v[212:215], v[92:95]
	v_mfma_f32_16x16x32_bf16 v[88:91], v[166:169], v[212:215], v[88:91]
	v_mfma_f32_16x16x32_bf16 v[76:79], v[158:161], v[220:223], v[76:79]
	v_mfma_f32_16x16x32_bf16 v[72:75], v[166:169], v[220:223], v[72:75]
	v_mfma_f32_16x16x32_bf16 v[116:119], v[170:173], v[192:195], v[116:119]
	v_mfma_f32_16x16x32_bf16 v[112:115], v[178:181], v[192:195], v[112:115]
	v_mfma_f32_16x16x32_bf16 v[100:103], v[170:173], v[200:203], v[100:103]
	v_mfma_f32_16x16x32_bf16 v[96:99], v[178:181], v[200:203], v[96:99]
	v_mfma_f32_16x16x32_bf16 v[84:87], v[170:173], v[208:211], v[84:87]
	v_mfma_f32_16x16x32_bf16 v[80:83], v[178:181], v[208:211], v[80:83]
	v_mfma_f32_16x16x32_bf16 v[68:71], v[170:173], v[216:219], v[68:71]
	v_mfma_f32_16x16x32_bf16 v[64:67], v[178:181], v[216:219], v[64:67]
	v_mfma_f32_16x16x32_bf16 v[116:119], v[174:177], v[196:199], v[116:119]
	v_mfma_f32_16x16x32_bf16 v[112:115], v[188:191], v[196:199], v[112:115]
	v_mfma_f32_16x16x32_bf16 v[100:103], v[174:177], v[204:207], v[100:103]
	v_mfma_f32_16x16x32_bf16 v[96:99], v[188:191], v[204:207], v[96:99]
	v_mfma_f32_16x16x32_bf16 v[84:87], v[174:177], v[212:215], v[84:87]
	v_mfma_f32_16x16x32_bf16 v[80:83], v[188:191], v[212:215], v[80:83]
	v_mfma_f32_16x16x32_bf16 v[68:71], v[174:177], v[220:223], v[68:71]
	v_mfma_f32_16x16x32_bf16 v[64:67], v[188:191], v[220:223], v[64:67]
	s_barrier
	s_add_i32 s73, s65, s83
	v_lshl_add_u64 v[182:183], s[50:51], 0, v[130:131]
	s_mov_b32 m0, s73
	ds_read_b128 v[192:195], v153 offset:16384
	ds_read_b128 v[196:199], v153 offset:17408
	ds_read_b128 v[200:203], v153 offset:18432
	ds_read_b128 v[204:207], v153 offset:19456
	ds_read_b128 v[208:211], v153 offset:20480
	ds_read_b128 v[212:215], v153 offset:21504
	ds_read_b128 v[216:219], v153 offset:22528
	ds_read_b128 v[220:223], v153 offset:23552
	global_load_lds_dwordx4 v[182:183], off
	s_add_i32 m0, s73, 0x2000
	s_add_u32 s74, s50, 0x40000
	v_lshl_add_u64 v[224:225], s[50:51], 0, v[134:135]
	s_addc_u32 s75, s51, 0
	s_add_i32 s73, s67, s83
	global_load_lds_dwordx4 v[224:225], off
	v_lshl_add_u64 v[226:227], s[74:75], 0, v[130:131]
	s_mov_b32 m0, s73
	v_lshl_add_u64 v[228:229], s[52:53], 0, v[132:133]
	global_load_lds_dwordx4 v[226:227], off
	v_lshl_add_u64 v[226:227], s[74:75], 0, v[134:135]
	s_add_i32 m0, s73, 0x2000
	s_nop 0
	global_load_lds_dwordx4 v[226:227], off
	v_lshl_add_u64 v[226:227], s[52:53], 0, v[128:129]
	s_mov_b32 m0, s56
	s_nop 0
	global_load_lds_dwordx4 v[226:227], off
	s_mov_b32 m0, s57
	s_nop 0
	global_load_lds_dwordx4 v[228:229], off
	s_waitcnt vmcnt(8)
	s_waitcnt lgkmcnt(0)
	s_barrier
; #define PG8_STAGE(bufoff, gbase, voff) do { _Pragma("unroll") for (int _i = 0; _i < 2; ++_i) \
;         __builtin_amdgcn_global_load_lds((const GAS unsigned*)((const char*)(gbase) + (voff)[_i]), (LAS unsigned*)(lds + (bufoff) + ldsw + _i * 8192), 16, 0, 0); } while (0)
; #define PG8_LDA(dst, b, h) do { _Pragma("unroll") for (int m = 0; m < 4; ++m) _Pragma("unroll") for (int k = 0; k < 2; ++k) dst[m][k] = *(const LAS bf16x8*)(lds + PG8_SA(b, h) + aoff + m * 2048 + k * 1024); } while (0)
; #define PG8_WAIT_V(n) asm volatile("s_waitcnt vmcnt(" #n ")" ::: "memory")
; #define PG8_WAIT_L(n) asm volatile("s_waitcnt lgkmcnt(" #n ")" ::: "memory")
; #define PG8_BAR __builtin_amdgcn_s_barrier()
; template <class Epi, class Sched>
; __device__ __forceinline__ void gemm_phase(LAS unsigned char* lds, const Gemm g, const Sched& S, const Epi& E, const int wave_) {
;     ...
;         for (int t = 0; t < nt; t += 2) {
;             if constexpr (Epi::HOOK) { if (t == 8 || t == 16) { E.hook(acc, cur, t >> 3, wr, wc, fr, fq); PG8_WAIT_V(0); } }
;             const bool last = (t == nt - 2);
;             const char* a1 = cA + (size_t)(t + 1) * kstep;
;             const char* a2 = last ? nA : cA + (size_t)(t + 2) * kstep; const char* b2 = last ? nB : cB + (size_t)(t + 2) * kstep;
;             const char* a3 = a2 + kstep; const char* b3 = b2 + kstep;
;             PG8_LDB(B0, 0, 0); PG8_LDB(B1, 0, 1); PG8_SCHED; PG8_LDA(At, 0, 0); PG8_STAGE(PG8_SA(1, 1), a1 + hstepA, voffA);
;             PG8_WAIT_V(8); PG8_WAIT_L(0); PG8_BAR; PG8_MMA(0, 0, At, B0); PG8_MMA(0, 1, At, B1); PG8_BAR; PG8_SCHED;
;             PG8_LDA(At, 0, 1); PG8_STAGE(PG8_SB(0, 0), b2, voffB); PG8_STAGE(PG8_SB(0, 1), b2 + hstepB, voffB); PG8_STAGE(PG8_SA(0, 0), a2, voffA);
;             PG8_WAIT_V(8); PG8_WAIT_L(0); PG8_BAR; PG8_MMA(1, 0, At, B0); PG8_MMA(1, 1, At, B1); PG8_BAR; PG8_SCHED;
;             PG8_LDB(B0, 1, 0); PG8_LDB(B1, 1, 1); PG8_SCHED; PG8_LDA(At, 1, 0); PG8_STAGE(PG8_SA(0, 1), a2 + hstepA, voffA);
;             PG8_WAIT_V(8); PG8_WAIT_L(0); PG8_BAR; PG8_MMA(0, 0, At, B0); PG8_MMA(0, 1, At, B1); PG8_BAR; PG8_SCHED;
;             PG8_LDA(At, 1, 1); PG8_STAGE(PG8_SB(1, 0), b3, voffB); PG8_STAGE(PG8_SB(1, 1), b3 + hstepB, voffB); PG8_STAGE(PG8_SA(1, 0), a3, voffA);
;             PG8_WAIT_V(8); PG8_WAIT_L(0); PG8_BAR; PG8_MMA(1, 0, At, B0); PG8_MMA(1, 1, At, B1); PG8_BAR; PG8_SCHED;
;         }
	s_waitcnt lgkmcnt(0)
	v_mfma_f32_16x16x32_bf16 v[60:63], v[154:157], v[192:195], v[60:63]
	v_mfma_f32_16x16x32_bf16 v[56:59], v[162:165], v[192:195], v[56:59]
	v_mfma_f32_16x16x32_bf16 v[44:47], v[154:157], v[200:203], v[44:47]
	v_mfma_f32_16x16x32_bf16 v[40:43], v[162:165], v[200:203], v[40:43]
	v_mfma_f32_16x16x32_bf16 v[28:31], v[154:157], v[208:211], v[28:31]
	v_mfma_f32_16x16x32_bf16 v[24:27], v[162:165], v[208:211], v[24:27]
	v_mfma_f32_16x16x32_bf16 v[12:15], v[154:157], v[216:219], v[12:15]
	v_mfma_f32_16x16x32_bf16 v[8:11], v[162:165], v[216:219], v[8:11]
	v_mfma_f32_16x16x32_bf16 v[60:63], v[158:161], v[196:199], v[60:63]
	v_mfma_f32_16x16x32_bf16 v[56:59], v[166:169], v[196:199], v[56:59]
	v_mfma_f32_16x16x32_bf16 v[44:47], v[158:161], v[204:207], v[44:47]
	v_mfma_f32_16x16x32_bf16 v[40:43], v[166:169], v[204:207], v[40:43]
	v_mfma_f32_16x16x32_bf16 v[28:31], v[158:161], v[212:215], v[28:31]
	v_mfma_f32_16x16x32_bf16 v[24:27], v[166:169], v[212:215], v[24:27]
	v_mfma_f32_16x16x32_bf16 v[12:15], v[158:161], v[220:223], v[12:15]
	v_mfma_f32_16x16x32_bf16 v[8:11], v[166:169], v[220:223], v[8:11]
	v_mfma_f32_16x16x32_bf16 v[52:55], v[170:173], v[192:195], v[52:55]
	v_mfma_f32_16x16x32_bf16 v[48:51], v[178:181], v[192:195], v[48:51]
	v_mfma_f32_16x16x32_bf16 v[36:39], v[170:173], v[200:203], v[36:39]
	v_mfma_f32_16x16x32_bf16 v[32:35], v[178:181], v[200:203], v[32:35]
	v_mfma_f32_16x16x32_bf16 v[20:23], v[170:173], v[208:211], v[20:23]
	v_mfma_f32_16x16x32_bf16 v[16:19], v[178:181], v[208:211], v[16:19]
	v_mfma_f32_16x16x32_bf16 v[4:7], v[170:173], v[216:219], v[4:7]
	v_mfma_f32_16x16x32_bf16 v[0:3], v[178:181], v[216:219], v[0:3]
	v_mfma_f32_16x16x32_bf16 v[52:55], v[174:177], v[196:199], v[52:55]
	v_mfma_f32_16x16x32_bf16 v[48:51], v[188:191], v[196:199], v[48:51]
	v_mfma_f32_16x16x32_bf16 v[36:39], v[174:177], v[204:207], v[36:39]
	v_mfma_f32_16x16x32_bf16 v[32:35], v[188:191], v[204:207], v[32:35]
	v_mfma_f32_16x16x32_bf16 v[20:23], v[174:177], v[212:215], v[20:23]
	v_mfma_f32_16x16x32_bf16 v[16:19], v[188:191], v[212:215], v[16:19]
	v_mfma_f32_16x16x32_bf16 v[4:7], v[174:177], v[220:223], v[4:7]
	v_mfma_f32_16x16x32_bf16 v[0:3], v[188:191], v[220:223], v[0:3]
	s_barrier
	s_add_i32 s73, 0, 0x18000
	s_add_i32 s74, 0, 0x1c000
	v_add_u32_e32 v166, s73, v147
	v_add_u32_e32 v188, s74, v147
	ds_read_b128 v[154:157], v166
	ds_read_b128 v[158:161], v166 offset:1024
	ds_read_b128 v[162:165], v166 offset:2048
	ds_read_b128 v[166:169], v166 offset:3072
	ds_read_b128 v[170:173], v188
	ds_read_b128 v[174:177], v188 offset:1024
	ds_read_b128 v[178:181], v188 offset:2048
	ds_read_b128 v[188:191], v188 offset:3072
	s_add_u32 s52, s52, 0x40000
	s_addc_u32 s53, s53, 0
	s_mov_b32 m0, s58
	v_lshl_add_u64 v[230:231], s[52:53], 0, v[128:129]
	ds_read_b128 v[192:195], v153 offset:32768
	ds_read_b128 v[196:199], v153 offset:33792
	ds_read_b128 v[200:203], v153 offset:34816
	ds_read_b128 v[204:207], v153 offset:35840
	ds_read_b128 v[208:211], v153 offset:36864
	ds_read_b128 v[212:215], v153 offset:37888
	ds_read_b128 v[216:219], v153 offset:38912
	ds_read_b128 v[220:223], v153 offset:39936
	global_load_lds_dwordx4 v[230:231], off
	v_lshl_add_u64 v[230:231], s[52:53], 0, v[132:133]
	s_mov_b32 m0, s59
	s_nop 0
	global_load_lds_dwordx4 v[230:231], off
	s_waitcnt vmcnt(8)
	s_waitcnt lgkmcnt(0)
	s_barrier
	s_waitcnt lgkmcnt(0)
	v_mfma_f32_16x16x32_bf16 v[120:123], v[154:157], v[192:195], v[120:123]
	v_mfma_f32_16x16x32_bf16 v[124:127], v[162:165], v[192:195], v[124:127]
	v_mfma_f32_16x16x32_bf16 v[108:111], v[154:157], v[200:203], v[108:111]
	v_mfma_f32_16x16x32_bf16 v[104:107], v[162:165], v[200:203], v[104:107]
	v_mfma_f32_16x16x32_bf16 v[92:95], v[154:157], v[208:211], v[92:95]
	v_mfma_f32_16x16x32_bf16 v[88:91], v[162:165], v[208:211], v[88:91]
	v_mfma_f32_16x16x32_bf16 v[76:79], v[154:157], v[216:219], v[76:79]
	v_mfma_f32_16x16x32_bf16 v[72:75], v[162:165], v[216:219], v[72:75]
	v_mfma_f32_16x16x32_bf16 v[120:123], v[158:161], v[196:199], v[120:123]
	v_mfma_f32_16x16x32_bf16 v[124:127], v[166:169], v[196:199], v[124:127]
	v_mfma_f32_16x16x32_bf16 v[108:111], v[158:161], v[204:207], v[108:111]
	v_mfma_f32_16x16x32_bf16 v[104:107], v[166:169], v[204:207], v[104:107]
	v_mfma_f32_16x16x32_bf16 v[92:95], v[158:161], v[212:215], v[92:95]
	v_mfma_f32_16x16x32_bf16 v[88:91], v[166:169], v[212:215], v[88:91]
	v_mfma_f32_16x16x32_bf16 v[76:79], v[158:161], v[220:223], v[76:79]
	v_mfma_f32_16x16x32_bf16 v[72:75], v[166:169], v[220:223], v[72:75]
	v_mfma_f32_16x16x32_bf16 v[116:119], v[170:173], v[192:195], v[116:119]
	v_mfma_f32_16x16x32_bf16 v[112:115], v[178:181], v[192:195], v[112:115]
	v_mfma_f32_16x16x32_bf16 v[100:103], v[170:173], v[200:203], v[100:103]
	v_mfma_f32_16x16x32_bf16 v[96:99], v[178:181], v[200:203], v[96:99]
	v_mfma_f32_16x16x32_bf16 v[84:87], v[170:173], v[208:211], v[84:87]
	v_mfma_f32_16x16x32_bf16 v[80:83], v[178:181], v[208:211], v[80:83]
	v_mfma_f32_16x16x32_bf16 v[68:71], v[170:173], v[216:219], v[68:71]
	v_mfma_f32_16x16x32_bf16 v[64:67], v[178:181], v[216:219], v[64:67]
	v_mfma_f32_16x16x32_bf16 v[116:119], v[174:177], v[196:199], v[116:119]
	v_mfma_f32_16x16x32_bf16 v[112:115], v[188:191], v[196:199], v[112:115]
	v_mfma_f32_16x16x32_bf16 v[100:103], v[174:177], v[204:207], v[100:103]
	v_mfma_f32_16x16x32_bf16 v[96:99], v[188:191], v[204:207], v[96:99]
	v_mfma_f32_16x16x32_bf16 v[84:87], v[174:177], v[212:215], v[84:87]
	v_mfma_f32_16x16x32_bf16 v[80:83], v[188:191], v[212:215], v[80:83]
	v_mfma_f32_16x16x32_bf16 v[68:71], v[174:177], v[220:223], v[68:71]
	v_mfma_f32_16x16x32_bf16 v[64:67], v[188:191], v[220:223], v[64:67]
	s_barrier
; #define PG8_STAGE(bufoff, gbase, voff) do { _Pragma("unroll") for (int _i = 0; _i < 2; ++_i) \
;         __builtin_amdgcn_global_load_lds((const GAS unsigned*)((const char*)(gbase) + (voff)[_i]), (LAS unsigned*)(lds + (bufoff) + ldsw + _i * 8192), 16, 0, 0); } while (0)
; #define PG8_LDA(dst, b, h) do { _Pragma("unroll") for (int m = 0; m < 4; ++m) _Pragma("unroll") for (int k = 0; k < 2; ++k) dst[m][k] = *(const LAS bf16x8*)(lds + PG8_SA(b, h) + aoff + m * 2048 + k * 1024); } while (0)
; #define PG8_WAIT_V(n) asm volatile("s_waitcnt vmcnt(" #n ")" ::: "memory")
; #define PG8_WAIT_L(n) asm volatile("s_waitcnt lgkmcnt(" #n ")" ::: "memory")
; #define PG8_BAR __builtin_amdgcn_s_barrier()
; template <class Epi, class Sched>
; __device__ __forceinline__ void gemm_phase(LAS unsigned char* lds, const Gemm g, const Sched& S, const Epi& E, const int wave_) {
;     ...
;         for (int t = 0; t < nt; t += 2) {
;             if constexpr (Epi::HOOK) { if (t == 8 || t == 16) { E.hook(acc, cur, t >> 3, wr, wc, fr, fq); PG8_WAIT_V(0); } }
;             const bool last = (t == nt - 2);
;             const char* a1 = cA + (size_t)(t + 1) * kstep;
;             const char* a2 = last ? nA : cA + (size_t)(t + 2) * kstep; const char* b2 = last ? nB : cB + (size_t)(t + 2) * kstep;
;             const char* a3 = a2 + kstep; const char* b3 = b2 + kstep;
;             PG8_LDB(B0, 0, 0); PG8_LDB(B1, 0, 1); PG8_SCHED; PG8_LDA(At, 0, 0); PG8_STAGE(PG8_SA(1, 1), a1 + hstepA, voffA);
;             PG8_WAIT_V(8); PG8_WAIT_L(0); PG8_BAR; PG8_MMA(0, 0, At, B0); PG8_MMA(0, 1, At, B1); PG8_BAR; PG8_SCHED;
;             PG8_LDA(At, 0, 1); PG8_STAGE(PG8_SB(0, 0), b2, voffB); PG8_STAGE(PG8_SB(0, 1), b2 + hstepB, voffB); PG8_STAGE(PG8_SA(0, 0), a2, voffA);
;             PG8_WAIT_V(8); PG8_WAIT_L(0); PG8_BAR; PG8_MMA(1, 0, At, B0); PG8_MMA(1, 1, At, B1); PG8_BAR; PG8_SCHED;
;             PG8_LDB(B0, 1, 0); PG8_LDB(B1, 1, 1); PG8_SCHED; PG8_LDA(At, 1, 0); PG8_STAGE(PG8_SA(0, 1), a2 + hstepA, voffA);
;             PG8_WAIT_V(8); PG8_WAIT_L(0); PG8_BAR; PG8_MMA(0, 0, At, B0); PG8_MMA(0, 1, At, B1); PG8_BAR; PG8_SCHED;
;             PG8_LDA(At, 1, 1); PG8_STAGE(PG8_SB(1, 0), b3, voffB); PG8_STAGE(PG8_SB(1, 1), b3 + hstepB, voffB); PG8_STAGE(PG8_SA(1, 0), a3, voffA);
;             PG8_WAIT_V(8); PG8_WAIT_L(0); PG8_BAR; PG8_MMA(1, 0, At, B0); PG8_MMA(1, 1, At, B1); PG8_BAR; PG8_SCHED;
;         }
	s_add_i32 s52, s73, s83
	v_lshl_add_u64 v[182:183], v[182:183], 0, s[10:11]
	s_mov_b32 m0, s52
	ds_read_b128 v[192:195], v153 offset:49152
	ds_read_b128 v[196:199], v153 offset:50176
	ds_read_b128 v[200:203], v153 offset:51200
	ds_read_b128 v[204:207], v153 offset:52224
	ds_read_b128 v[208:211], v153 offset:53248
	ds_read_b128 v[212:215], v153 offset:54272
	ds_read_b128 v[216:219], v153 offset:55296
	ds_read_b128 v[220:223], v153 offset:56320
	global_load_lds_dwordx4 v[182:183], off
	s_add_i32 m0, s52, 0x2000
	s_add_u32 s50, s50, 0x40080
	v_lshl_add_u64 v[182:183], v[224:225], 0, s[10:11]
	s_addc_u32 s51, s51, 0
	s_add_i32 s52, s74, s83
	global_load_lds_dwordx4 v[182:183], off
	v_lshl_add_u64 v[182:183], s[50:51], 0, v[130:131]
	s_mov_b32 m0, s52
	s_nop 0
	global_load_lds_dwordx4 v[182:183], off
	v_lshl_add_u64 v[182:183], s[50:51], 0, v[134:135]
	s_add_i32 m0, s52, 0x2000
	s_nop 0
	global_load_lds_dwordx4 v[182:183], off
	v_lshl_add_u64 v[182:183], v[226:227], 0, s[10:11]
	s_mov_b32 m0, s62
	s_nop 0
	global_load_lds_dwordx4 v[182:183], off
	v_lshl_add_u64 v[182:183], v[228:229], 0, s[10:11]
	s_mov_b32 m0, s63
	s_nop 0
	global_load_lds_dwordx4 v[182:183], off
	s_waitcnt vmcnt(8)
	s_waitcnt lgkmcnt(0)
	s_barrier
	s_waitcnt lgkmcnt(0)
	v_mfma_f32_16x16x32_bf16 v[60:63], v[154:157], v[192:195], v[60:63]
	v_mfma_f32_16x16x32_bf16 v[56:59], v[162:165], v[192:195], v[56:59]
	v_mfma_f32_16x16x32_bf16 v[44:47], v[154:157], v[200:203], v[44:47]
	v_mfma_f32_16x16x32_bf16 v[40:43], v[162:165], v[200:203], v[40:43]
	v_mfma_f32_16x16x32_bf16 v[28:31], v[154:157], v[208:211], v[28:31]
	v_mfma_f32_16x16x32_bf16 v[24:27], v[162:165], v[208:211], v[24:27]
	v_mfma_f32_16x16x32_bf16 v[12:15], v[154:157], v[216:219], v[12:15]
	v_mfma_f32_16x16x32_bf16 v[8:11], v[162:165], v[216:219], v[8:11]
	v_mfma_f32_16x16x32_bf16 v[60:63], v[158:161], v[196:199], v[60:63]
	v_mfma_f32_16x16x32_bf16 v[56:59], v[166:169], v[196:199], v[56:59]
	v_mfma_f32_16x16x32_bf16 v[44:47], v[158:161], v[204:207], v[44:47]
	v_mfma_f32_16x16x32_bf16 v[40:43], v[166:169], v[204:207], v[40:43]
	v_mfma_f32_16x16x32_bf16 v[28:31], v[158:161], v[212:215], v[28:31]
	v_mfma_f32_16x16x32_bf16 v[24:27], v[166:169], v[212:215], v[24:27]
	v_mfma_f32_16x16x32_bf16 v[12:15], v[158:161], v[220:223], v[12:15]
	v_mfma_f32_16x16x32_bf16 v[8:11], v[166:169], v[220:223], v[8:11]
	v_mfma_f32_16x16x32_bf16 v[52:55], v[170:173], v[192:195], v[52:55]
	v_mfma_f32_16x16x32_bf16 v[48:51], v[178:181], v[192:195], v[48:51]
	v_mfma_f32_16x16x32_bf16 v[36:39], v[170:173], v[200:203], v[36:39]
	v_mfma_f32_16x16x32_bf16 v[32:35], v[178:181], v[200:203], v[32:35]
	v_mfma_f32_16x16x32_bf16 v[20:23], v[170:173], v[208:211], v[20:23]
	v_mfma_f32_16x16x32_bf16 v[16:19], v[178:181], v[208:211], v[16:19]
	v_mfma_f32_16x16x32_bf16 v[4:7], v[170:173], v[216:219], v[4:7]
	v_mfma_f32_16x16x32_bf16 v[0:3], v[178:181], v[216:219], v[0:3]
	v_mfma_f32_16x16x32_bf16 v[52:55], v[174:177], v[196:199], v[52:55]
	v_mfma_f32_16x16x32_bf16 v[48:51], v[188:191], v[196:199], v[48:51]
	v_mfma_f32_16x16x32_bf16 v[36:39], v[174:177], v[204:207], v[36:39]
	v_mfma_f32_16x16x32_bf16 v[32:35], v[188:191], v[204:207], v[32:35]
	v_mfma_f32_16x16x32_bf16 v[20:23], v[174:177], v[212:215], v[20:23]
	v_mfma_f32_16x16x32_bf16 v[16:19], v[188:191], v[212:215], v[16:19]
	v_mfma_f32_16x16x32_bf16 v[4:7], v[174:177], v[220:223], v[4:7]
	v_mfma_f32_16x16x32_bf16 v[0:3], v[188:191], v[220:223], v[0:3]
	s_barrier
	s_add_u32 s70, s70, 0x100
	s_addc_u32 s71, s71, 0
	s_add_u32 s48, s48, 0x100
	s_addc_u32 s49, s49, 0
	s_cmp_ge_i32 s72, s61
	s_mov_b32 s50, s72
	s_cbranch_scc0 .LBB0_1109

; #define PG8_STAGE(bufoff, gbase, voff) do { _Pragma("unroll") for (int _i = 0; _i < 2; ++_i) \
;         __builtin_amdgcn_global_load_lds((const GAS unsigned*)((const char*)(gbase) + (voff)[_i]), (LAS unsigned*)(lds + (bufoff) + ldsw + _i * 8192), 16, 0, 0); } while (0)
; #define PG8_LDA(dst, b, h) do { _Pragma("unroll") for (int m = 0; m < 4; ++m) _Pragma("unroll") for (int k = 0; k < 2; ++k) dst[m][k] = *(const LAS bf16x8*)(lds + PG8_SA(b, h) + aoff + m * 2048 + k * 1024); } while (0)
; #define PG8_WAIT_V(n) asm volatile("s_waitcnt vmcnt(" #n ")" ::: "memory")
; #define PG8_WAIT_L(n) asm volatile("s_waitcnt lgkmcnt(" #n ")" ::: "memory")
; #define PG8_BAR __builtin_amdgcn_s_barrier()
; template <class Epi, class Sched>
; __device__ __forceinline__ void gemm_phase(LAS unsigned char* lds, const Gemm g, const Sched& S, const Epi& E, const int wave_) {
;     ...
;         for (int t = 0; t < nt; t += 2) {
;             if constexpr (Epi::HOOK) { if (t == 8 || t == 16) { E.hook(acc, cur, t >> 3, wr, wc, fr, fq); PG8_WAIT_V(0); } }
;             const bool last = (t == nt - 2);
;             const char* a1 = cA + (size_t)(t + 1) * kstep;
;             const char* a2 = last ? nA : cA + (size_t)(t + 2) * kstep; const char* b2 = last ? nB : cB + (size_t)(t + 2) * kstep;
;             const char* a3 = a2 + kstep; const char* b3 = b2 + kstep;
;             PG8_LDB(B0, 0, 0); PG8_LDB(B1, 0, 1); PG8_SCHED; PG8_LDA(At, 0, 0); PG8_STAGE(PG8_SA(1, 1), a1 + hstepA, voffA);
;             PG8_WAIT_V(8); PG8_WAIT_L(0); PG8_BAR; PG8_MMA(0, 0, At, B0); PG8_MMA(0, 1, At, B1); PG8_BAR; PG8_SCHED;
;             PG8_LDA(At, 0, 1); PG8_STAGE(PG8_SB(0, 0), b2, voffB); PG8_STAGE(PG8_SB(0, 1), b2 + hstepB, voffB); PG8_STAGE(PG8_SA(0, 0), a2, voffA);
;             PG8_WAIT_V(8); PG8_WAIT_L(0); PG8_BAR; PG8_MMA(1, 0, At, B0); PG8_MMA(1, 1, At, B1); PG8_BAR; PG8_SCHED;
;             PG8_LDB(B0, 1, 0); PG8_LDB(B1, 1, 1); PG8_SCHED; PG8_LDA(At, 1, 0); PG8_STAGE(PG8_SA(0, 1), a2 + hstepA, voffA);
;             PG8_WAIT_V(8); PG8_WAIT_L(0); PG8_BAR; PG8_MMA(0, 0, At, B0); PG8_MMA(0, 1, At, B1); PG8_BAR; PG8_SCHED;
;             PG8_LDA(At, 1, 1); PG8_STAGE(PG8_SB(1, 0), b3, voffB); PG8_STAGE(PG8_SB(1, 1), b3 + hstepB, voffB); PG8_STAGE(PG8_SA(1, 0), a3, voffA);
;             PG8_WAIT_V(8); PG8_WAIT_L(0); PG8_BAR; PG8_MMA(1, 0, At, B0); PG8_MMA(1, 1, At, B1); PG8_BAR; PG8_SCHED;
;         }
.LBB0_1180:
	ds_read_b128 v[166:169], v163
	ds_read_b128 v[170:173], v163 offset:1024
	ds_read_b128 v[174:177], v163 offset:2048
	ds_read_b128 v[178:181], v163 offset:3072
	ds_read_b128 v[182:185], v165
	ds_read_b128 v[186:189], v165 offset:1024
	ds_read_b128 v[190:193], v165 offset:2048
	ds_read_b128 v[194:197], v165 offset:3072
	s_add_i32 s64, s40, 2
	s_add_u32 s41, s38, 0xfffc0080
	s_addc_u32 s42, s39, -1
	s_cmp_eq_u32 s54, s40
	s_cselect_b32 s40, s61, s62
	s_cselect_b32 s43, s37, s42
	s_cselect_b32 s42, s59, s41
	s_cselect_b32 s41, s60, s63
	v_lshl_add_u64 v[230:231], s[38:39], 0, v[156:157]
	s_add_i32 m0, s47, 0xc000
	ds_read_b128 v[198:201], v164
	ds_read_b128 v[202:205], v164 offset:1024
	ds_read_b128 v[206:209], v164 offset:2048
	ds_read_b128 v[210:213], v164 offset:3072
	ds_read_b128 v[214:217], v164 offset:4096
	ds_read_b128 v[218:221], v164 offset:5120
	ds_read_b128 v[222:225], v164 offset:6144
	ds_read_b128 v[226:229], v164 offset:7168
	global_load_lds_dwordx4 v[230:231], off
	v_lshl_add_u64 v[230:231], s[38:39], 0, v[154:155]
	s_add_i32 m0, s47, 0xe000
	s_nop 0
	global_load_lds_dwordx4 v[230:231], off
	s_waitcnt vmcnt(8)
	s_waitcnt lgkmcnt(0)
	s_barrier
	s_waitcnt lgkmcnt(0)
	v_mfma_f32_16x16x32_bf16 v[124:127], v[166:169], v[198:201], v[124:127]
	v_mfma_f32_16x16x32_bf16 v[120:123], v[174:177], v[198:201], v[120:123]
	v_mfma_f32_16x16x32_bf16 v[108:111], v[166:169], v[206:209], v[108:111]
	v_mfma_f32_16x16x32_bf16 v[104:107], v[174:177], v[206:209], v[104:107]
	v_mfma_f32_16x16x32_bf16 v[92:95], v[166:169], v[214:217], v[92:95]
	v_mfma_f32_16x16x32_bf16 v[88:91], v[174:177], v[214:217], v[88:91]
	v_mfma_f32_16x16x32_bf16 v[76:79], v[166:169], v[222:225], v[76:79]
	v_mfma_f32_16x16x32_bf16 v[72:75], v[174:177], v[222:225], v[72:75]
	v_mfma_f32_16x16x32_bf16 v[124:127], v[170:173], v[202:205], v[124:127]
	v_mfma_f32_16x16x32_bf16 v[120:123], v[178:181], v[202:205], v[120:123]
	v_mfma_f32_16x16x32_bf16 v[108:111], v[170:173], v[210:213], v[108:111]
	v_mfma_f32_16x16x32_bf16 v[104:107], v[178:181], v[210:213], v[104:107]
	v_mfma_f32_16x16x32_bf16 v[92:95], v[170:173], v[218:221], v[92:95]
	v_mfma_f32_16x16x32_bf16 v[88:91], v[178:181], v[218:221], v[88:91]
	v_mfma_f32_16x16x32_bf16 v[76:79], v[170:173], v[226:229], v[76:79]
	v_mfma_f32_16x16x32_bf16 v[72:75], v[178:181], v[226:229], v[72:75]
	v_mfma_f32_16x16x32_bf16 v[116:119], v[182:185], v[198:201], v[116:119]
	v_mfma_f32_16x16x32_bf16 v[112:115], v[190:193], v[198:201], v[112:115]
	v_mfma_f32_16x16x32_bf16 v[100:103], v[182:185], v[206:209], v[100:103]
	v_mfma_f32_16x16x32_bf16 v[96:99], v[190:193], v[206:209], v[96:99]
	v_mfma_f32_16x16x32_bf16 v[84:87], v[182:185], v[214:217], v[84:87]
	v_mfma_f32_16x16x32_bf16 v[80:83], v[190:193], v[214:217], v[80:83]
	v_mfma_f32_16x16x32_bf16 v[68:71], v[182:185], v[222:225], v[68:71]
	v_mfma_f32_16x16x32_bf16 v[64:67], v[190:193], v[222:225], v[64:67]
	v_mfma_f32_16x16x32_bf16 v[116:119], v[186:189], v[202:205], v[116:119]
	v_mfma_f32_16x16x32_bf16 v[112:115], v[194:197], v[202:205], v[112:115]
	v_mfma_f32_16x16x32_bf16 v[100:103], v[186:189], v[210:213], v[100:103]
	v_mfma_f32_16x16x32_bf16 v[96:99], v[194:197], v[210:213], v[96:99]
	v_mfma_f32_16x16x32_bf16 v[84:87], v[186:189], v[218:221], v[84:87]
	v_mfma_f32_16x16x32_bf16 v[80:83], v[194:197], v[218:221], v[80:83]
	v_mfma_f32_16x16x32_bf16 v[68:71], v[186:189], v[226:229], v[68:71]
	v_mfma_f32_16x16x32_bf16 v[64:67], v[194:197], v[226:229], v[64:67]
	s_barrier
	s_add_i32 s65, s55, s83
	v_lshl_add_u64 v[230:231], s[40:41], 0, v[130:131]
	s_mov_b32 m0, s65
	ds_read_b128 v[198:201], v164 offset:16384
	ds_read_b128 v[202:205], v164 offset:17408
	ds_read_b128 v[206:209], v164 offset:18432
	ds_read_b128 v[210:213], v164 offset:19456
	ds_read_b128 v[214:217], v164 offset:20480
	ds_read_b128 v[218:221], v164 offset:21504
	ds_read_b128 v[222:225], v164 offset:22528
	ds_read_b128 v[226:229], v164 offset:23552
	global_load_lds_dwordx4 v[230:231], off
	s_add_i32 m0, s65, 0x2000
	s_add_u32 s66, s40, 0x40000
	v_lshl_add_u64 v[232:233], s[40:41], 0, v[134:135]
	s_addc_u32 s67, s41, 0
	s_add_i32 s65, s56, s83
	global_load_lds_dwordx4 v[232:233], off
	v_lshl_add_u64 v[234:235], s[66:67], 0, v[130:131]
	s_mov_b32 m0, s65
	v_lshl_add_u64 v[236:237], s[42:43], 0, v[132:133]
	global_load_lds_dwordx4 v[234:235], off
	v_lshl_add_u64 v[234:235], s[66:67], 0, v[134:135]
	s_add_i32 m0, s65, 0x2000
	s_nop 0
	global_load_lds_dwordx4 v[234:235], off
	v_lshl_add_u64 v[234:235], s[42:43], 0, v[128:129]
	s_mov_b32 m0, s47
	s_nop 0
	global_load_lds_dwordx4 v[234:235], off
	s_mov_b32 m0, s48
	s_nop 0
	global_load_lds_dwordx4 v[236:237], off
	s_waitcnt vmcnt(8)
	s_waitcnt lgkmcnt(0)
	s_barrier
; #define PG8_STAGE(bufoff, gbase, voff) do { _Pragma("unroll") for (int _i = 0; _i < 2; ++_i) \
;         __builtin_amdgcn_global_load_lds((const GAS unsigned*)((const char*)(gbase) + (voff)[_i]), (LAS unsigned*)(lds + (bufoff) + ldsw + _i * 8192), 16, 0, 0); } while (0)
; #define PG8_LDA(dst, b, h) do { _Pragma("unroll") for (int m = 0; m < 4; ++m) _Pragma("unroll") for (int k = 0; k < 2; ++k) dst[m][k] = *(const LAS bf16x8*)(lds + PG8_SA(b, h) + aoff + m * 2048 + k * 1024); } while (0)
; #define PG8_WAIT_V(n) asm volatile("s_waitcnt vmcnt(" #n ")" ::: "memory")
; #define PG8_WAIT_L(n) asm volatile("s_waitcnt lgkmcnt(" #n ")" ::: "memory")
; #define PG8_BAR __builtin_amdgcn_s_barrier()
; template <class Epi, class Sched>
; __device__ __forceinline__ void gemm_phase(LAS unsigned char* lds, const Gemm g, const Sched& S, const Epi& E, const int wave_) {
;     ...
;         for (int t = 0; t < nt; t += 2) {
;             if constexpr (Epi::HOOK) { if (t == 8 || t == 16) { E.hook(acc, cur, t >> 3, wr, wc, fr, fq); PG8_WAIT_V(0); } }
;             const bool last = (t == nt - 2);
;             const char* a1 = cA + (size_t)(t + 1) * kstep;
;             const char* a2 = last ? nA : cA + (size_t)(t + 2) * kstep; const char* b2 = last ? nB : cB + (size_t)(t + 2) * kstep;
;             const char* a3 = a2 + kstep; const char* b3 = b2 + kstep;
;             PG8_LDB(B0, 0, 0); PG8_LDB(B1, 0, 1); PG8_SCHED; PG8_LDA(At, 0, 0); PG8_STAGE(PG8_SA(1, 1), a1 + hstepA, voffA);
;             PG8_WAIT_V(8); PG8_WAIT_L(0); PG8_BAR; PG8_MMA(0, 0, At, B0); PG8_MMA(0, 1, At, B1); PG8_BAR; PG8_SCHED;
;             PG8_LDA(At, 0, 1); PG8_STAGE(PG8_SB(0, 0), b2, voffB); PG8_STAGE(PG8_SB(0, 1), b2 + hstepB, voffB); PG8_STAGE(PG8_SA(0, 0), a2, voffA);
;             PG8_WAIT_V(8); PG8_WAIT_L(0); PG8_BAR; PG8_MMA(1, 0, At, B0); PG8_MMA(1, 1, At, B1); PG8_BAR; PG8_SCHED;
;             PG8_LDB(B0, 1, 0); PG8_LDB(B1, 1, 1); PG8_SCHED; PG8_LDA(At, 1, 0); PG8_STAGE(PG8_SA(0, 1), a2 + hstepA, voffA);
;             PG8_WAIT_V(8); PG8_WAIT_L(0); PG8_BAR; PG8_MMA(0, 0, At, B0); PG8_MMA(0, 1, At, B1); PG8_BAR; PG8_SCHED;
;             PG8_LDA(At, 1, 1); PG8_STAGE(PG8_SB(1, 0), b3, voffB); PG8_STAGE(PG8_SB(1, 1), b3 + hstepB, voffB); PG8_STAGE(PG8_SA(1, 0), a3, voffA);
;             PG8_WAIT_V(8); PG8_WAIT_L(0); PG8_BAR; PG8_MMA(1, 0, At, B0); PG8_MMA(1, 1, At, B1); PG8_BAR; PG8_SCHED;
;         }
	s_waitcnt lgkmcnt(0)
	v_mfma_f32_16x16x32_bf16 v[60:63], v[166:169], v[198:201], v[60:63]
	v_mfma_f32_16x16x32_bf16 v[56:59], v[174:177], v[198:201], v[56:59]
	v_mfma_f32_16x16x32_bf16 v[44:47], v[166:169], v[206:209], v[44:47]
	v_mfma_f32_16x16x32_bf16 v[40:43], v[174:177], v[206:209], v[40:43]
	v_mfma_f32_16x16x32_bf16 v[28:31], v[166:169], v[214:217], v[28:31]
	v_mfma_f32_16x16x32_bf16 v[24:27], v[174:177], v[214:217], v[24:27]
	v_mfma_f32_16x16x32_bf16 v[12:15], v[166:169], v[222:225], v[12:15]
	v_mfma_f32_16x16x32_bf16 v[8:11], v[174:177], v[222:225], v[8:11]
	v_mfma_f32_16x16x32_bf16 v[60:63], v[170:173], v[202:205], v[60:63]
	v_mfma_f32_16x16x32_bf16 v[56:59], v[178:181], v[202:205], v[56:59]
	v_mfma_f32_16x16x32_bf16 v[44:47], v[170:173], v[210:213], v[44:47]
	v_mfma_f32_16x16x32_bf16 v[40:43], v[178:181], v[210:213], v[40:43]
	v_mfma_f32_16x16x32_bf16 v[28:31], v[170:173], v[218:221], v[28:31]
	v_mfma_f32_16x16x32_bf16 v[24:27], v[178:181], v[218:221], v[24:27]
	v_mfma_f32_16x16x32_bf16 v[12:15], v[170:173], v[226:229], v[12:15]
	v_mfma_f32_16x16x32_bf16 v[8:11], v[178:181], v[226:229], v[8:11]
	v_mfma_f32_16x16x32_bf16 v[52:55], v[182:185], v[198:201], v[52:55]
	v_mfma_f32_16x16x32_bf16 v[48:51], v[190:193], v[198:201], v[48:51]
	v_mfma_f32_16x16x32_bf16 v[36:39], v[182:185], v[206:209], v[36:39]
	v_mfma_f32_16x16x32_bf16 v[32:35], v[190:193], v[206:209], v[32:35]
	v_mfma_f32_16x16x32_bf16 v[20:23], v[182:185], v[214:217], v[20:23]
	v_mfma_f32_16x16x32_bf16 v[16:19], v[190:193], v[214:217], v[16:19]
	v_mfma_f32_16x16x32_bf16 v[4:7], v[182:185], v[222:225], v[4:7]
	v_mfma_f32_16x16x32_bf16 v[0:3], v[190:193], v[222:225], v[0:3]
	v_mfma_f32_16x16x32_bf16 v[52:55], v[186:189], v[202:205], v[52:55]
	v_mfma_f32_16x16x32_bf16 v[48:51], v[194:197], v[202:205], v[48:51]
	v_mfma_f32_16x16x32_bf16 v[36:39], v[186:189], v[210:213], v[36:39]
	v_mfma_f32_16x16x32_bf16 v[32:35], v[194:197], v[210:213], v[32:35]
	v_mfma_f32_16x16x32_bf16 v[20:23], v[186:189], v[218:221], v[20:23]
	v_mfma_f32_16x16x32_bf16 v[16:19], v[194:197], v[218:221], v[16:19]
	v_mfma_f32_16x16x32_bf16 v[4:7], v[186:189], v[226:229], v[4:7]
	v_mfma_f32_16x16x32_bf16 v[0:3], v[194:197], v[226:229], v[0:3]
	s_barrier
	s_add_i32 s65, 0, 0x18000
	s_add_i32 s66, 0, 0x1c000
	v_add_u32_e32 v178, s65, v159
	v_add_u32_e32 v194, s66, v159
	ds_read_b128 v[166:169], v178
	ds_read_b128 v[170:173], v178 offset:1024
	ds_read_b128 v[174:177], v178 offset:2048
	ds_read_b128 v[178:181], v178 offset:3072
	ds_read_b128 v[182:185], v194
	ds_read_b128 v[186:189], v194 offset:1024
	ds_read_b128 v[190:193], v194 offset:2048
	ds_read_b128 v[194:197], v194 offset:3072
	s_add_u32 s42, s42, 0x40000
	s_addc_u32 s43, s43, 0
	s_mov_b32 m0, s49
	v_lshl_add_u64 v[238:239], s[42:43], 0, v[128:129]
	ds_read_b128 v[198:201], v164 offset:32768
	ds_read_b128 v[202:205], v164 offset:33792
	ds_read_b128 v[206:209], v164 offset:34816
	ds_read_b128 v[210:213], v164 offset:35840
	ds_read_b128 v[214:217], v164 offset:36864
	ds_read_b128 v[218:221], v164 offset:37888
	ds_read_b128 v[222:225], v164 offset:38912
	ds_read_b128 v[226:229], v164 offset:39936
	global_load_lds_dwordx4 v[238:239], off
	v_lshl_add_u64 v[238:239], s[42:43], 0, v[132:133]
	s_mov_b32 m0, s50
	s_nop 0
	global_load_lds_dwordx4 v[238:239], off
	s_waitcnt vmcnt(8)
	s_waitcnt lgkmcnt(0)
	s_barrier
	s_waitcnt lgkmcnt(0)
	v_mfma_f32_16x16x32_bf16 v[124:127], v[166:169], v[198:201], v[124:127]
	v_mfma_f32_16x16x32_bf16 v[120:123], v[174:177], v[198:201], v[120:123]
	v_mfma_f32_16x16x32_bf16 v[108:111], v[166:169], v[206:209], v[108:111]
	v_mfma_f32_16x16x32_bf16 v[104:107], v[174:177], v[206:209], v[104:107]
	v_mfma_f32_16x16x32_bf16 v[92:95], v[166:169], v[214:217], v[92:95]
	v_mfma_f32_16x16x32_bf16 v[88:91], v[174:177], v[214:217], v[88:91]
	v_mfma_f32_16x16x32_bf16 v[76:79], v[166:169], v[222:225], v[76:79]
	v_mfma_f32_16x16x32_bf16 v[72:75], v[174:177], v[222:225], v[72:75]
	v_mfma_f32_16x16x32_bf16 v[124:127], v[170:173], v[202:205], v[124:127]
	v_mfma_f32_16x16x32_bf16 v[120:123], v[178:181], v[202:205], v[120:123]
	v_mfma_f32_16x16x32_bf16 v[108:111], v[170:173], v[210:213], v[108:111]
	v_mfma_f32_16x16x32_bf16 v[104:107], v[178:181], v[210:213], v[104:107]
	v_mfma_f32_16x16x32_bf16 v[92:95], v[170:173], v[218:221], v[92:95]
	v_mfma_f32_16x16x32_bf16 v[88:91], v[178:181], v[218:221], v[88:91]
	v_mfma_f32_16x16x32_bf16 v[76:79], v[170:173], v[226:229], v[76:79]
	v_mfma_f32_16x16x32_bf16 v[72:75], v[178:181], v[226:229], v[72:75]
	v_mfma_f32_16x16x32_bf16 v[116:119], v[182:185], v[198:201], v[116:119]
	v_mfma_f32_16x16x32_bf16 v[112:115], v[190:193], v[198:201], v[112:115]
	v_mfma_f32_16x16x32_bf16 v[100:103], v[182:185], v[206:209], v[100:103]
	v_mfma_f32_16x16x32_bf16 v[96:99], v[190:193], v[206:209], v[96:99]
	v_mfma_f32_16x16x32_bf16 v[84:87], v[182:185], v[214:217], v[84:87]
	v_mfma_f32_16x16x32_bf16 v[80:83], v[190:193], v[214:217], v[80:83]
	v_mfma_f32_16x16x32_bf16 v[68:71], v[182:185], v[222:225], v[68:71]
	v_mfma_f32_16x16x32_bf16 v[64:67], v[190:193], v[222:225], v[64:67]
	v_mfma_f32_16x16x32_bf16 v[116:119], v[186:189], v[202:205], v[116:119]
	v_mfma_f32_16x16x32_bf16 v[112:115], v[194:197], v[202:205], v[112:115]
	v_mfma_f32_16x16x32_bf16 v[100:103], v[186:189], v[210:213], v[100:103]
	v_mfma_f32_16x16x32_bf16 v[96:99], v[194:197], v[210:213], v[96:99]
	v_mfma_f32_16x16x32_bf16 v[84:87], v[186:189], v[218:221], v[84:87]
	v_mfma_f32_16x16x32_bf16 v[80:83], v[194:197], v[218:221], v[80:83]
	v_mfma_f32_16x16x32_bf16 v[68:71], v[186:189], v[226:229], v[68:71]
	v_mfma_f32_16x16x32_bf16 v[64:67], v[194:197], v[226:229], v[64:67]
	s_barrier
; #define PG8_STAGE(bufoff, gbase, voff) do { _Pragma("unroll") for (int _i = 0; _i < 2; ++_i) \
;         __builtin_amdgcn_global_load_lds((const GAS unsigned*)((const char*)(gbase) + (voff)[_i]), (LAS unsigned*)(lds + (bufoff) + ldsw + _i * 8192), 16, 0, 0); } while (0)
; #define PG8_LDA(dst, b, h) do { _Pragma("unroll") for (int m = 0; m < 4; ++m) _Pragma("unroll") for (int k = 0; k < 2; ++k) dst[m][k] = *(const LAS bf16x8*)(lds + PG8_SA(b, h) + aoff + m * 2048 + k * 1024); } while (0)
; #define PG8_WAIT_V(n) asm volatile("s_waitcnt vmcnt(" #n ")" ::: "memory")
; #define PG8_WAIT_L(n) asm volatile("s_waitcnt lgkmcnt(" #n ")" ::: "memory")
; #define PG8_BAR __builtin_amdgcn_s_barrier()
; template <class Epi, class Sched>
; __device__ __forceinline__ void gemm_phase(LAS unsigned char* lds, const Gemm g, const Sched& S, const Epi& E, const int wave_) {
;     ...
;         for (int t = 0; t < nt; t += 2) {
;             if constexpr (Epi::HOOK) { if (t == 8 || t == 16) { E.hook(acc, cur, t >> 3, wr, wc, fr, fq); PG8_WAIT_V(0); } }
;             const bool last = (t == nt - 2);
;             const char* a1 = cA + (size_t)(t + 1) * kstep;
;             const char* a2 = last ? nA : cA + (size_t)(t + 2) * kstep; const char* b2 = last ? nB : cB + (size_t)(t + 2) * kstep;
;             const char* a3 = a2 + kstep; const char* b3 = b2 + kstep;
;             PG8_LDB(B0, 0, 0); PG8_LDB(B1, 0, 1); PG8_SCHED; PG8_LDA(At, 0, 0); PG8_STAGE(PG8_SA(1, 1), a1 + hstepA, voffA);
;             PG8_WAIT_V(8); PG8_WAIT_L(0); PG8_BAR; PG8_MMA(0, 0, At, B0); PG8_MMA(0, 1, At, B1); PG8_BAR; PG8_SCHED;
;             PG8_LDA(At, 0, 1); PG8_STAGE(PG8_SB(0, 0), b2, voffB); PG8_STAGE(PG8_SB(0, 1), b2 + hstepB, voffB); PG8_STAGE(PG8_SA(0, 0), a2, voffA);
;             PG8_WAIT_V(8); PG8_WAIT_L(0); PG8_BAR; PG8_MMA(1, 0, At, B0); PG8_MMA(1, 1, At, B1); PG8_BAR; PG8_SCHED;
;             PG8_LDB(B0, 1, 0); PG8_LDB(B1, 1, 1); PG8_SCHED; PG8_LDA(At, 1, 0); PG8_STAGE(PG8_SA(0, 1), a2 + hstepA, voffA);
;             PG8_WAIT_V(8); PG8_WAIT_L(0); PG8_BAR; PG8_MMA(0, 0, At, B0); PG8_MMA(0, 1, At, B1); PG8_BAR; PG8_SCHED;
;             PG8_LDA(At, 1, 1); PG8_STAGE(PG8_SB(1, 0), b3, voffB); PG8_STAGE(PG8_SB(1, 1), b3 + hstepB, voffB); PG8_STAGE(PG8_SA(1, 0), a3, voffA);
;             PG8_WAIT_V(8); PG8_WAIT_L(0); PG8_BAR; PG8_MMA(1, 0, At, B0); PG8_MMA(1, 1, At, B1); PG8_BAR; PG8_SCHED;
;         }
	s_add_i32 s42, s65, s83
	v_lshl_add_u64 v[230:231], v[230:231], 0, s[24:25]
	s_mov_b32 m0, s42
	ds_read_b128 v[198:201], v164 offset:49152
	ds_read_b128 v[202:205], v164 offset:50176
	ds_read_b128 v[206:209], v164 offset:51200
	ds_read_b128 v[210:213], v164 offset:52224
	ds_read_b128 v[214:217], v164 offset:53248
	ds_read_b128 v[218:221], v164 offset:54272
	ds_read_b128 v[222:225], v164 offset:55296
	ds_read_b128 v[226:229], v164 offset:56320
	global_load_lds_dwordx4 v[230:231], off
	s_add_i32 m0, s42, 0x2000
	s_add_u32 s40, s40, 0x40080
	v_lshl_add_u64 v[230:231], v[232:233], 0, s[24:25]
	s_addc_u32 s41, s41, 0
	s_add_i32 s42, s66, s83
	global_load_lds_dwordx4 v[230:231], off
	v_lshl_add_u64 v[230:231], s[40:41], 0, v[130:131]
	s_mov_b32 m0, s42
	s_nop 0
	global_load_lds_dwordx4 v[230:231], off
	v_lshl_add_u64 v[230:231], s[40:41], 0, v[134:135]
	s_add_i32 m0, s42, 0x2000
	s_nop 0
	global_load_lds_dwordx4 v[230:231], off
	v_lshl_add_u64 v[230:231], v[234:235], 0, s[24:25]
	s_mov_b32 m0, s52
	s_nop 0
	global_load_lds_dwordx4 v[230:231], off
	v_lshl_add_u64 v[230:231], v[236:237], 0, s[24:25]
	s_mov_b32 m0, s53
	s_nop 0
	global_load_lds_dwordx4 v[230:231], off
	s_waitcnt vmcnt(8)
	s_waitcnt lgkmcnt(0)
	s_barrier
	s_waitcnt lgkmcnt(0)
	v_mfma_f32_16x16x32_bf16 v[60:63], v[166:169], v[198:201], v[60:63]
	v_mfma_f32_16x16x32_bf16 v[56:59], v[174:177], v[198:201], v[56:59]
	v_mfma_f32_16x16x32_bf16 v[44:47], v[166:169], v[206:209], v[44:47]
	v_mfma_f32_16x16x32_bf16 v[40:43], v[174:177], v[206:209], v[40:43]
	v_mfma_f32_16x16x32_bf16 v[28:31], v[166:169], v[214:217], v[28:31]
	v_mfma_f32_16x16x32_bf16 v[24:27], v[174:177], v[214:217], v[24:27]
	v_mfma_f32_16x16x32_bf16 v[12:15], v[166:169], v[222:225], v[12:15]
	v_mfma_f32_16x16x32_bf16 v[8:11], v[174:177], v[222:225], v[8:11]
	v_mfma_f32_16x16x32_bf16 v[60:63], v[170:173], v[202:205], v[60:63]
	v_mfma_f32_16x16x32_bf16 v[56:59], v[178:181], v[202:205], v[56:59]
	v_mfma_f32_16x16x32_bf16 v[44:47], v[170:173], v[210:213], v[44:47]
	v_mfma_f32_16x16x32_bf16 v[40:43], v[178:181], v[210:213], v[40:43]
	v_mfma_f32_16x16x32_bf16 v[28:31], v[170:173], v[218:221], v[28:31]
	v_mfma_f32_16x16x32_bf16 v[24:27], v[178:181], v[218:221], v[24:27]
	v_mfma_f32_16x16x32_bf16 v[12:15], v[170:173], v[226:229], v[12:15]
	v_mfma_f32_16x16x32_bf16 v[8:11], v[178:181], v[226:229], v[8:11]
	v_mfma_f32_16x16x32_bf16 v[52:55], v[182:185], v[198:201], v[52:55]
	v_mfma_f32_16x16x32_bf16 v[48:51], v[190:193], v[198:201], v[48:51]
	v_mfma_f32_16x16x32_bf16 v[36:39], v[182:185], v[206:209], v[36:39]
	v_mfma_f32_16x16x32_bf16 v[32:35], v[190:193], v[206:209], v[32:35]
	v_mfma_f32_16x16x32_bf16 v[20:23], v[182:185], v[214:217], v[20:23]
	v_mfma_f32_16x16x32_bf16 v[16:19], v[190:193], v[214:217], v[16:19]
	v_mfma_f32_16x16x32_bf16 v[4:7], v[182:185], v[222:225], v[4:7]
	v_mfma_f32_16x16x32_bf16 v[0:3], v[190:193], v[222:225], v[0:3]
	v_mfma_f32_16x16x32_bf16 v[52:55], v[186:189], v[202:205], v[52:55]
	v_mfma_f32_16x16x32_bf16 v[48:51], v[194:197], v[202:205], v[48:51]
	v_mfma_f32_16x16x32_bf16 v[36:39], v[186:189], v[210:213], v[36:39]
	v_mfma_f32_16x16x32_bf16 v[32:35], v[194:197], v[210:213], v[32:35]
	v_mfma_f32_16x16x32_bf16 v[20:23], v[186:189], v[218:221], v[20:23]
	v_mfma_f32_16x16x32_bf16 v[16:19], v[194:197], v[218:221], v[16:19]
	v_mfma_f32_16x16x32_bf16 v[4:7], v[186:189], v[226:229], v[4:7]
	v_mfma_f32_16x16x32_bf16 v[0:3], v[194:197], v[226:229], v[0:3]
	s_barrier
	s_add_u32 s62, s62, 0x100
	s_addc_u32 s63, s63, 0
	s_add_u32 s38, s38, 0x100
	s_addc_u32 s39, s39, 0
	s_cmp_ge_i32 s64, s51
	s_mov_b32 s40, s64
	s_cbranch_scc0 .LBB0_1180
